# MFMA issue order per interval regrouped so 4 consecutive MFMAs share src1 (the A fragment), k0 for all 16 accumulators then k1 (w_in, w_out, down, up loops)
# baseline (speedup 1.0000x reference)
; #define PG8_STAGE(bufoff, gbase, voff) do { _Pragma("unroll") for (int _i = 0; _i < 2; ++_i) \
;         __builtin_amdgcn_global_load_lds((const unsigned*)((const char*)(gbase) + (voff)[_i]), (PG8_LAS unsigned*)(lds + (bufoff) + ldsw + _i * 8192), 16, 0, 0); } while (0)
; #define PG8_LDA(dst, b, h) do { _Pragma("unroll") for (int m = 0; m < 4; ++m) _Pragma("unroll") for (int k = 0; k < 2; ++k) dst[m][k] = *(const PG8_LAS bf16x8*)(lds + PG8_SA(b, h) + aoff + m * 2048 + k * 1024); } while (0)
; #define PG8_LDB(dst, b, h) do { _Pragma("unroll") for (int n = 0; n < 2; ++n) _Pragma("unroll") for (int k = 0; k < 2; ++k) dst[n][k] = *(const PG8_LAS bf16x8*)(lds + PG8_SB(b, h) + boff + n * 2048 + k * 1024); } while (0)
; #define PG8_MMA(ai, bj, At, Bt) do { __builtin_amdgcn_s_setprio(1); _Pragma("unroll") for (int m = 0; m < 4; ++m) _Pragma("unroll") for (int n = 0; n < 2; ++n) _Pragma("unroll") for (int k = 0; k < 2; ++k) \
;         acc[ai][bj][m][n] = __builtin_amdgcn_mfma_f32_16x16x32_bf16(Bt[n][k], At[m][k], acc[ai][bj][m][n], 0, 0, 0); __builtin_amdgcn_s_setprio(0); } while (0)
; #define PG8_BAR __builtin_amdgcn_s_barrier()
; template <class Epi, class Sched, bool ALIGN_EPI = false, bool SP2 = false>
; __device__ __forceinline__ void gemm_phase(PG8_LAS unsigned char* lds, const Gemm g, const Sched& S, const Epi& E) {
;     ...
;         const bool has_next = S.next(ui + 1, nxt);
;         const char* nA = has_next ? (const char*)g.A + (size_t)nxt.pm * tstep : cA; const char* nB = has_next ? (const char*)g.Bt + (size_t)nxt.pn * tstep : cB;
;         for (int t = 0; t < nt; t += 2) {
;             const bool last = (t == nt - 2);
;             const char* a1 = cA + (size_t)(t + 1) * kstep;
;             const char* a2 = last ? nA : cA + (size_t)(t + 2) * kstep; const char* b2 = last ? nB : cB + (size_t)(t + 2) * kstep;
;             const char* a3 = a2 + kstep; const char* b3 = b2 + kstep;
;             if (last && has_next) S.a_ready(nxt);
;             if constexpr (SP2) {
;             PG8_LDB(B0, 0, 0); PG8_LDB(B1, 0, 1); PG8_SCHED; PG8_LDA(At, 0, 0); PG8_STAGE(PG8_SA(1, 1), a1 + hstep, voffA);
;             PG8_WAIT_V(8); PG8_WAIT_L(0); PG8_BAR; PG8_MMA(0, 0, At, B0); PG8_MMA(0, 1, At, B1); PG8_BAR; PG8_SCHED;
;             PG8_LDA(At, 0, 1); PG8_STAGE(PG8_SB(0, 0), b2, voffB); PG8_STAGE(PG8_SB(0, 1), b2 + hstepB, voffB); PG8_STAGE(PG8_SA(0, 0), a2, voffA);
.LBB0_169:
	s_add_u32 s93, s46, 0x100
	s_addc_u32 s94, s47, 0
	s_ashr_i32 s69, s68, 31
	s_lshl_b64 s[4:5], s[68:69], 20
	s_add_u32 s76, s52, s4
	s_addc_u32 s77, s53, s5
	s_and_b64 s[4:5], s[38:39], exec
	s_cselect_b32 s4, s77, s71
	s_cselect_b32 s5, s76, s70
	s_ashr_i32 s63, s62, 31
	s_lshl_b64 s[6:7], s[62:63], 20
	v_readlane_b32 s8, v249, 19
	v_readlane_b32 s9, v249, 20
	s_add_u32 s72, s8, s6
	s_addc_u32 s73, s9, s7
	s_and_b64 s[6:7], s[38:39], exec
	s_cselect_b32 s6, s73, s47
	s_cselect_b32 s7, s72, s46
	s_add_u32 s8, s70, 0x80080
	s_addc_u32 s9, s71, 0
	v_lshl_add_u64 v[144:145], s[8:9], 0, v[140:141]
	v_lshl_add_u64 v[146:147], s[8:9], 0, v[142:143]
	s_mov_b32 s8, -2
	s_mov_b64 s[46:47], 0
	v_add_u32_e32 v186, 0x10000, v139
	v_add_u32_e32 v187, 0x14000, v139
	v_add_u32_e32 v198, 0x18000, v139
	v_add_u32_e32 v199, 0x1c000, v139
	s_add_u32 s9, s70, s46
	s_addc_u32 s10, s71, s47
	s_add_u32 s9, s9, 0x100
	s_addc_u32 s10, s10, 0
	s_add_u32 s100, s9, 0x7ff80
	s_addc_u32 s101, s10, 0
	s_add_u32 s11, s93, s46
	s_addc_u32 s12, s94, s47
	s_add_i32 s13, 0, 0x10000
	s_cmpk_eq_i32 s46, 0xf00
	s_cselect_b32 s85, s4, s10
	s_cselect_b32 s84, s5, s9
	s_cselect_b32 s81, s6, s12
	s_cselect_b32 s80, s7, s11
	s_add_i32 s9, 0, 0x14000
	ds_read_b128 v[148:151], v186
	ds_read_b128 v[152:155], v186 offset:1024
	ds_read_b128 v[156:159], v186 offset:2048
	ds_read_b128 v[160:163], v186 offset:3072
	ds_read_b128 v[166:169], v187
	ds_read_b128 v[170:173], v187 offset:1024
	ds_read_b128 v[174:177], v187 offset:2048
	ds_read_b128 v[178:181], v187 offset:3072
	s_add_i32 m0, s1, 0xc000
	ds_read_b128 v[182:185], v165
	ds_read_b128 v[206:209], v165 offset:1024
	ds_read_b128 v[210:213], v165 offset:2048
	ds_read_b128 v[214:217], v165 offset:3072
	ds_read_b128 v[218:221], v165 offset:4096
	ds_read_b128 v[236:239], v165 offset:5120
	ds_read_b128 v[240:243], v165 offset:6144
	ds_read_b128 v[244:247], v165 offset:7168
	global_load_lds_dwordx4 v140, s[100:101]
	s_add_i32 m0, s1, 0xe000
	s_nop 0
	global_load_lds_dwordx4 v142, s[100:101]
	s_waitcnt vmcnt(8)
	s_waitcnt lgkmcnt(0)
	s_barrier
	v_mfma_f32_16x16x32_bf16 v[126:129], v[148:151], v[182:185], 0
	v_mfma_f32_16x16x32_bf16 v[122:125], v[156:159], v[182:185], 0
	v_mfma_f32_16x16x32_bf16 v[94:97], v[166:169], v[182:185], 0
	v_mfma_f32_16x16x32_bf16 v[90:93], v[174:177], v[182:185], 0
	v_mfma_f32_16x16x32_bf16 v[118:121], v[148:151], v[210:213], 0
	v_mfma_f32_16x16x32_bf16 v[114:117], v[156:159], v[210:213], 0
	v_mfma_f32_16x16x32_bf16 v[86:89], v[166:169], v[210:213], 0
	v_mfma_f32_16x16x32_bf16 v[82:85], v[174:177], v[210:213], 0
	v_mfma_f32_16x16x32_bf16 v[110:113], v[148:151], v[218:221], 0
	v_mfma_f32_16x16x32_bf16 v[106:109], v[156:159], v[218:221], 0
	v_mfma_f32_16x16x32_bf16 v[78:81], v[166:169], v[218:221], 0
	v_mfma_f32_16x16x32_bf16 v[74:77], v[174:177], v[218:221], 0
	v_mfma_f32_16x16x32_bf16 v[102:105], v[148:151], v[240:243], 0
	v_mfma_f32_16x16x32_bf16 v[98:101], v[156:159], v[240:243], 0
	v_mfma_f32_16x16x32_bf16 v[70:73], v[166:169], v[240:243], 0
	v_mfma_f32_16x16x32_bf16 v[66:69], v[174:177], v[240:243], 0
	v_mfma_f32_16x16x32_bf16 v[126:129], v[152:155], v[206:209], v[126:129]
	v_mfma_f32_16x16x32_bf16 v[122:125], v[160:163], v[206:209], v[122:125]
	v_mfma_f32_16x16x32_bf16 v[94:97], v[170:173], v[206:209], v[94:97]
	v_mfma_f32_16x16x32_bf16 v[90:93], v[178:181], v[206:209], v[90:93]
	v_mfma_f32_16x16x32_bf16 v[118:121], v[152:155], v[214:217], v[118:121]
	v_mfma_f32_16x16x32_bf16 v[114:117], v[160:163], v[214:217], v[114:117]
	v_mfma_f32_16x16x32_bf16 v[86:89], v[170:173], v[214:217], v[86:89]
	v_mfma_f32_16x16x32_bf16 v[82:85], v[178:181], v[214:217], v[82:85]
	v_mfma_f32_16x16x32_bf16 v[110:113], v[152:155], v[236:239], v[110:113]
	v_mfma_f32_16x16x32_bf16 v[106:109], v[160:163], v[236:239], v[106:109]
	v_mfma_f32_16x16x32_bf16 v[78:81], v[170:173], v[236:239], v[78:81]
	v_mfma_f32_16x16x32_bf16 v[74:77], v[178:181], v[236:239], v[74:77]
	v_mfma_f32_16x16x32_bf16 v[102:105], v[152:155], v[244:247], v[102:105]
	v_mfma_f32_16x16x32_bf16 v[98:101], v[160:163], v[244:247], v[98:101]
	v_mfma_f32_16x16x32_bf16 v[70:73], v[170:173], v[244:247], v[70:73]
	v_mfma_f32_16x16x32_bf16 v[66:69], v[178:181], v[244:247], v[66:69]
	s_barrier
	s_add_i32 s10, s13, s0
	s_mov_b32 m0, s10
	ds_read_b128 v[182:185], v165 offset:16384
	ds_read_b128 v[206:209], v165 offset:17408
	ds_read_b128 v[210:213], v165 offset:18432
	ds_read_b128 v[214:217], v165 offset:19456
	ds_read_b128 v[218:221], v165 offset:20480
	ds_read_b128 v[236:239], v165 offset:21504
	ds_read_b128 v[240:243], v165 offset:22528
	ds_read_b128 v[244:247], v165 offset:23552
	global_load_lds_dwordx4 v132, s[80:81]
	s_add_i32 m0, s10, 0x2000
	s_add_u32 s10, s80, 0x20000
	s_addc_u32 s11, s81, 0
	s_add_i32 s9, s9, s0
	global_load_lds_dwordx4 v136, s[80:81]
	s_mov_b32 m0, s9
	s_nop 0
	global_load_lds_dwordx4 v132, s[10:11]
	s_add_i32 m0, s9, 0x2000
	s_nop 0
	global_load_lds_dwordx4 v136, s[10:11]
	s_mov_b32 m0, s1
	s_nop 0
	global_load_lds_dwordx4 v130, s[84:85]
	s_mov_b32 m0, s25
	s_nop 0
	global_load_lds_dwordx4 v134, s[84:85]
	s_waitcnt vmcnt(8)
	s_waitcnt lgkmcnt(0)
	s_barrier
; #define PG8_STAGE(bufoff, gbase, voff) do { _Pragma("unroll") for (int _i = 0; _i < 2; ++_i) \
;         __builtin_amdgcn_global_load_lds((const unsigned*)((const char*)(gbase) + (voff)[_i]), (PG8_LAS unsigned*)(lds + (bufoff) + ldsw + _i * 8192), 16, 0, 0); } while (0)
; #define PG8_LDA(dst, b, h) do { _Pragma("unroll") for (int m = 0; m < 4; ++m) _Pragma("unroll") for (int k = 0; k < 2; ++k) dst[m][k] = *(const PG8_LAS bf16x8*)(lds + PG8_SA(b, h) + aoff + m * 2048 + k * 1024); } while (0)
; #define PG8_LDB(dst, b, h) do { _Pragma("unroll") for (int n = 0; n < 2; ++n) _Pragma("unroll") for (int k = 0; k < 2; ++k) dst[n][k] = *(const PG8_LAS bf16x8*)(lds + PG8_SB(b, h) + boff + n * 2048 + k * 1024); } while (0)
; #define PG8_MMA(ai, bj, At, Bt) do { __builtin_amdgcn_s_setprio(1); _Pragma("unroll") for (int m = 0; m < 4; ++m) _Pragma("unroll") for (int n = 0; n < 2; ++n) _Pragma("unroll") for (int k = 0; k < 2; ++k) \
;         acc[ai][bj][m][n] = __builtin_amdgcn_mfma_f32_16x16x32_bf16(Bt[n][k], At[m][k], acc[ai][bj][m][n], 0, 0, 0); __builtin_amdgcn_s_setprio(0); } while (0)
; #define PG8_WAIT_V(n) asm volatile("s_waitcnt vmcnt(" #n ")" ::: "memory")
; #define PG8_WAIT_L(n) asm volatile("s_waitcnt lgkmcnt(" #n ")" ::: "memory")
; #define PG8_BAR __builtin_amdgcn_s_barrier()
; #define PG8_SCHED __builtin_amdgcn_sched_barrier(0)
; template <class Epi, class Sched, bool ALIGN_EPI = false, bool SP2 = false>
; __device__ __forceinline__ void gemm_phase(PG8_LAS unsigned char* lds, const Gemm g, const Sched& S, const Epi& E) {
;     ...
;             PG8_WAIT_V(8); PG8_WAIT_L(0); PG8_BAR; PG8_MMA(1, 0, At, B0); PG8_MMA(1, 1, At, B1); PG8_BAR; PG8_SCHED;
;             PG8_LDB(B0, 1, 0); PG8_LDB(B1, 1, 1); PG8_SCHED; PG8_LDA(At, 1, 0); PG8_STAGE(PG8_SA(0, 1), a2 + hstep, voffA);
;             PG8_WAIT_V(8); PG8_WAIT_L(0); PG8_BAR; PG8_MMA(0, 0, At, B0); PG8_MMA(0, 1, At, B1); PG8_BAR; PG8_SCHED;
	v_mfma_f32_16x16x32_bf16 v[62:65], v[148:151], v[182:185], 0
	v_mfma_f32_16x16x32_bf16 v[58:61], v[156:159], v[182:185], 0
	v_mfma_f32_16x16x32_bf16 v[30:33], v[166:169], v[182:185], 0
	v_mfma_f32_16x16x32_bf16 v[26:29], v[174:177], v[182:185], 0
	v_mfma_f32_16x16x32_bf16 v[54:57], v[148:151], v[210:213], 0
	v_mfma_f32_16x16x32_bf16 v[50:53], v[156:159], v[210:213], 0
	v_mfma_f32_16x16x32_bf16 v[22:25], v[166:169], v[210:213], 0
	v_mfma_f32_16x16x32_bf16 v[18:21], v[174:177], v[210:213], 0
	v_mfma_f32_16x16x32_bf16 v[46:49], v[148:151], v[218:221], 0
	v_mfma_f32_16x16x32_bf16 v[42:45], v[156:159], v[218:221], 0
	v_mfma_f32_16x16x32_bf16 v[14:17], v[166:169], v[218:221], 0
	v_mfma_f32_16x16x32_bf16 v[10:13], v[174:177], v[218:221], 0
	v_mfma_f32_16x16x32_bf16 v[38:41], v[148:151], v[240:243], 0
	v_mfma_f32_16x16x32_bf16 v[34:37], v[156:159], v[240:243], 0
	v_mfma_f32_16x16x32_bf16 v[6:9], v[166:169], v[240:243], 0
	v_mfma_f32_16x16x32_bf16 v[2:5], v[174:177], v[240:243], 0
	v_mfma_f32_16x16x32_bf16 v[62:65], v[152:155], v[206:209], v[62:65]
	v_mfma_f32_16x16x32_bf16 v[58:61], v[160:163], v[206:209], v[58:61]
	v_mfma_f32_16x16x32_bf16 v[30:33], v[170:173], v[206:209], v[30:33]
	v_mfma_f32_16x16x32_bf16 v[26:29], v[178:181], v[206:209], v[26:29]
	v_mfma_f32_16x16x32_bf16 v[54:57], v[152:155], v[214:217], v[54:57]
	v_mfma_f32_16x16x32_bf16 v[50:53], v[160:163], v[214:217], v[50:53]
	v_mfma_f32_16x16x32_bf16 v[22:25], v[170:173], v[214:217], v[22:25]
	v_mfma_f32_16x16x32_bf16 v[18:21], v[178:181], v[214:217], v[18:21]
	v_mfma_f32_16x16x32_bf16 v[46:49], v[152:155], v[236:239], v[46:49]
	v_mfma_f32_16x16x32_bf16 v[42:45], v[160:163], v[236:239], v[42:45]
	v_mfma_f32_16x16x32_bf16 v[14:17], v[170:173], v[236:239], v[14:17]
	v_mfma_f32_16x16x32_bf16 v[10:13], v[178:181], v[236:239], v[10:13]
	v_mfma_f32_16x16x32_bf16 v[38:41], v[152:155], v[244:247], v[38:41]
	v_mfma_f32_16x16x32_bf16 v[34:37], v[160:163], v[244:247], v[34:37]
	v_mfma_f32_16x16x32_bf16 v[6:9], v[170:173], v[244:247], v[6:9]
	v_mfma_f32_16x16x32_bf16 v[2:5], v[178:181], v[244:247], v[2:5]
	s_barrier
	s_add_i32 s9, 0, 0x18000
	s_add_i32 s12, 0, 0x1c000
	ds_read_b128 v[148:151], v198
	ds_read_b128 v[152:155], v198 offset:1024
	ds_read_b128 v[156:159], v198 offset:2048
	ds_read_b128 v[160:163], v198 offset:3072
	ds_read_b128 v[166:169], v199
	ds_read_b128 v[170:173], v199 offset:1024
	ds_read_b128 v[174:177], v199 offset:2048
	ds_read_b128 v[178:181], v199 offset:3072
	s_add_u32 s10, s84, 0x80000
	s_addc_u32 s11, s85, 0
	s_mov_b32 m0, s42
	ds_read_b128 v[182:185], v165 offset:32768
	ds_read_b128 v[206:209], v165 offset:33792
	ds_read_b128 v[210:213], v165 offset:34816
	ds_read_b128 v[214:217], v165 offset:35840
	ds_read_b128 v[218:221], v165 offset:36864
	ds_read_b128 v[236:239], v165 offset:37888
	ds_read_b128 v[240:243], v165 offset:38912
	ds_read_b128 v[244:247], v165 offset:39936
	global_load_lds_dwordx4 v130, s[10:11]
	s_mov_b32 m0, s51
	s_nop 0
	global_load_lds_dwordx4 v134, s[10:11]
	s_waitcnt vmcnt(8)
	s_waitcnt lgkmcnt(0)
	s_barrier
	v_mfma_f32_16x16x32_bf16 v[126:129], v[148:151], v[182:185], v[126:129]
	v_mfma_f32_16x16x32_bf16 v[122:125], v[156:159], v[182:185], v[122:125]
	v_mfma_f32_16x16x32_bf16 v[94:97], v[166:169], v[182:185], v[94:97]
	v_mfma_f32_16x16x32_bf16 v[90:93], v[174:177], v[182:185], v[90:93]
	v_mfma_f32_16x16x32_bf16 v[118:121], v[148:151], v[210:213], v[118:121]
	v_mfma_f32_16x16x32_bf16 v[114:117], v[156:159], v[210:213], v[114:117]
	v_mfma_f32_16x16x32_bf16 v[86:89], v[166:169], v[210:213], v[86:89]
	v_mfma_f32_16x16x32_bf16 v[82:85], v[174:177], v[210:213], v[82:85]
	v_mfma_f32_16x16x32_bf16 v[110:113], v[148:151], v[218:221], v[110:113]
	v_mfma_f32_16x16x32_bf16 v[106:109], v[156:159], v[218:221], v[106:109]
	v_mfma_f32_16x16x32_bf16 v[78:81], v[166:169], v[218:221], v[78:81]
	v_mfma_f32_16x16x32_bf16 v[74:77], v[174:177], v[218:221], v[74:77]
	v_mfma_f32_16x16x32_bf16 v[102:105], v[148:151], v[240:243], v[102:105]
	v_mfma_f32_16x16x32_bf16 v[98:101], v[156:159], v[240:243], v[98:101]
	v_mfma_f32_16x16x32_bf16 v[70:73], v[166:169], v[240:243], v[70:73]
	v_mfma_f32_16x16x32_bf16 v[66:69], v[174:177], v[240:243], v[66:69]
	v_mfma_f32_16x16x32_bf16 v[126:129], v[152:155], v[206:209], v[126:129]
	v_mfma_f32_16x16x32_bf16 v[122:125], v[160:163], v[206:209], v[122:125]
	v_mfma_f32_16x16x32_bf16 v[94:97], v[170:173], v[206:209], v[94:97]
	v_mfma_f32_16x16x32_bf16 v[90:93], v[178:181], v[206:209], v[90:93]
	v_mfma_f32_16x16x32_bf16 v[118:121], v[152:155], v[214:217], v[118:121]
	v_mfma_f32_16x16x32_bf16 v[114:117], v[160:163], v[214:217], v[114:117]
	v_mfma_f32_16x16x32_bf16 v[86:89], v[170:173], v[214:217], v[86:89]
	v_mfma_f32_16x16x32_bf16 v[82:85], v[178:181], v[214:217], v[82:85]
	v_mfma_f32_16x16x32_bf16 v[110:113], v[152:155], v[236:239], v[110:113]
	v_mfma_f32_16x16x32_bf16 v[106:109], v[160:163], v[236:239], v[106:109]
	v_mfma_f32_16x16x32_bf16 v[78:81], v[170:173], v[236:239], v[78:81]
	v_mfma_f32_16x16x32_bf16 v[74:77], v[178:181], v[236:239], v[74:77]
	v_mfma_f32_16x16x32_bf16 v[102:105], v[152:155], v[244:247], v[102:105]
	v_mfma_f32_16x16x32_bf16 v[98:101], v[160:163], v[244:247], v[98:101]
	v_mfma_f32_16x16x32_bf16 v[70:73], v[170:173], v[244:247], v[70:73]
	v_mfma_f32_16x16x32_bf16 v[66:69], v[178:181], v[244:247], v[66:69]
	s_barrier
; #define PG8_STAGE(bufoff, gbase, voff) do { _Pragma("unroll") for (int _i = 0; _i < 2; ++_i) \
;         __builtin_amdgcn_global_load_lds((const unsigned*)((const char*)(gbase) + (voff)[_i]), (PG8_LAS unsigned*)(lds + (bufoff) + ldsw + _i * 8192), 16, 0, 0); } while (0)
; #define PG8_LDA(dst, b, h) do { _Pragma("unroll") for (int m = 0; m < 4; ++m) _Pragma("unroll") for (int k = 0; k < 2; ++k) dst[m][k] = *(const PG8_LAS bf16x8*)(lds + PG8_SA(b, h) + aoff + m * 2048 + k * 1024); } while (0)
; #define PG8_LDB(dst, b, h) do { _Pragma("unroll") for (int n = 0; n < 2; ++n) _Pragma("unroll") for (int k = 0; k < 2; ++k) dst[n][k] = *(const PG8_LAS bf16x8*)(lds + PG8_SB(b, h) + boff + n * 2048 + k * 1024); } while (0)
; template <class Epi, class Sched, bool ALIGN_EPI = false, bool SP2 = false>
; __device__ __forceinline__ void gemm_phase(PG8_LAS unsigned char* lds, const Gemm g, const Sched& S, const Epi& E) {
;     ...
;         for (int t = 0; t < nt; t += 2) {
;             const bool last = (t == nt - 2);
;             const char* a1 = cA + (size_t)(t + 1) * kstep;
;             const char* a2 = last ? nA : cA + (size_t)(t + 2) * kstep; const char* b2 = last ? nB : cB + (size_t)(t + 2) * kstep;
;             const char* a3 = a2 + kstep; const char* b3 = b2 + kstep;
;             if (last && has_next) S.a_ready(nxt);
;             if constexpr (SP2) {
;             PG8_LDB(B0, 0, 0); PG8_LDB(B1, 0, 1); PG8_SCHED; PG8_LDA(At, 0, 0); PG8_STAGE(PG8_SA(1, 1), a1 + hstep, voffA);
;             PG8_WAIT_V(8); PG8_WAIT_L(0); PG8_BAR; PG8_MMA(0, 0, At, B0); PG8_MMA(0, 1, At, B1); PG8_BAR; PG8_SCHED;
;             PG8_LDA(At, 0, 1); PG8_STAGE(PG8_SB(0, 0), b2, voffB); PG8_STAGE(PG8_SB(0, 1), b2 + hstepB, voffB); PG8_STAGE(PG8_SA(0, 0), a2, voffA);
;             PG8_WAIT_V(8); PG8_WAIT_L(0); PG8_BAR; PG8_MMA(1, 0, At, B0); PG8_MMA(1, 1, At, B1); PG8_BAR; PG8_SCHED;
;             PG8_LDB(B0, 1, 0); PG8_LDB(B1, 1, 1); PG8_SCHED; PG8_LDA(At, 1, 0); PG8_STAGE(PG8_SA(0, 1), a2 + hstep, voffA);
;             PG8_WAIT_V(8); PG8_WAIT_L(0); PG8_BAR; PG8_MMA(0, 0, At, B0); PG8_MMA(0, 1, At, B1); PG8_BAR; PG8_SCHED;
;             PG8_LDA(At, 1, 1); PG8_STAGE(PG8_SB(1, 0), b3, voffB); PG8_STAGE(PG8_SB(1, 1), b3 + hstepB, voffB); PG8_STAGE(PG8_SA(1, 0), a3, voffA);
;             PG8_WAIT_V(8); PG8_WAIT_L(0); PG8_BAR; PG8_MMA(1, 0, At, B0); PG8_MMA(1, 1, At, B1); PG8_BAR; PG8_SCHED;
	s_add_i32 s9, s9, s0
	s_mov_b32 m0, s9
	ds_read_b128 v[182:185], v165 offset:49152
	ds_read_b128 v[206:209], v165 offset:50176
	ds_read_b128 v[210:213], v165 offset:51200
	ds_read_b128 v[214:217], v165 offset:52224
	ds_read_b128 v[218:221], v165 offset:53248
	ds_read_b128 v[236:239], v165 offset:54272
	ds_read_b128 v[240:243], v165 offset:55296
	ds_read_b128 v[244:247], v165 offset:56320
	s_add_u32 s100, s80, s60
	s_addc_u32 s101, s81, s61
	global_load_lds_dwordx4 v132, s[100:101]
	s_add_i32 m0, s9, 0x2000
	s_add_u32 s10, s80, 0x20080
	s_addc_u32 s11, s81, 0
	s_add_i32 s9, s12, s0
	global_load_lds_dwordx4 v136, s[100:101]
	s_mov_b32 m0, s9
	s_nop 0
	global_load_lds_dwordx4 v132, s[10:11]
	s_add_i32 m0, s9, 0x2000
	s_nop 0
	global_load_lds_dwordx4 v136, s[10:11]
	s_mov_b32 m0, s66
	s_add_u32 s100, s84, s60
	s_addc_u32 s101, s85, s61
	global_load_lds_dwordx4 v130, s[100:101]
	s_mov_b32 m0, s67
	s_nop 0
	global_load_lds_dwordx4 v134, s[100:101]
	s_waitcnt vmcnt(8)
	s_waitcnt lgkmcnt(0)
	s_barrier
	v_mfma_f32_16x16x32_bf16 v[62:65], v[148:151], v[182:185], v[62:65]
	v_mfma_f32_16x16x32_bf16 v[58:61], v[156:159], v[182:185], v[58:61]
	v_mfma_f32_16x16x32_bf16 v[30:33], v[166:169], v[182:185], v[30:33]
	v_mfma_f32_16x16x32_bf16 v[26:29], v[174:177], v[182:185], v[26:29]
	v_mfma_f32_16x16x32_bf16 v[54:57], v[148:151], v[210:213], v[54:57]
	v_mfma_f32_16x16x32_bf16 v[50:53], v[156:159], v[210:213], v[50:53]
	v_mfma_f32_16x16x32_bf16 v[22:25], v[166:169], v[210:213], v[22:25]
	v_mfma_f32_16x16x32_bf16 v[18:21], v[174:177], v[210:213], v[18:21]
	v_mfma_f32_16x16x32_bf16 v[46:49], v[148:151], v[218:221], v[46:49]
	v_mfma_f32_16x16x32_bf16 v[42:45], v[156:159], v[218:221], v[42:45]
	v_mfma_f32_16x16x32_bf16 v[14:17], v[166:169], v[218:221], v[14:17]
	v_mfma_f32_16x16x32_bf16 v[10:13], v[174:177], v[218:221], v[10:13]
	v_mfma_f32_16x16x32_bf16 v[38:41], v[148:151], v[240:243], v[38:41]
	v_mfma_f32_16x16x32_bf16 v[34:37], v[156:159], v[240:243], v[34:37]
	v_mfma_f32_16x16x32_bf16 v[6:9], v[166:169], v[240:243], v[6:9]
	v_mfma_f32_16x16x32_bf16 v[2:5], v[174:177], v[240:243], v[2:5]
	v_mfma_f32_16x16x32_bf16 v[62:65], v[152:155], v[206:209], v[62:65]
	v_mfma_f32_16x16x32_bf16 v[58:61], v[160:163], v[206:209], v[58:61]
	v_mfma_f32_16x16x32_bf16 v[30:33], v[170:173], v[206:209], v[30:33]
	v_mfma_f32_16x16x32_bf16 v[26:29], v[178:181], v[206:209], v[26:29]
	v_mfma_f32_16x16x32_bf16 v[54:57], v[152:155], v[214:217], v[54:57]
	v_mfma_f32_16x16x32_bf16 v[50:53], v[160:163], v[214:217], v[50:53]
	v_mfma_f32_16x16x32_bf16 v[22:25], v[170:173], v[214:217], v[22:25]
	v_mfma_f32_16x16x32_bf16 v[18:21], v[178:181], v[214:217], v[18:21]
	v_mfma_f32_16x16x32_bf16 v[46:49], v[152:155], v[236:239], v[46:49]
	v_mfma_f32_16x16x32_bf16 v[42:45], v[160:163], v[236:239], v[42:45]
	v_mfma_f32_16x16x32_bf16 v[14:17], v[170:173], v[236:239], v[14:17]
	v_mfma_f32_16x16x32_bf16 v[10:13], v[178:181], v[236:239], v[10:13]
	v_mfma_f32_16x16x32_bf16 v[38:41], v[152:155], v[244:247], v[38:41]
	v_mfma_f32_16x16x32_bf16 v[34:37], v[160:163], v[244:247], v[34:37]
	v_mfma_f32_16x16x32_bf16 v[6:9], v[170:173], v[244:247], v[6:9]
	v_mfma_f32_16x16x32_bf16 v[2:5], v[178:181], v[244:247], v[2:5]
	s_barrier
	s_add_i32 s8, s8, 2
	s_add_u32 s46, s46, 0x100
	s_addc_u32 s47, s47, 0
	s_cmp_gt_u32 s8, 29
.LBB0_170:
	s_add_u32 s9, s70, s46
	s_addc_u32 s10, s71, s47
	s_add_u32 s9, s9, 0x100
	s_addc_u32 s10, s10, 0
	s_add_u32 s100, s9, 0x7ff80
	s_addc_u32 s101, s10, 0
	s_add_u32 s11, s93, s46
	s_addc_u32 s12, s94, s47
	s_add_i32 s13, 0, 0x10000
	s_cmpk_eq_i32 s46, 0xf00
	s_cselect_b32 s85, s4, s10
	s_cselect_b32 s84, s5, s9
	s_cselect_b32 s81, s6, s12
	s_cselect_b32 s80, s7, s11
	s_add_i32 s9, 0, 0x14000
	ds_read_b128 v[148:151], v186
	ds_read_b128 v[152:155], v186 offset:1024
	ds_read_b128 v[156:159], v186 offset:2048
	ds_read_b128 v[160:163], v186 offset:3072
	ds_read_b128 v[166:169], v187
	ds_read_b128 v[170:173], v187 offset:1024
	ds_read_b128 v[174:177], v187 offset:2048
	ds_read_b128 v[178:181], v187 offset:3072
	s_add_i32 m0, s1, 0xc000
	ds_read_b128 v[182:185], v165
	ds_read_b128 v[206:209], v165 offset:1024
	ds_read_b128 v[210:213], v165 offset:2048
	ds_read_b128 v[214:217], v165 offset:3072
	ds_read_b128 v[218:221], v165 offset:4096
	ds_read_b128 v[236:239], v165 offset:5120
	ds_read_b128 v[240:243], v165 offset:6144
	ds_read_b128 v[244:247], v165 offset:7168
	global_load_lds_dwordx4 v140, s[100:101]
	s_add_i32 m0, s1, 0xe000
	s_nop 0
	global_load_lds_dwordx4 v142, s[100:101]
	s_waitcnt vmcnt(8)
	s_waitcnt lgkmcnt(0)
	s_barrier
; #define PG8_STAGE(bufoff, gbase, voff) do { _Pragma("unroll") for (int _i = 0; _i < 2; ++_i) \
;         __builtin_amdgcn_global_load_lds((const unsigned*)((const char*)(gbase) + (voff)[_i]), (PG8_LAS unsigned*)(lds + (bufoff) + ldsw + _i * 8192), 16, 0, 0); } while (0)
; #define PG8_LDA(dst, b, h) do { _Pragma("unroll") for (int m = 0; m < 4; ++m) _Pragma("unroll") for (int k = 0; k < 2; ++k) dst[m][k] = *(const PG8_LAS bf16x8*)(lds + PG8_SA(b, h) + aoff + m * 2048 + k * 1024); } while (0)
; #define PG8_MMA(ai, bj, At, Bt) do { __builtin_amdgcn_s_setprio(1); _Pragma("unroll") for (int m = 0; m < 4; ++m) _Pragma("unroll") for (int n = 0; n < 2; ++n) _Pragma("unroll") for (int k = 0; k < 2; ++k) \
;         acc[ai][bj][m][n] = __builtin_amdgcn_mfma_f32_16x16x32_bf16(Bt[n][k], At[m][k], acc[ai][bj][m][n], 0, 0, 0); __builtin_amdgcn_s_setprio(0); } while (0)
; #define PG8_WAIT_V(n) asm volatile("s_waitcnt vmcnt(" #n ")" ::: "memory")
; #define PG8_WAIT_L(n) asm volatile("s_waitcnt lgkmcnt(" #n ")" ::: "memory")
; #define PG8_BAR __builtin_amdgcn_s_barrier()
; #define PG8_SCHED __builtin_amdgcn_sched_barrier(0)
; template <class Epi, class Sched, bool ALIGN_EPI = false, bool SP2 = false>
; __device__ __forceinline__ void gemm_phase(PG8_LAS unsigned char* lds, const Gemm g, const Sched& S, const Epi& E) {
;     ...
;             PG8_WAIT_V(8); PG8_WAIT_L(0); PG8_BAR; PG8_MMA(0, 0, At, B0); PG8_MMA(0, 1, At, B1); PG8_BAR; PG8_SCHED;
;             PG8_LDA(At, 0, 1); PG8_STAGE(PG8_SB(0, 0), b2, voffB); PG8_STAGE(PG8_SB(0, 1), b2 + hstepB, voffB); PG8_STAGE(PG8_SA(0, 0), a2, voffA);
;             PG8_WAIT_V(8); PG8_WAIT_L(0); PG8_BAR; PG8_MMA(1, 0, At, B0); PG8_MMA(1, 1, At, B1); PG8_BAR; PG8_SCHED;
	v_mfma_f32_16x16x32_bf16 v[126:129], v[148:151], v[182:185], v[126:129]
	v_mfma_f32_16x16x32_bf16 v[122:125], v[156:159], v[182:185], v[122:125]
	v_mfma_f32_16x16x32_bf16 v[94:97], v[166:169], v[182:185], v[94:97]
	v_mfma_f32_16x16x32_bf16 v[90:93], v[174:177], v[182:185], v[90:93]
	v_mfma_f32_16x16x32_bf16 v[118:121], v[148:151], v[210:213], v[118:121]
	v_mfma_f32_16x16x32_bf16 v[114:117], v[156:159], v[210:213], v[114:117]
	v_mfma_f32_16x16x32_bf16 v[86:89], v[166:169], v[210:213], v[86:89]
	v_mfma_f32_16x16x32_bf16 v[82:85], v[174:177], v[210:213], v[82:85]
	v_mfma_f32_16x16x32_bf16 v[110:113], v[148:151], v[218:221], v[110:113]
	v_mfma_f32_16x16x32_bf16 v[106:109], v[156:159], v[218:221], v[106:109]
	v_mfma_f32_16x16x32_bf16 v[78:81], v[166:169], v[218:221], v[78:81]
	v_mfma_f32_16x16x32_bf16 v[74:77], v[174:177], v[218:221], v[74:77]
	v_mfma_f32_16x16x32_bf16 v[102:105], v[148:151], v[240:243], v[102:105]
	v_mfma_f32_16x16x32_bf16 v[98:101], v[156:159], v[240:243], v[98:101]
	v_mfma_f32_16x16x32_bf16 v[70:73], v[166:169], v[240:243], v[70:73]
	v_mfma_f32_16x16x32_bf16 v[66:69], v[174:177], v[240:243], v[66:69]
	v_mfma_f32_16x16x32_bf16 v[126:129], v[152:155], v[206:209], v[126:129]
	v_mfma_f32_16x16x32_bf16 v[122:125], v[160:163], v[206:209], v[122:125]
	v_mfma_f32_16x16x32_bf16 v[94:97], v[170:173], v[206:209], v[94:97]
	v_mfma_f32_16x16x32_bf16 v[90:93], v[178:181], v[206:209], v[90:93]
	v_mfma_f32_16x16x32_bf16 v[118:121], v[152:155], v[214:217], v[118:121]
	v_mfma_f32_16x16x32_bf16 v[114:117], v[160:163], v[214:217], v[114:117]
	v_mfma_f32_16x16x32_bf16 v[86:89], v[170:173], v[214:217], v[86:89]
	v_mfma_f32_16x16x32_bf16 v[82:85], v[178:181], v[214:217], v[82:85]
	v_mfma_f32_16x16x32_bf16 v[110:113], v[152:155], v[236:239], v[110:113]
	v_mfma_f32_16x16x32_bf16 v[106:109], v[160:163], v[236:239], v[106:109]
	v_mfma_f32_16x16x32_bf16 v[78:81], v[170:173], v[236:239], v[78:81]
	v_mfma_f32_16x16x32_bf16 v[74:77], v[178:181], v[236:239], v[74:77]
	v_mfma_f32_16x16x32_bf16 v[102:105], v[152:155], v[244:247], v[102:105]
	v_mfma_f32_16x16x32_bf16 v[98:101], v[160:163], v[244:247], v[98:101]
	v_mfma_f32_16x16x32_bf16 v[70:73], v[170:173], v[244:247], v[70:73]
	v_mfma_f32_16x16x32_bf16 v[66:69], v[178:181], v[244:247], v[66:69]
	s_barrier
	s_add_i32 s10, s13, s0
	s_mov_b32 m0, s10
	ds_read_b128 v[182:185], v165 offset:16384
	ds_read_b128 v[206:209], v165 offset:17408
	ds_read_b128 v[210:213], v165 offset:18432
	ds_read_b128 v[214:217], v165 offset:19456
	ds_read_b128 v[218:221], v165 offset:20480
	ds_read_b128 v[236:239], v165 offset:21504
	ds_read_b128 v[240:243], v165 offset:22528
	ds_read_b128 v[244:247], v165 offset:23552
	global_load_lds_dwordx4 v132, s[80:81]
	s_add_i32 m0, s10, 0x2000
	s_add_u32 s10, s80, 0x20000
	s_addc_u32 s11, s81, 0
	s_add_i32 s9, s9, s0
	global_load_lds_dwordx4 v136, s[80:81]
	s_mov_b32 m0, s9
	s_nop 0
	global_load_lds_dwordx4 v132, s[10:11]
	s_add_i32 m0, s9, 0x2000
	s_nop 0
	global_load_lds_dwordx4 v136, s[10:11]
	s_mov_b32 m0, s1
	s_nop 0
	global_load_lds_dwordx4 v130, s[84:85]
	s_mov_b32 m0, s25
	s_nop 0
	global_load_lds_dwordx4 v134, s[84:85]
	s_waitcnt vmcnt(8)
	s_waitcnt lgkmcnt(0)
	s_barrier
	v_mfma_f32_16x16x32_bf16 v[62:65], v[148:151], v[182:185], v[62:65]
	v_mfma_f32_16x16x32_bf16 v[58:61], v[156:159], v[182:185], v[58:61]
	v_mfma_f32_16x16x32_bf16 v[30:33], v[166:169], v[182:185], v[30:33]
	v_mfma_f32_16x16x32_bf16 v[26:29], v[174:177], v[182:185], v[26:29]
	v_mfma_f32_16x16x32_bf16 v[54:57], v[148:151], v[210:213], v[54:57]
	v_mfma_f32_16x16x32_bf16 v[50:53], v[156:159], v[210:213], v[50:53]
	v_mfma_f32_16x16x32_bf16 v[22:25], v[166:169], v[210:213], v[22:25]
	v_mfma_f32_16x16x32_bf16 v[18:21], v[174:177], v[210:213], v[18:21]
	v_mfma_f32_16x16x32_bf16 v[46:49], v[148:151], v[218:221], v[46:49]
	v_mfma_f32_16x16x32_bf16 v[42:45], v[156:159], v[218:221], v[42:45]
	v_mfma_f32_16x16x32_bf16 v[14:17], v[166:169], v[218:221], v[14:17]
	v_mfma_f32_16x16x32_bf16 v[10:13], v[174:177], v[218:221], v[10:13]
	v_mfma_f32_16x16x32_bf16 v[38:41], v[148:151], v[240:243], v[38:41]
	v_mfma_f32_16x16x32_bf16 v[34:37], v[156:159], v[240:243], v[34:37]
	v_mfma_f32_16x16x32_bf16 v[6:9], v[166:169], v[240:243], v[6:9]
	v_mfma_f32_16x16x32_bf16 v[2:5], v[174:177], v[240:243], v[2:5]
	v_mfma_f32_16x16x32_bf16 v[62:65], v[152:155], v[206:209], v[62:65]
	v_mfma_f32_16x16x32_bf16 v[58:61], v[160:163], v[206:209], v[58:61]
	v_mfma_f32_16x16x32_bf16 v[30:33], v[170:173], v[206:209], v[30:33]
	v_mfma_f32_16x16x32_bf16 v[26:29], v[178:181], v[206:209], v[26:29]
	v_mfma_f32_16x16x32_bf16 v[54:57], v[152:155], v[214:217], v[54:57]
	v_mfma_f32_16x16x32_bf16 v[50:53], v[160:163], v[214:217], v[50:53]
	v_mfma_f32_16x16x32_bf16 v[22:25], v[170:173], v[214:217], v[22:25]
	v_mfma_f32_16x16x32_bf16 v[18:21], v[178:181], v[214:217], v[18:21]
	v_mfma_f32_16x16x32_bf16 v[46:49], v[152:155], v[236:239], v[46:49]
	v_mfma_f32_16x16x32_bf16 v[42:45], v[160:163], v[236:239], v[42:45]
	v_mfma_f32_16x16x32_bf16 v[14:17], v[170:173], v[236:239], v[14:17]
	v_mfma_f32_16x16x32_bf16 v[10:13], v[178:181], v[236:239], v[10:13]
	v_mfma_f32_16x16x32_bf16 v[38:41], v[152:155], v[244:247], v[38:41]
	v_mfma_f32_16x16x32_bf16 v[34:37], v[160:163], v[244:247], v[34:37]
	v_mfma_f32_16x16x32_bf16 v[6:9], v[170:173], v[244:247], v[6:9]
	v_mfma_f32_16x16x32_bf16 v[2:5], v[178:181], v[244:247], v[2:5]
	s_barrier
; #define PG8_STAGE(bufoff, gbase, voff) do { _Pragma("unroll") for (int _i = 0; _i < 2; ++_i) \
;         __builtin_amdgcn_global_load_lds((const unsigned*)((const char*)(gbase) + (voff)[_i]), (PG8_LAS unsigned*)(lds + (bufoff) + ldsw + _i * 8192), 16, 0, 0); } while (0)
; #define PG8_LDA(dst, b, h) do { _Pragma("unroll") for (int m = 0; m < 4; ++m) _Pragma("unroll") for (int k = 0; k < 2; ++k) dst[m][k] = *(const PG8_LAS bf16x8*)(lds + PG8_SA(b, h) + aoff + m * 2048 + k * 1024); } while (0)
; #define PG8_LDB(dst, b, h) do { _Pragma("unroll") for (int n = 0; n < 2; ++n) _Pragma("unroll") for (int k = 0; k < 2; ++k) dst[n][k] = *(const PG8_LAS bf16x8*)(lds + PG8_SB(b, h) + boff + n * 2048 + k * 1024); } while (0)
; #define PG8_MMA(ai, bj, At, Bt) do { __builtin_amdgcn_s_setprio(1); _Pragma("unroll") for (int m = 0; m < 4; ++m) _Pragma("unroll") for (int n = 0; n < 2; ++n) _Pragma("unroll") for (int k = 0; k < 2; ++k) \
;         acc[ai][bj][m][n] = __builtin_amdgcn_mfma_f32_16x16x32_bf16(Bt[n][k], At[m][k], acc[ai][bj][m][n], 0, 0, 0); __builtin_amdgcn_s_setprio(0); } while (0)
; #define PG8_WAIT_V(n) asm volatile("s_waitcnt vmcnt(" #n ")" ::: "memory")
; #define PG8_WAIT_L(n) asm volatile("s_waitcnt lgkmcnt(" #n ")" ::: "memory")
; #define PG8_BAR __builtin_amdgcn_s_barrier()
; #define PG8_SCHED __builtin_amdgcn_sched_barrier(0)
; template <class Epi, class Sched, bool ALIGN_EPI = false, bool SP2 = false>
; __device__ __forceinline__ void gemm_phase(PG8_LAS unsigned char* lds, const Gemm g, const Sched& S, const Epi& E) {
;     ...
;             PG8_LDB(B0, 1, 0); PG8_LDB(B1, 1, 1); PG8_SCHED; PG8_LDA(At, 1, 0); PG8_STAGE(PG8_SA(0, 1), a2 + hstep, voffA);
;             PG8_WAIT_V(8); PG8_WAIT_L(0); PG8_BAR; PG8_MMA(0, 0, At, B0); PG8_MMA(0, 1, At, B1); PG8_BAR; PG8_SCHED;
;             PG8_LDA(At, 1, 1); PG8_STAGE(PG8_SB(1, 0), b3, voffB); PG8_STAGE(PG8_SB(1, 1), b3 + hstepB, voffB); PG8_STAGE(PG8_SA(1, 0), a3, voffA);
;             PG8_WAIT_V(8); PG8_WAIT_L(0); PG8_BAR; PG8_MMA(1, 0, At, B0); PG8_MMA(1, 1, At, B1); PG8_BAR; PG8_SCHED;
;     ...
;         if constexpr (ALIGN_EPI) { if (wr == 0) PG8_BAR; }
	s_add_i32 s9, 0, 0x18000
	s_add_i32 s12, 0, 0x1c000
	ds_read_b128 v[148:151], v198
	ds_read_b128 v[152:155], v198 offset:1024
	ds_read_b128 v[156:159], v198 offset:2048
	ds_read_b128 v[160:163], v198 offset:3072
	ds_read_b128 v[166:169], v199
	ds_read_b128 v[170:173], v199 offset:1024
	ds_read_b128 v[174:177], v199 offset:2048
	ds_read_b128 v[178:181], v199 offset:3072
	s_add_u32 s10, s84, 0x80000
	s_addc_u32 s11, s85, 0
	s_mov_b32 m0, s42
	ds_read_b128 v[182:185], v165 offset:32768
	ds_read_b128 v[206:209], v165 offset:33792
	ds_read_b128 v[210:213], v165 offset:34816
	ds_read_b128 v[214:217], v165 offset:35840
	ds_read_b128 v[218:221], v165 offset:36864
	ds_read_b128 v[236:239], v165 offset:37888
	ds_read_b128 v[240:243], v165 offset:38912
	ds_read_b128 v[244:247], v165 offset:39936
	global_load_lds_dwordx4 v130, s[10:11]
	s_mov_b32 m0, s51
	s_nop 0
	global_load_lds_dwordx4 v134, s[10:11]
	s_waitcnt vmcnt(8)
	s_waitcnt lgkmcnt(0)
	s_barrier
	v_mfma_f32_16x16x32_bf16 v[126:129], v[148:151], v[182:185], v[126:129]
	v_mfma_f32_16x16x32_bf16 v[122:125], v[156:159], v[182:185], v[122:125]
	v_mfma_f32_16x16x32_bf16 v[94:97], v[166:169], v[182:185], v[94:97]
	v_mfma_f32_16x16x32_bf16 v[90:93], v[174:177], v[182:185], v[90:93]
	v_mfma_f32_16x16x32_bf16 v[118:121], v[148:151], v[210:213], v[118:121]
	v_mfma_f32_16x16x32_bf16 v[114:117], v[156:159], v[210:213], v[114:117]
	v_mfma_f32_16x16x32_bf16 v[86:89], v[166:169], v[210:213], v[86:89]
	v_mfma_f32_16x16x32_bf16 v[82:85], v[174:177], v[210:213], v[82:85]
	v_mfma_f32_16x16x32_bf16 v[110:113], v[148:151], v[218:221], v[110:113]
	v_mfma_f32_16x16x32_bf16 v[106:109], v[156:159], v[218:221], v[106:109]
	v_mfma_f32_16x16x32_bf16 v[78:81], v[166:169], v[218:221], v[78:81]
	v_mfma_f32_16x16x32_bf16 v[74:77], v[174:177], v[218:221], v[74:77]
	v_mfma_f32_16x16x32_bf16 v[102:105], v[148:151], v[240:243], v[102:105]
	v_mfma_f32_16x16x32_bf16 v[98:101], v[156:159], v[240:243], v[98:101]
	v_mfma_f32_16x16x32_bf16 v[70:73], v[166:169], v[240:243], v[70:73]
	v_mfma_f32_16x16x32_bf16 v[66:69], v[174:177], v[240:243], v[66:69]
	v_mfma_f32_16x16x32_bf16 v[126:129], v[152:155], v[206:209], v[126:129]
	v_mfma_f32_16x16x32_bf16 v[122:125], v[160:163], v[206:209], v[122:125]
	v_mfma_f32_16x16x32_bf16 v[94:97], v[170:173], v[206:209], v[94:97]
	v_mfma_f32_16x16x32_bf16 v[90:93], v[178:181], v[206:209], v[90:93]
	v_mfma_f32_16x16x32_bf16 v[118:121], v[152:155], v[214:217], v[118:121]
	v_mfma_f32_16x16x32_bf16 v[114:117], v[160:163], v[214:217], v[114:117]
	v_mfma_f32_16x16x32_bf16 v[86:89], v[170:173], v[214:217], v[86:89]
	v_mfma_f32_16x16x32_bf16 v[82:85], v[178:181], v[214:217], v[82:85]
	v_mfma_f32_16x16x32_bf16 v[110:113], v[152:155], v[236:239], v[110:113]
	v_mfma_f32_16x16x32_bf16 v[106:109], v[160:163], v[236:239], v[106:109]
	v_mfma_f32_16x16x32_bf16 v[78:81], v[170:173], v[236:239], v[78:81]
	v_mfma_f32_16x16x32_bf16 v[74:77], v[178:181], v[236:239], v[74:77]
	v_mfma_f32_16x16x32_bf16 v[102:105], v[152:155], v[244:247], v[102:105]
	v_mfma_f32_16x16x32_bf16 v[98:101], v[160:163], v[244:247], v[98:101]
	v_mfma_f32_16x16x32_bf16 v[70:73], v[170:173], v[244:247], v[70:73]
	v_mfma_f32_16x16x32_bf16 v[66:69], v[178:181], v[244:247], v[66:69]
	s_barrier
	s_add_i32 s9, s9, s0
	s_mov_b32 m0, s9
	ds_read_b128 v[182:185], v165 offset:49152
	ds_read_b128 v[206:209], v165 offset:50176
	ds_read_b128 v[210:213], v165 offset:51200
	ds_read_b128 v[214:217], v165 offset:52224
	ds_read_b128 v[218:221], v165 offset:53248
	ds_read_b128 v[236:239], v165 offset:54272
	ds_read_b128 v[240:243], v165 offset:55296
	ds_read_b128 v[244:247], v165 offset:56320
	s_add_u32 s100, s80, s60
	s_addc_u32 s101, s81, s61
	global_load_lds_dwordx4 v132, s[100:101]
	s_add_i32 m0, s9, 0x2000
	s_add_u32 s10, s80, 0x20080
	s_addc_u32 s11, s81, 0
	s_add_i32 s9, s12, s0
	global_load_lds_dwordx4 v136, s[100:101]
	s_mov_b32 m0, s9
	s_nop 0
	global_load_lds_dwordx4 v132, s[10:11]
	s_add_i32 m0, s9, 0x2000
	s_nop 0
	global_load_lds_dwordx4 v136, s[10:11]
	s_mov_b32 m0, s66
	s_add_u32 s100, s84, s60
	s_addc_u32 s101, s85, s61
	global_load_lds_dwordx4 v130, s[100:101]
	s_mov_b32 m0, s67
	s_nop 0
	global_load_lds_dwordx4 v134, s[100:101]
	s_waitcnt vmcnt(8)
	s_waitcnt lgkmcnt(0)
	s_barrier
	v_mfma_f32_16x16x32_bf16 v[62:65], v[148:151], v[182:185], v[62:65]
	v_mfma_f32_16x16x32_bf16 v[58:61], v[156:159], v[182:185], v[58:61]
	v_mfma_f32_16x16x32_bf16 v[30:33], v[166:169], v[182:185], v[30:33]
	v_mfma_f32_16x16x32_bf16 v[26:29], v[174:177], v[182:185], v[26:29]
	v_mfma_f32_16x16x32_bf16 v[54:57], v[148:151], v[210:213], v[54:57]
	v_mfma_f32_16x16x32_bf16 v[50:53], v[156:159], v[210:213], v[50:53]
	v_mfma_f32_16x16x32_bf16 v[22:25], v[166:169], v[210:213], v[22:25]
	v_mfma_f32_16x16x32_bf16 v[18:21], v[174:177], v[210:213], v[18:21]
	v_mfma_f32_16x16x32_bf16 v[46:49], v[148:151], v[218:221], v[46:49]
	v_mfma_f32_16x16x32_bf16 v[42:45], v[156:159], v[218:221], v[42:45]
	v_mfma_f32_16x16x32_bf16 v[14:17], v[166:169], v[218:221], v[14:17]
	v_mfma_f32_16x16x32_bf16 v[10:13], v[174:177], v[218:221], v[10:13]
	v_mfma_f32_16x16x32_bf16 v[38:41], v[148:151], v[240:243], v[38:41]
	v_mfma_f32_16x16x32_bf16 v[34:37], v[156:159], v[240:243], v[34:37]
	v_mfma_f32_16x16x32_bf16 v[6:9], v[166:169], v[240:243], v[6:9]
	v_mfma_f32_16x16x32_bf16 v[2:5], v[174:177], v[240:243], v[2:5]
	v_mfma_f32_16x16x32_bf16 v[62:65], v[152:155], v[206:209], v[62:65]
	v_mfma_f32_16x16x32_bf16 v[58:61], v[160:163], v[206:209], v[58:61]
	v_mfma_f32_16x16x32_bf16 v[30:33], v[170:173], v[206:209], v[30:33]
	v_mfma_f32_16x16x32_bf16 v[26:29], v[178:181], v[206:209], v[26:29]
	v_mfma_f32_16x16x32_bf16 v[54:57], v[152:155], v[214:217], v[54:57]
	v_mfma_f32_16x16x32_bf16 v[50:53], v[160:163], v[214:217], v[50:53]
	v_mfma_f32_16x16x32_bf16 v[22:25], v[170:173], v[214:217], v[22:25]
	v_mfma_f32_16x16x32_bf16 v[18:21], v[178:181], v[214:217], v[18:21]
	v_mfma_f32_16x16x32_bf16 v[46:49], v[152:155], v[236:239], v[46:49]
	v_mfma_f32_16x16x32_bf16 v[42:45], v[160:163], v[236:239], v[42:45]
	v_mfma_f32_16x16x32_bf16 v[14:17], v[170:173], v[236:239], v[14:17]
	v_mfma_f32_16x16x32_bf16 v[10:13], v[178:181], v[236:239], v[10:13]
	v_mfma_f32_16x16x32_bf16 v[38:41], v[152:155], v[244:247], v[38:41]
	v_mfma_f32_16x16x32_bf16 v[34:37], v[160:163], v[244:247], v[34:37]
	v_mfma_f32_16x16x32_bf16 v[6:9], v[170:173], v[244:247], v[6:9]
	v_mfma_f32_16x16x32_bf16 v[2:5], v[178:181], v[244:247], v[2:5]
	s_barrier
	s_add_i32 s8, s8, 2
	s_add_u32 s46, s46, 0x100
	s_addc_u32 s47, s47, 0
	s_cmp_gt_u32 s8, 29
	s_cbranch_scc0 .LBB0_170
	s_and_b64 vcc, exec, s[54:55]
	s_cbranch_vccz .LBB0_173
	s_barrier

; #define PG8_STAGE(bufoff, gbase, voff) do { _Pragma("unroll") for (int _i = 0; _i < 2; ++_i) \
;         __builtin_amdgcn_global_load_lds((const unsigned*)((const char*)(gbase) + (voff)[_i]), (PG8_LAS unsigned*)(lds + (bufoff) + ldsw + _i * 8192), 16, 0, 0); } while (0)
; #define PG8_LDA(dst, b, h) do { _Pragma("unroll") for (int m = 0; m < 4; ++m) _Pragma("unroll") for (int k = 0; k < 2; ++k) dst[m][k] = *(const PG8_LAS bf16x8*)(lds + PG8_SA(b, h) + aoff + m * 2048 + k * 1024); } while (0)
; #define PG8_LDB(dst, b, h) do { _Pragma("unroll") for (int n = 0; n < 2; ++n) _Pragma("unroll") for (int k = 0; k < 2; ++k) dst[n][k] = *(const PG8_LAS bf16x8*)(lds + PG8_SB(b, h) + boff + n * 2048 + k * 1024); } while (0)
; #define PG8_MMA(ai, bj, At, Bt) do { __builtin_amdgcn_s_setprio(1); _Pragma("unroll") for (int m = 0; m < 4; ++m) _Pragma("unroll") for (int n = 0; n < 2; ++n) _Pragma("unroll") for (int k = 0; k < 2; ++k) \
;         acc[ai][bj][m][n] = __builtin_amdgcn_mfma_f32_16x16x32_bf16(Bt[n][k], At[m][k], acc[ai][bj][m][n], 0, 0, 0); __builtin_amdgcn_s_setprio(0); } while (0)
; #define PG8_BAR __builtin_amdgcn_s_barrier()
; template <class Epi, class Sched, bool ALIGN_EPI = false, bool SP2 = false>
; __device__ __forceinline__ void gemm_phase(PG8_LAS unsigned char* lds, const Gemm g, const Sched& S, const Epi& E) {
;     ...
;         const bool has_next = S.next(ui + 1, nxt);
;         const char* nA = has_next ? (const char*)g.A + (size_t)nxt.pm * tstep : cA; const char* nB = has_next ? (const char*)g.Bt + (size_t)nxt.pn * tstep : cB;
;         for (int t = 0; t < nt; t += 2) {
;             const bool last = (t == nt - 2);
;             const char* a1 = cA + (size_t)(t + 1) * kstep;
;             const char* a2 = last ? nA : cA + (size_t)(t + 2) * kstep; const char* b2 = last ? nB : cB + (size_t)(t + 2) * kstep;
;             const char* a3 = a2 + kstep; const char* b3 = b2 + kstep;
;             if (last && has_next) S.a_ready(nxt);
;             if constexpr (SP2) {
;             PG8_LDB(B0, 0, 0); PG8_LDB(B1, 0, 1); PG8_SCHED; PG8_LDA(At, 0, 0); PG8_STAGE(PG8_SA(1, 1), a1 + hstep, voffA);
;             PG8_WAIT_V(8); PG8_WAIT_L(0); PG8_BAR; PG8_MMA(0, 0, At, B0); PG8_MMA(0, 1, At, B1); PG8_BAR; PG8_SCHED;
;             PG8_LDA(At, 0, 1); PG8_STAGE(PG8_SB(0, 0), b2, voffB); PG8_STAGE(PG8_SB(0, 1), b2 + hstepB, voffB); PG8_STAGE(PG8_SA(0, 0), a2, voffA);
.LBB0_926:
	s_ashr_i32 s73, s72, 31
	s_lshl_b64 s[4:5], s[72:73], 20
	v_readlane_b32 s6, v249, 9
	v_readlane_b32 s7, v249, 10
	s_add_u32 s76, s6, s4
	s_addc_u32 s77, s7, s5
	s_and_b64 s[4:5], s[92:93], exec
	s_cselect_b32 s36, s77, s39
	s_cselect_b32 s37, s76, s38
	s_ashr_i32 s69, s68, 31
	s_lshl_b64 s[4:5], s[68:69], 20
	v_readlane_b32 s6, v249, 17
	v_readlane_b32 s7, v249, 18
	s_add_u32 s80, s6, s4
	s_addc_u32 s81, s7, s5
	s_and_b64 s[4:5], s[92:93], exec
	s_cselect_b32 s4, s81, s47
	s_cselect_b32 s5, s80, s46
	s_add_u32 s38, s38, 0x80080
	s_addc_u32 s39, s39, 0
	s_add_u32 s6, s46, 0x100
	v_mov_b32_e32 v2, 0
	s_addc_u32 s7, s47, 0
	s_mov_b32 s8, -2
	v_mov_b32_e32 v3, v2
	v_mov_b32_e32 v4, v2
	v_mov_b32_e32 v5, v2
	v_mov_b32_e32 v6, v2
	v_mov_b32_e32 v7, v2
	v_mov_b32_e32 v8, v2
	v_mov_b32_e32 v9, v2
	v_mov_b32_e32 v18, v2
	v_mov_b32_e32 v19, v2
	v_mov_b32_e32 v20, v2
	v_mov_b32_e32 v21, v2
	v_mov_b32_e32 v22, v2
	v_mov_b32_e32 v23, v2
	v_mov_b32_e32 v24, v2
	v_mov_b32_e32 v25, v2
	v_mov_b32_e32 v34, v2
	s_waitcnt lgkmcnt(0)
	v_add_u32_e32 v186, 0x10000, v193
	v_add_u32_e32 v187, 0x14000, v193
	v_add_u32_e32 v198, 0x18000, v193
	v_add_u32_e32 v199, 0x1c000, v193
	s_add_u32 s9, s38, 0xfff80080
	s_addc_u32 s10, s39, -1
	s_add_i32 s11, 0, 0x10000
	s_cmp_eq_u32 s8, 28
	s_cselect_b32 s95, s36, s10
	s_cselect_b32 s94, s37, s9
	s_cselect_b32 s47, s4, s7
	s_cselect_b32 s46, s5, s6
	s_add_i32 s9, 0, 0x14000
	ds_read_b128 v[66:69], v186
	ds_read_b128 v[70:73], v186 offset:1024
	ds_read_b128 v[78:81], v186 offset:2048
	ds_read_b128 v[86:89], v186 offset:3072
	ds_read_b128 v[146:149], v187
	ds_read_b128 v[150:153], v187 offset:1024
	ds_read_b128 v[154:157], v187 offset:2048
	ds_read_b128 v[158:161], v187 offset:3072
	s_add_i32 m0, s66, 0xc000
	ds_read_b128 v[162:165], v236
	ds_read_b128 v[166:169], v236 offset:1024
	ds_read_b128 v[170:173], v236 offset:2048
	ds_read_b128 v[174:177], v236 offset:3072
	ds_read_b128 v[178:181], v236 offset:4096
	ds_read_b128 v[182:185], v236 offset:5120
	ds_read_b128 v[216:219], v236 offset:6144
	ds_read_b128 v[220:223], v236 offset:7168
	global_load_lds_dwordx4 v212, s[38:39]
	s_add_i32 m0, s66, 0xe000
	s_nop 0
	global_load_lds_dwordx4 v214, s[38:39]
	s_waitcnt vmcnt(8)
	s_waitcnt lgkmcnt(0)
	s_barrier
	v_mfma_f32_16x16x32_bf16 v[142:145], v[66:69], v[162:165], 0
	v_mfma_f32_16x16x32_bf16 v[138:141], v[78:81], v[162:165], 0
	v_mfma_f32_16x16x32_bf16 v[134:137], v[146:149], v[162:165], 0
	v_mfma_f32_16x16x32_bf16 v[130:133], v[154:157], v[162:165], 0
	v_mfma_f32_16x16x32_bf16 v[126:129], v[66:69], v[170:173], 0
	v_mfma_f32_16x16x32_bf16 v[122:125], v[78:81], v[170:173], 0
	v_mfma_f32_16x16x32_bf16 v[118:121], v[146:149], v[170:173], 0
	v_mfma_f32_16x16x32_bf16 v[114:117], v[154:157], v[170:173], 0
	v_mfma_f32_16x16x32_bf16 v[110:113], v[66:69], v[178:181], 0
	v_mfma_f32_16x16x32_bf16 v[106:109], v[78:81], v[178:181], 0
	v_mfma_f32_16x16x32_bf16 v[102:105], v[146:149], v[178:181], 0
	v_mfma_f32_16x16x32_bf16 v[98:101], v[154:157], v[178:181], 0
	v_mfma_f32_16x16x32_bf16 v[94:97], v[66:69], v[216:219], 0
	v_mfma_f32_16x16x32_bf16 v[90:93], v[78:81], v[216:219], 0
	v_mfma_f32_16x16x32_bf16 v[82:85], v[146:149], v[216:219], 0
	v_mfma_f32_16x16x32_bf16 v[74:77], v[154:157], v[216:219], 0
	v_mfma_f32_16x16x32_bf16 v[142:145], v[70:73], v[166:169], v[142:145]
	v_mfma_f32_16x16x32_bf16 v[138:141], v[86:89], v[166:169], v[138:141]
	v_mfma_f32_16x16x32_bf16 v[134:137], v[150:153], v[166:169], v[134:137]
	v_mfma_f32_16x16x32_bf16 v[130:133], v[158:161], v[166:169], v[130:133]
	v_mfma_f32_16x16x32_bf16 v[126:129], v[70:73], v[174:177], v[126:129]
	v_mfma_f32_16x16x32_bf16 v[122:125], v[86:89], v[174:177], v[122:125]
	v_mfma_f32_16x16x32_bf16 v[118:121], v[150:153], v[174:177], v[118:121]
	v_mfma_f32_16x16x32_bf16 v[114:117], v[158:161], v[174:177], v[114:117]
	v_mfma_f32_16x16x32_bf16 v[110:113], v[70:73], v[182:185], v[110:113]
	v_mfma_f32_16x16x32_bf16 v[106:109], v[86:89], v[182:185], v[106:109]
	v_mfma_f32_16x16x32_bf16 v[102:105], v[150:153], v[182:185], v[102:105]
	v_mfma_f32_16x16x32_bf16 v[98:101], v[158:161], v[182:185], v[98:101]
	v_mfma_f32_16x16x32_bf16 v[94:97], v[70:73], v[220:223], v[94:97]
	v_mfma_f32_16x16x32_bf16 v[90:93], v[86:89], v[220:223], v[90:93]
	v_mfma_f32_16x16x32_bf16 v[82:85], v[150:153], v[220:223], v[82:85]
	v_mfma_f32_16x16x32_bf16 v[74:77], v[158:161], v[220:223], v[74:77]
	s_barrier
	s_add_i32 s10, s11, s25
	s_mov_b32 m0, s10
	ds_read_b128 v[162:165], v236 offset:16384
	ds_read_b128 v[166:169], v236 offset:17408
	ds_read_b128 v[170:173], v236 offset:18432
	ds_read_b128 v[174:177], v236 offset:19456
	ds_read_b128 v[178:181], v236 offset:20480
	ds_read_b128 v[182:185], v236 offset:21504
	ds_read_b128 v[216:219], v236 offset:22528
	ds_read_b128 v[220:223], v236 offset:23552
	global_load_lds_dwordx4 v190, s[46:47]
	s_add_i32 m0, s10, 0x2000
	s_add_u32 s10, s46, 0x20000
	s_addc_u32 s11, s47, 0
	s_add_i32 s9, s9, s25
	global_load_lds_dwordx4 v206, s[46:47]
	s_mov_b32 m0, s9
	s_nop 0
	global_load_lds_dwordx4 v190, s[10:11]
	s_add_i32 m0, s9, 0x2000
	s_nop 0
	global_load_lds_dwordx4 v206, s[10:11]
	s_mov_b32 m0, s66
	s_nop 0
	global_load_lds_dwordx4 v210, s[94:95]
	s_mov_b32 m0, s67
	s_nop 0
	global_load_lds_dwordx4 v208, s[94:95]
	s_waitcnt vmcnt(8)
	s_waitcnt lgkmcnt(0)
	s_barrier
; #define PG8_STAGE(bufoff, gbase, voff) do { _Pragma("unroll") for (int _i = 0; _i < 2; ++_i) \
;         __builtin_amdgcn_global_load_lds((const unsigned*)((const char*)(gbase) + (voff)[_i]), (PG8_LAS unsigned*)(lds + (bufoff) + ldsw + _i * 8192), 16, 0, 0); } while (0)
; #define PG8_LDA(dst, b, h) do { _Pragma("unroll") for (int m = 0; m < 4; ++m) _Pragma("unroll") for (int k = 0; k < 2; ++k) dst[m][k] = *(const PG8_LAS bf16x8*)(lds + PG8_SA(b, h) + aoff + m * 2048 + k * 1024); } while (0)
; #define PG8_LDB(dst, b, h) do { _Pragma("unroll") for (int n = 0; n < 2; ++n) _Pragma("unroll") for (int k = 0; k < 2; ++k) dst[n][k] = *(const PG8_LAS bf16x8*)(lds + PG8_SB(b, h) + boff + n * 2048 + k * 1024); } while (0)
; #define PG8_MMA(ai, bj, At, Bt) do { __builtin_amdgcn_s_setprio(1); _Pragma("unroll") for (int m = 0; m < 4; ++m) _Pragma("unroll") for (int n = 0; n < 2; ++n) _Pragma("unroll") for (int k = 0; k < 2; ++k) \
;         acc[ai][bj][m][n] = __builtin_amdgcn_mfma_f32_16x16x32_bf16(Bt[n][k], At[m][k], acc[ai][bj][m][n], 0, 0, 0); __builtin_amdgcn_s_setprio(0); } while (0)
; #define PG8_WAIT_V(n) asm volatile("s_waitcnt vmcnt(" #n ")" ::: "memory")
; #define PG8_WAIT_L(n) asm volatile("s_waitcnt lgkmcnt(" #n ")" ::: "memory")
; #define PG8_BAR __builtin_amdgcn_s_barrier()
; #define PG8_SCHED __builtin_amdgcn_sched_barrier(0)
; template <class Epi, class Sched, bool ALIGN_EPI = false, bool SP2 = false>
; __device__ __forceinline__ void gemm_phase(PG8_LAS unsigned char* lds, const Gemm g, const Sched& S, const Epi& E) {
;     ...
;             PG8_WAIT_V(8); PG8_WAIT_L(0); PG8_BAR; PG8_MMA(1, 0, At, B0); PG8_MMA(1, 1, At, B1); PG8_BAR; PG8_SCHED;
;             PG8_LDB(B0, 1, 0); PG8_LDB(B1, 1, 1); PG8_SCHED; PG8_LDA(At, 1, 0); PG8_STAGE(PG8_SA(0, 1), a2 + hstep, voffA);
;             PG8_WAIT_V(8); PG8_WAIT_L(0); PG8_BAR; PG8_MMA(0, 0, At, B0); PG8_MMA(0, 1, At, B1); PG8_BAR; PG8_SCHED;
	v_mfma_f32_16x16x32_bf16 v[62:65], v[66:69], v[162:165], 0
	v_mfma_f32_16x16x32_bf16 v[58:61], v[78:81], v[162:165], 0
	v_mfma_f32_16x16x32_bf16 v[54:57], v[146:149], v[162:165], 0
	v_mfma_f32_16x16x32_bf16 v[50:53], v[154:157], v[162:165], 0
	v_mfma_f32_16x16x32_bf16 v[46:49], v[66:69], v[170:173], 0
	v_mfma_f32_16x16x32_bf16 v[42:45], v[78:81], v[170:173], 0
	v_mfma_f32_16x16x32_bf16 v[38:41], v[146:149], v[170:173], 0
	v_mfma_f32_16x16x32_bf16 v[34:37], v[154:157], v[170:173], 0
	v_mfma_f32_16x16x32_bf16 v[30:33], v[66:69], v[178:181], 0
	v_mfma_f32_16x16x32_bf16 v[26:29], v[78:81], v[178:181], 0
	v_mfma_f32_16x16x32_bf16 v[22:25], v[146:149], v[178:181], 0
	v_mfma_f32_16x16x32_bf16 v[18:21], v[154:157], v[178:181], 0
	v_mfma_f32_16x16x32_bf16 v[14:17], v[66:69], v[216:219], 0
	v_mfma_f32_16x16x32_bf16 v[10:13], v[78:81], v[216:219], 0
	v_mfma_f32_16x16x32_bf16 v[6:9], v[146:149], v[216:219], 0
	v_mfma_f32_16x16x32_bf16 v[2:5], v[154:157], v[216:219], 0
	v_mfma_f32_16x16x32_bf16 v[62:65], v[70:73], v[166:169], v[62:65]
	v_mfma_f32_16x16x32_bf16 v[58:61], v[86:89], v[166:169], v[58:61]
	v_mfma_f32_16x16x32_bf16 v[54:57], v[150:153], v[166:169], v[54:57]
	v_mfma_f32_16x16x32_bf16 v[50:53], v[158:161], v[166:169], v[50:53]
	v_mfma_f32_16x16x32_bf16 v[46:49], v[70:73], v[174:177], v[46:49]
	v_mfma_f32_16x16x32_bf16 v[42:45], v[86:89], v[174:177], v[42:45]
	v_mfma_f32_16x16x32_bf16 v[38:41], v[150:153], v[174:177], v[38:41]
	v_mfma_f32_16x16x32_bf16 v[34:37], v[158:161], v[174:177], v[34:37]
	v_mfma_f32_16x16x32_bf16 v[30:33], v[70:73], v[182:185], v[30:33]
	v_mfma_f32_16x16x32_bf16 v[26:29], v[86:89], v[182:185], v[26:29]
	v_mfma_f32_16x16x32_bf16 v[22:25], v[150:153], v[182:185], v[22:25]
	v_mfma_f32_16x16x32_bf16 v[18:21], v[158:161], v[182:185], v[18:21]
	v_mfma_f32_16x16x32_bf16 v[14:17], v[70:73], v[220:223], v[14:17]
	v_mfma_f32_16x16x32_bf16 v[10:13], v[86:89], v[220:223], v[10:13]
	v_mfma_f32_16x16x32_bf16 v[6:9], v[150:153], v[220:223], v[6:9]
	v_mfma_f32_16x16x32_bf16 v[2:5], v[158:161], v[220:223], v[2:5]
	s_barrier
	s_add_i32 s9, 0, 0x18000
	s_add_i32 s12, 0, 0x1c000
	ds_read_b128 v[66:69], v198
	ds_read_b128 v[70:73], v198 offset:1024
	ds_read_b128 v[78:81], v198 offset:2048
	ds_read_b128 v[86:89], v198 offset:3072
	ds_read_b128 v[146:149], v199
	ds_read_b128 v[150:153], v199 offset:1024
	ds_read_b128 v[154:157], v199 offset:2048
	ds_read_b128 v[158:161], v199 offset:3072
	s_add_u32 s10, s94, 0x80000
	s_addc_u32 s11, s95, 0
	s_mov_b32 m0, s59
	ds_read_b128 v[162:165], v236 offset:32768
	ds_read_b128 v[166:169], v236 offset:33792
	ds_read_b128 v[170:173], v236 offset:34816
	ds_read_b128 v[174:177], v236 offset:35840
	ds_read_b128 v[178:181], v236 offset:36864
	ds_read_b128 v[182:185], v236 offset:37888
	ds_read_b128 v[216:219], v236 offset:38912
	ds_read_b128 v[220:223], v236 offset:39936
	global_load_lds_dwordx4 v210, s[10:11]
	s_mov_b32 m0, s74
	s_nop 0
	global_load_lds_dwordx4 v208, s[10:11]
	s_waitcnt vmcnt(8)
	s_waitcnt lgkmcnt(0)
	s_barrier
	v_mfma_f32_16x16x32_bf16 v[142:145], v[66:69], v[162:165], v[142:145]
	v_mfma_f32_16x16x32_bf16 v[138:141], v[78:81], v[162:165], v[138:141]
	v_mfma_f32_16x16x32_bf16 v[134:137], v[146:149], v[162:165], v[134:137]
	v_mfma_f32_16x16x32_bf16 v[130:133], v[154:157], v[162:165], v[130:133]
	v_mfma_f32_16x16x32_bf16 v[126:129], v[66:69], v[170:173], v[126:129]
	v_mfma_f32_16x16x32_bf16 v[122:125], v[78:81], v[170:173], v[122:125]
	v_mfma_f32_16x16x32_bf16 v[118:121], v[146:149], v[170:173], v[118:121]
	v_mfma_f32_16x16x32_bf16 v[114:117], v[154:157], v[170:173], v[114:117]
	v_mfma_f32_16x16x32_bf16 v[110:113], v[66:69], v[178:181], v[110:113]
	v_mfma_f32_16x16x32_bf16 v[106:109], v[78:81], v[178:181], v[106:109]
	v_mfma_f32_16x16x32_bf16 v[102:105], v[146:149], v[178:181], v[102:105]
	v_mfma_f32_16x16x32_bf16 v[98:101], v[154:157], v[178:181], v[98:101]
	v_mfma_f32_16x16x32_bf16 v[94:97], v[66:69], v[216:219], v[94:97]
	v_mfma_f32_16x16x32_bf16 v[90:93], v[78:81], v[216:219], v[90:93]
	v_mfma_f32_16x16x32_bf16 v[82:85], v[146:149], v[216:219], v[82:85]
	v_mfma_f32_16x16x32_bf16 v[74:77], v[154:157], v[216:219], v[74:77]
	v_mfma_f32_16x16x32_bf16 v[142:145], v[70:73], v[166:169], v[142:145]
	v_mfma_f32_16x16x32_bf16 v[138:141], v[86:89], v[166:169], v[138:141]
	v_mfma_f32_16x16x32_bf16 v[134:137], v[150:153], v[166:169], v[134:137]
	v_mfma_f32_16x16x32_bf16 v[130:133], v[158:161], v[166:169], v[130:133]
	v_mfma_f32_16x16x32_bf16 v[126:129], v[70:73], v[174:177], v[126:129]
	v_mfma_f32_16x16x32_bf16 v[122:125], v[86:89], v[174:177], v[122:125]
	v_mfma_f32_16x16x32_bf16 v[118:121], v[150:153], v[174:177], v[118:121]
	v_mfma_f32_16x16x32_bf16 v[114:117], v[158:161], v[174:177], v[114:117]
	v_mfma_f32_16x16x32_bf16 v[110:113], v[70:73], v[182:185], v[110:113]
	v_mfma_f32_16x16x32_bf16 v[106:109], v[86:89], v[182:185], v[106:109]
	v_mfma_f32_16x16x32_bf16 v[102:105], v[150:153], v[182:185], v[102:105]
	v_mfma_f32_16x16x32_bf16 v[98:101], v[158:161], v[182:185], v[98:101]
	v_mfma_f32_16x16x32_bf16 v[94:97], v[70:73], v[220:223], v[94:97]
	v_mfma_f32_16x16x32_bf16 v[90:93], v[86:89], v[220:223], v[90:93]
	v_mfma_f32_16x16x32_bf16 v[82:85], v[150:153], v[220:223], v[82:85]
	v_mfma_f32_16x16x32_bf16 v[74:77], v[158:161], v[220:223], v[74:77]
	s_barrier
; #define PG8_STAGE(bufoff, gbase, voff) do { _Pragma("unroll") for (int _i = 0; _i < 2; ++_i) \
;         __builtin_amdgcn_global_load_lds((const unsigned*)((const char*)(gbase) + (voff)[_i]), (PG8_LAS unsigned*)(lds + (bufoff) + ldsw + _i * 8192), 16, 0, 0); } while (0)
; #define PG8_LDA(dst, b, h) do { _Pragma("unroll") for (int m = 0; m < 4; ++m) _Pragma("unroll") for (int k = 0; k < 2; ++k) dst[m][k] = *(const PG8_LAS bf16x8*)(lds + PG8_SA(b, h) + aoff + m * 2048 + k * 1024); } while (0)
; #define PG8_LDB(dst, b, h) do { _Pragma("unroll") for (int n = 0; n < 2; ++n) _Pragma("unroll") for (int k = 0; k < 2; ++k) dst[n][k] = *(const PG8_LAS bf16x8*)(lds + PG8_SB(b, h) + boff + n * 2048 + k * 1024); } while (0)
; #define PG8_MMA(ai, bj, At, Bt) do { __builtin_amdgcn_s_setprio(1); _Pragma("unroll") for (int m = 0; m < 4; ++m) _Pragma("unroll") for (int n = 0; n < 2; ++n) _Pragma("unroll") for (int k = 0; k < 2; ++k) \
;         acc[ai][bj][m][n] = __builtin_amdgcn_mfma_f32_16x16x32_bf16(Bt[n][k], At[m][k], acc[ai][bj][m][n], 0, 0, 0); __builtin_amdgcn_s_setprio(0); } while (0)
; #define PG8_WAIT_V(n) asm volatile("s_waitcnt vmcnt(" #n ")" ::: "memory")
; template <class Epi, class Sched, bool ALIGN_EPI = false, bool SP2 = false>
; __device__ __forceinline__ void gemm_phase(PG8_LAS unsigned char* lds, const Gemm g, const Sched& S, const Epi& E) {
;     ...
;             PG8_LDB(B0, 0, 0); PG8_LDB(B1, 0, 1); PG8_SCHED; PG8_LDA(At, 0, 0); PG8_STAGE(PG8_SA(1, 1), a1 + hstep, voffA);
;             PG8_WAIT_V(8); PG8_WAIT_L(0); PG8_BAR; PG8_MMA(0, 0, At, B0); PG8_MMA(0, 1, At, B1); PG8_BAR; PG8_SCHED;
;             PG8_LDA(At, 0, 1); PG8_STAGE(PG8_SB(0, 0), b2, voffB); PG8_STAGE(PG8_SB(0, 1), b2 + hstepB, voffB); PG8_STAGE(PG8_SA(0, 0), a2, voffA);
;             PG8_WAIT_V(8); PG8_WAIT_L(0); PG8_BAR; PG8_MMA(1, 0, At, B0); PG8_MMA(1, 1, At, B1); PG8_BAR; PG8_SCHED;
;             PG8_LDB(B0, 1, 0); PG8_LDB(B1, 1, 1); PG8_SCHED; PG8_LDA(At, 1, 0); PG8_STAGE(PG8_SA(0, 1), a2 + hstep, voffA);
;             PG8_WAIT_V(8); PG8_WAIT_L(0); PG8_BAR; PG8_MMA(0, 0, At, B0); PG8_MMA(0, 1, At, B1); PG8_BAR; PG8_SCHED;
;             PG8_LDA(At, 1, 1); PG8_STAGE(PG8_SB(1, 0), b3, voffB); PG8_STAGE(PG8_SB(1, 1), b3 + hstepB, voffB); PG8_STAGE(PG8_SA(1, 0), a3, voffA);
;             PG8_WAIT_V(8); PG8_WAIT_L(0); PG8_BAR; PG8_MMA(1, 0, At, B0); PG8_MMA(1, 1, At, B1); PG8_BAR; PG8_SCHED;
	s_add_i32 s9, s9, s25
	s_mov_b32 m0, s9
	ds_read_b128 v[162:165], v236 offset:49152
	ds_read_b128 v[166:169], v236 offset:50176
	ds_read_b128 v[170:173], v236 offset:51200
	ds_read_b128 v[174:177], v236 offset:52224
	ds_read_b128 v[178:181], v236 offset:53248
	ds_read_b128 v[182:185], v236 offset:54272
	ds_read_b128 v[216:219], v236 offset:55296
	ds_read_b128 v[220:223], v236 offset:56320
	s_add_u32 s100, s46, s60
	s_addc_u32 s101, s47, s61
	global_load_lds_dwordx4 v190, s[100:101]
	s_add_i32 m0, s9, 0x2000
	s_add_u32 s10, s46, 0x20080
	s_addc_u32 s11, s47, 0
	s_add_i32 s9, s12, s25
	global_load_lds_dwordx4 v206, s[100:101]
	s_mov_b32 m0, s9
	s_nop 0
	global_load_lds_dwordx4 v190, s[10:11]
	s_add_i32 m0, s9, 0x2000
	s_nop 0
	global_load_lds_dwordx4 v206, s[10:11]
	s_mov_b32 m0, s75
	s_add_u32 s100, s94, s60
	s_addc_u32 s101, s95, s61
	global_load_lds_dwordx4 v210, s[100:101]
	s_mov_b32 m0, s0
	s_nop 0
	global_load_lds_dwordx4 v208, s[100:101]
	s_waitcnt vmcnt(8)
	s_waitcnt lgkmcnt(0)
	s_barrier
	v_mfma_f32_16x16x32_bf16 v[62:65], v[66:69], v[162:165], v[62:65]
	v_mfma_f32_16x16x32_bf16 v[58:61], v[78:81], v[162:165], v[58:61]
	v_mfma_f32_16x16x32_bf16 v[54:57], v[146:149], v[162:165], v[54:57]
	v_mfma_f32_16x16x32_bf16 v[50:53], v[154:157], v[162:165], v[50:53]
	v_mfma_f32_16x16x32_bf16 v[46:49], v[66:69], v[170:173], v[46:49]
	v_mfma_f32_16x16x32_bf16 v[42:45], v[78:81], v[170:173], v[42:45]
	v_mfma_f32_16x16x32_bf16 v[38:41], v[146:149], v[170:173], v[38:41]
	v_mfma_f32_16x16x32_bf16 v[34:37], v[154:157], v[170:173], v[34:37]
	v_mfma_f32_16x16x32_bf16 v[30:33], v[66:69], v[178:181], v[30:33]
	v_mfma_f32_16x16x32_bf16 v[26:29], v[78:81], v[178:181], v[26:29]
	v_mfma_f32_16x16x32_bf16 v[22:25], v[146:149], v[178:181], v[22:25]
	v_mfma_f32_16x16x32_bf16 v[18:21], v[154:157], v[178:181], v[18:21]
	v_mfma_f32_16x16x32_bf16 v[14:17], v[66:69], v[216:219], v[14:17]
	v_mfma_f32_16x16x32_bf16 v[10:13], v[78:81], v[216:219], v[10:13]
	v_mfma_f32_16x16x32_bf16 v[6:9], v[146:149], v[216:219], v[6:9]
	v_mfma_f32_16x16x32_bf16 v[2:5], v[154:157], v[216:219], v[2:5]
	v_mfma_f32_16x16x32_bf16 v[62:65], v[70:73], v[166:169], v[62:65]
	v_mfma_f32_16x16x32_bf16 v[58:61], v[86:89], v[166:169], v[58:61]
	v_mfma_f32_16x16x32_bf16 v[54:57], v[150:153], v[166:169], v[54:57]
	v_mfma_f32_16x16x32_bf16 v[50:53], v[158:161], v[166:169], v[50:53]
	v_mfma_f32_16x16x32_bf16 v[46:49], v[70:73], v[174:177], v[46:49]
	v_mfma_f32_16x16x32_bf16 v[42:45], v[86:89], v[174:177], v[42:45]
	v_mfma_f32_16x16x32_bf16 v[38:41], v[150:153], v[174:177], v[38:41]
	v_mfma_f32_16x16x32_bf16 v[34:37], v[158:161], v[174:177], v[34:37]
	v_mfma_f32_16x16x32_bf16 v[30:33], v[70:73], v[182:185], v[30:33]
	v_mfma_f32_16x16x32_bf16 v[26:29], v[86:89], v[182:185], v[26:29]
	v_mfma_f32_16x16x32_bf16 v[22:25], v[150:153], v[182:185], v[22:25]
	v_mfma_f32_16x16x32_bf16 v[18:21], v[158:161], v[182:185], v[18:21]
	v_mfma_f32_16x16x32_bf16 v[14:17], v[70:73], v[220:223], v[14:17]
	v_mfma_f32_16x16x32_bf16 v[10:13], v[86:89], v[220:223], v[10:13]
	v_mfma_f32_16x16x32_bf16 v[6:9], v[150:153], v[220:223], v[6:9]
	v_mfma_f32_16x16x32_bf16 v[2:5], v[158:161], v[220:223], v[2:5]
	s_barrier
	s_add_i32 s8, s8, 2
	s_add_u32 s38, s38, 0x100
	s_addc_u32 s39, s39, 0
	s_add_u32 s6, s6, 0x100
	s_addc_u32 s7, s7, 0
	s_cmp_gt_u32 s8, 29
.LBB0_927:
	s_add_u32 s9, s38, 0xfff80080
	s_addc_u32 s10, s39, -1
	s_add_i32 s11, 0, 0x10000
	s_cmp_eq_u32 s8, 28
	s_cselect_b32 s95, s36, s10
	s_cselect_b32 s94, s37, s9
	s_cselect_b32 s47, s4, s7
	s_cselect_b32 s46, s5, s6
	s_add_i32 s9, 0, 0x14000
	ds_read_b128 v[66:69], v186
	ds_read_b128 v[70:73], v186 offset:1024
	ds_read_b128 v[78:81], v186 offset:2048
	ds_read_b128 v[86:89], v186 offset:3072
	ds_read_b128 v[146:149], v187
	ds_read_b128 v[150:153], v187 offset:1024
	ds_read_b128 v[154:157], v187 offset:2048
	ds_read_b128 v[158:161], v187 offset:3072
	s_add_i32 m0, s66, 0xc000
	ds_read_b128 v[162:165], v236
	ds_read_b128 v[166:169], v236 offset:1024
	ds_read_b128 v[170:173], v236 offset:2048
	ds_read_b128 v[174:177], v236 offset:3072
	ds_read_b128 v[178:181], v236 offset:4096
	ds_read_b128 v[182:185], v236 offset:5120
	ds_read_b128 v[216:219], v236 offset:6144
	ds_read_b128 v[220:223], v236 offset:7168
	global_load_lds_dwordx4 v212, s[38:39]
	s_add_i32 m0, s66, 0xe000
	s_nop 0
	global_load_lds_dwordx4 v214, s[38:39]
	s_waitcnt vmcnt(8)
	s_waitcnt lgkmcnt(0)
	s_barrier
	v_mfma_f32_16x16x32_bf16 v[142:145], v[66:69], v[162:165], v[142:145]
	v_mfma_f32_16x16x32_bf16 v[138:141], v[78:81], v[162:165], v[138:141]
	v_mfma_f32_16x16x32_bf16 v[134:137], v[146:149], v[162:165], v[134:137]
	v_mfma_f32_16x16x32_bf16 v[130:133], v[154:157], v[162:165], v[130:133]
	v_mfma_f32_16x16x32_bf16 v[126:129], v[66:69], v[170:173], v[126:129]
	v_mfma_f32_16x16x32_bf16 v[122:125], v[78:81], v[170:173], v[122:125]
	v_mfma_f32_16x16x32_bf16 v[118:121], v[146:149], v[170:173], v[118:121]
	v_mfma_f32_16x16x32_bf16 v[114:117], v[154:157], v[170:173], v[114:117]
	v_mfma_f32_16x16x32_bf16 v[110:113], v[66:69], v[178:181], v[110:113]
	v_mfma_f32_16x16x32_bf16 v[106:109], v[78:81], v[178:181], v[106:109]
	v_mfma_f32_16x16x32_bf16 v[102:105], v[146:149], v[178:181], v[102:105]
	v_mfma_f32_16x16x32_bf16 v[98:101], v[154:157], v[178:181], v[98:101]
	v_mfma_f32_16x16x32_bf16 v[94:97], v[66:69], v[216:219], v[94:97]
	v_mfma_f32_16x16x32_bf16 v[90:93], v[78:81], v[216:219], v[90:93]
	v_mfma_f32_16x16x32_bf16 v[82:85], v[146:149], v[216:219], v[82:85]
	v_mfma_f32_16x16x32_bf16 v[74:77], v[154:157], v[216:219], v[74:77]
	v_mfma_f32_16x16x32_bf16 v[142:145], v[70:73], v[166:169], v[142:145]
	v_mfma_f32_16x16x32_bf16 v[138:141], v[86:89], v[166:169], v[138:141]
	v_mfma_f32_16x16x32_bf16 v[134:137], v[150:153], v[166:169], v[134:137]
	v_mfma_f32_16x16x32_bf16 v[130:133], v[158:161], v[166:169], v[130:133]
	v_mfma_f32_16x16x32_bf16 v[126:129], v[70:73], v[174:177], v[126:129]
	v_mfma_f32_16x16x32_bf16 v[122:125], v[86:89], v[174:177], v[122:125]
	v_mfma_f32_16x16x32_bf16 v[118:121], v[150:153], v[174:177], v[118:121]
	v_mfma_f32_16x16x32_bf16 v[114:117], v[158:161], v[174:177], v[114:117]
	v_mfma_f32_16x16x32_bf16 v[110:113], v[70:73], v[182:185], v[110:113]
	v_mfma_f32_16x16x32_bf16 v[106:109], v[86:89], v[182:185], v[106:109]
	v_mfma_f32_16x16x32_bf16 v[102:105], v[150:153], v[182:185], v[102:105]
	v_mfma_f32_16x16x32_bf16 v[98:101], v[158:161], v[182:185], v[98:101]
	v_mfma_f32_16x16x32_bf16 v[94:97], v[70:73], v[220:223], v[94:97]
	v_mfma_f32_16x16x32_bf16 v[90:93], v[86:89], v[220:223], v[90:93]
	v_mfma_f32_16x16x32_bf16 v[82:85], v[150:153], v[220:223], v[82:85]
	v_mfma_f32_16x16x32_bf16 v[74:77], v[158:161], v[220:223], v[74:77]
	s_barrier
; #define PG8_STAGE(bufoff, gbase, voff) do { _Pragma("unroll") for (int _i = 0; _i < 2; ++_i) \
;         __builtin_amdgcn_global_load_lds((const unsigned*)((const char*)(gbase) + (voff)[_i]), (PG8_LAS unsigned*)(lds + (bufoff) + ldsw + _i * 8192), 16, 0, 0); } while (0)
; #define PG8_LDA(dst, b, h) do { _Pragma("unroll") for (int m = 0; m < 4; ++m) _Pragma("unroll") for (int k = 0; k < 2; ++k) dst[m][k] = *(const PG8_LAS bf16x8*)(lds + PG8_SA(b, h) + aoff + m * 2048 + k * 1024); } while (0)
; #define PG8_LDB(dst, b, h) do { _Pragma("unroll") for (int n = 0; n < 2; ++n) _Pragma("unroll") for (int k = 0; k < 2; ++k) dst[n][k] = *(const PG8_LAS bf16x8*)(lds + PG8_SB(b, h) + boff + n * 2048 + k * 1024); } while (0)
; #define PG8_MMA(ai, bj, At, Bt) do { __builtin_amdgcn_s_setprio(1); _Pragma("unroll") for (int m = 0; m < 4; ++m) _Pragma("unroll") for (int n = 0; n < 2; ++n) _Pragma("unroll") for (int k = 0; k < 2; ++k) \
;         acc[ai][bj][m][n] = __builtin_amdgcn_mfma_f32_16x16x32_bf16(Bt[n][k], At[m][k], acc[ai][bj][m][n], 0, 0, 0); __builtin_amdgcn_s_setprio(0); } while (0)
; #define PG8_WAIT_V(n) asm volatile("s_waitcnt vmcnt(" #n ")" ::: "memory")
; #define PG8_WAIT_L(n) asm volatile("s_waitcnt lgkmcnt(" #n ")" ::: "memory")
; #define PG8_BAR __builtin_amdgcn_s_barrier()
; #define PG8_SCHED __builtin_amdgcn_sched_barrier(0)
; template <class Epi, class Sched, bool ALIGN_EPI = false, bool SP2 = false>
; __device__ __forceinline__ void gemm_phase(PG8_LAS unsigned char* lds, const Gemm g, const Sched& S, const Epi& E) {
;     ...
;             PG8_LDA(At, 0, 1); PG8_STAGE(PG8_SB(0, 0), b2, voffB); PG8_STAGE(PG8_SB(0, 1), b2 + hstepB, voffB); PG8_STAGE(PG8_SA(0, 0), a2, voffA);
;             PG8_WAIT_V(8); PG8_WAIT_L(0); PG8_BAR; PG8_MMA(1, 0, At, B0); PG8_MMA(1, 1, At, B1); PG8_BAR; PG8_SCHED;
;             PG8_LDB(B0, 1, 0); PG8_LDB(B1, 1, 1); PG8_SCHED; PG8_LDA(At, 1, 0); PG8_STAGE(PG8_SA(0, 1), a2 + hstep, voffA);
	s_add_i32 s10, s11, s25
	s_mov_b32 m0, s10
	ds_read_b128 v[162:165], v236 offset:16384
	ds_read_b128 v[166:169], v236 offset:17408
	ds_read_b128 v[170:173], v236 offset:18432
	ds_read_b128 v[174:177], v236 offset:19456
	ds_read_b128 v[178:181], v236 offset:20480
	ds_read_b128 v[182:185], v236 offset:21504
	ds_read_b128 v[216:219], v236 offset:22528
	ds_read_b128 v[220:223], v236 offset:23552
	global_load_lds_dwordx4 v190, s[46:47]
	s_add_i32 m0, s10, 0x2000
	s_add_u32 s10, s46, 0x20000
	s_addc_u32 s11, s47, 0
	s_add_i32 s9, s9, s25
	global_load_lds_dwordx4 v206, s[46:47]
	s_mov_b32 m0, s9
	s_nop 0
	global_load_lds_dwordx4 v190, s[10:11]
	s_add_i32 m0, s9, 0x2000
	s_nop 0
	global_load_lds_dwordx4 v206, s[10:11]
	s_mov_b32 m0, s66
	s_nop 0
	global_load_lds_dwordx4 v210, s[94:95]
	s_mov_b32 m0, s67
	s_nop 0
	global_load_lds_dwordx4 v208, s[94:95]
	s_waitcnt vmcnt(8)
	s_waitcnt lgkmcnt(0)
	s_barrier
	v_mfma_f32_16x16x32_bf16 v[62:65], v[66:69], v[162:165], v[62:65]
	v_mfma_f32_16x16x32_bf16 v[58:61], v[78:81], v[162:165], v[58:61]
	v_mfma_f32_16x16x32_bf16 v[54:57], v[146:149], v[162:165], v[54:57]
	v_mfma_f32_16x16x32_bf16 v[50:53], v[154:157], v[162:165], v[50:53]
	v_mfma_f32_16x16x32_bf16 v[46:49], v[66:69], v[170:173], v[46:49]
	v_mfma_f32_16x16x32_bf16 v[42:45], v[78:81], v[170:173], v[42:45]
	v_mfma_f32_16x16x32_bf16 v[38:41], v[146:149], v[170:173], v[38:41]
	v_mfma_f32_16x16x32_bf16 v[34:37], v[154:157], v[170:173], v[34:37]
	v_mfma_f32_16x16x32_bf16 v[30:33], v[66:69], v[178:181], v[30:33]
	v_mfma_f32_16x16x32_bf16 v[26:29], v[78:81], v[178:181], v[26:29]
	v_mfma_f32_16x16x32_bf16 v[22:25], v[146:149], v[178:181], v[22:25]
	v_mfma_f32_16x16x32_bf16 v[18:21], v[154:157], v[178:181], v[18:21]
	v_mfma_f32_16x16x32_bf16 v[14:17], v[66:69], v[216:219], v[14:17]
	v_mfma_f32_16x16x32_bf16 v[10:13], v[78:81], v[216:219], v[10:13]
	v_mfma_f32_16x16x32_bf16 v[6:9], v[146:149], v[216:219], v[6:9]
	v_mfma_f32_16x16x32_bf16 v[2:5], v[154:157], v[216:219], v[2:5]
	v_mfma_f32_16x16x32_bf16 v[62:65], v[70:73], v[166:169], v[62:65]
	v_mfma_f32_16x16x32_bf16 v[58:61], v[86:89], v[166:169], v[58:61]
	v_mfma_f32_16x16x32_bf16 v[54:57], v[150:153], v[166:169], v[54:57]
	v_mfma_f32_16x16x32_bf16 v[50:53], v[158:161], v[166:169], v[50:53]
	v_mfma_f32_16x16x32_bf16 v[46:49], v[70:73], v[174:177], v[46:49]
	v_mfma_f32_16x16x32_bf16 v[42:45], v[86:89], v[174:177], v[42:45]
	v_mfma_f32_16x16x32_bf16 v[38:41], v[150:153], v[174:177], v[38:41]
	v_mfma_f32_16x16x32_bf16 v[34:37], v[158:161], v[174:177], v[34:37]
	v_mfma_f32_16x16x32_bf16 v[30:33], v[70:73], v[182:185], v[30:33]
	v_mfma_f32_16x16x32_bf16 v[26:29], v[86:89], v[182:185], v[26:29]
	v_mfma_f32_16x16x32_bf16 v[22:25], v[150:153], v[182:185], v[22:25]
	v_mfma_f32_16x16x32_bf16 v[18:21], v[158:161], v[182:185], v[18:21]
	v_mfma_f32_16x16x32_bf16 v[14:17], v[70:73], v[220:223], v[14:17]
	v_mfma_f32_16x16x32_bf16 v[10:13], v[86:89], v[220:223], v[10:13]
	v_mfma_f32_16x16x32_bf16 v[6:9], v[150:153], v[220:223], v[6:9]
	v_mfma_f32_16x16x32_bf16 v[2:5], v[158:161], v[220:223], v[2:5]
	s_barrier
	s_add_i32 s9, 0, 0x18000
	s_add_i32 s12, 0, 0x1c000
	ds_read_b128 v[66:69], v198
	ds_read_b128 v[70:73], v198 offset:1024
	ds_read_b128 v[78:81], v198 offset:2048
	ds_read_b128 v[86:89], v198 offset:3072
	ds_read_b128 v[146:149], v199
	ds_read_b128 v[150:153], v199 offset:1024
	ds_read_b128 v[154:157], v199 offset:2048
	ds_read_b128 v[158:161], v199 offset:3072
	s_add_u32 s10, s94, 0x80000
	s_addc_u32 s11, s95, 0
	s_mov_b32 m0, s59
	ds_read_b128 v[162:165], v236 offset:32768
	ds_read_b128 v[166:169], v236 offset:33792
	ds_read_b128 v[170:173], v236 offset:34816
	ds_read_b128 v[174:177], v236 offset:35840
	ds_read_b128 v[178:181], v236 offset:36864
	ds_read_b128 v[182:185], v236 offset:37888
	ds_read_b128 v[216:219], v236 offset:38912
	ds_read_b128 v[220:223], v236 offset:39936
	global_load_lds_dwordx4 v210, s[10:11]
	s_mov_b32 m0, s74
	s_nop 0
	global_load_lds_dwordx4 v208, s[10:11]
	s_waitcnt vmcnt(8)
	s_waitcnt lgkmcnt(0)
	s_barrier
; #define PG8_STAGE(bufoff, gbase, voff) do { _Pragma("unroll") for (int _i = 0; _i < 2; ++_i) \
;         __builtin_amdgcn_global_load_lds((const unsigned*)((const char*)(gbase) + (voff)[_i]), (PG8_LAS unsigned*)(lds + (bufoff) + ldsw + _i * 8192), 16, 0, 0); } while (0)
; #define PG8_LDA(dst, b, h) do { _Pragma("unroll") for (int m = 0; m < 4; ++m) _Pragma("unroll") for (int k = 0; k < 2; ++k) dst[m][k] = *(const PG8_LAS bf16x8*)(lds + PG8_SA(b, h) + aoff + m * 2048 + k * 1024); } while (0)
; #define PG8_MMA(ai, bj, At, Bt) do { __builtin_amdgcn_s_setprio(1); _Pragma("unroll") for (int m = 0; m < 4; ++m) _Pragma("unroll") for (int n = 0; n < 2; ++n) _Pragma("unroll") for (int k = 0; k < 2; ++k) \
;         acc[ai][bj][m][n] = __builtin_amdgcn_mfma_f32_16x16x32_bf16(Bt[n][k], At[m][k], acc[ai][bj][m][n], 0, 0, 0); __builtin_amdgcn_s_setprio(0); } while (0)
; #define PG8_WAIT_V(n) asm volatile("s_waitcnt vmcnt(" #n ")" ::: "memory")
; #define PG8_WAIT_L(n) asm volatile("s_waitcnt lgkmcnt(" #n ")" ::: "memory")
; #define PG8_BAR __builtin_amdgcn_s_barrier()
; #define PG8_SCHED __builtin_amdgcn_sched_barrier(0)
; template <class Epi, class Sched, bool ALIGN_EPI = false, bool SP2 = false>
; __device__ __forceinline__ void gemm_phase(PG8_LAS unsigned char* lds, const Gemm g, const Sched& S, const Epi& E) {
;     ...
;             PG8_WAIT_V(8); PG8_WAIT_L(0); PG8_BAR; PG8_MMA(0, 0, At, B0); PG8_MMA(0, 1, At, B1); PG8_BAR; PG8_SCHED;
;             PG8_LDA(At, 1, 1); PG8_STAGE(PG8_SB(1, 0), b3, voffB); PG8_STAGE(PG8_SB(1, 1), b3 + hstepB, voffB); PG8_STAGE(PG8_SA(1, 0), a3, voffA);
;             PG8_WAIT_V(8); PG8_WAIT_L(0); PG8_BAR; PG8_MMA(1, 0, At, B0); PG8_MMA(1, 1, At, B1); PG8_BAR; PG8_SCHED;
;     ...
;         }
;         if constexpr (ALIGN_EPI) { if (wr == 0) PG8_BAR; }
	v_mfma_f32_16x16x32_bf16 v[142:145], v[66:69], v[162:165], v[142:145]
	v_mfma_f32_16x16x32_bf16 v[138:141], v[78:81], v[162:165], v[138:141]
	v_mfma_f32_16x16x32_bf16 v[134:137], v[146:149], v[162:165], v[134:137]
	v_mfma_f32_16x16x32_bf16 v[130:133], v[154:157], v[162:165], v[130:133]
	v_mfma_f32_16x16x32_bf16 v[126:129], v[66:69], v[170:173], v[126:129]
	v_mfma_f32_16x16x32_bf16 v[122:125], v[78:81], v[170:173], v[122:125]
	v_mfma_f32_16x16x32_bf16 v[118:121], v[146:149], v[170:173], v[118:121]
	v_mfma_f32_16x16x32_bf16 v[114:117], v[154:157], v[170:173], v[114:117]
	v_mfma_f32_16x16x32_bf16 v[110:113], v[66:69], v[178:181], v[110:113]
	v_mfma_f32_16x16x32_bf16 v[106:109], v[78:81], v[178:181], v[106:109]
	v_mfma_f32_16x16x32_bf16 v[102:105], v[146:149], v[178:181], v[102:105]
	v_mfma_f32_16x16x32_bf16 v[98:101], v[154:157], v[178:181], v[98:101]
	v_mfma_f32_16x16x32_bf16 v[94:97], v[66:69], v[216:219], v[94:97]
	v_mfma_f32_16x16x32_bf16 v[90:93], v[78:81], v[216:219], v[90:93]
	v_mfma_f32_16x16x32_bf16 v[82:85], v[146:149], v[216:219], v[82:85]
	v_mfma_f32_16x16x32_bf16 v[74:77], v[154:157], v[216:219], v[74:77]
	v_mfma_f32_16x16x32_bf16 v[142:145], v[70:73], v[166:169], v[142:145]
	v_mfma_f32_16x16x32_bf16 v[138:141], v[86:89], v[166:169], v[138:141]
	v_mfma_f32_16x16x32_bf16 v[134:137], v[150:153], v[166:169], v[134:137]
	v_mfma_f32_16x16x32_bf16 v[130:133], v[158:161], v[166:169], v[130:133]
	v_mfma_f32_16x16x32_bf16 v[126:129], v[70:73], v[174:177], v[126:129]
	v_mfma_f32_16x16x32_bf16 v[122:125], v[86:89], v[174:177], v[122:125]
	v_mfma_f32_16x16x32_bf16 v[118:121], v[150:153], v[174:177], v[118:121]
	v_mfma_f32_16x16x32_bf16 v[114:117], v[158:161], v[174:177], v[114:117]
	v_mfma_f32_16x16x32_bf16 v[110:113], v[70:73], v[182:185], v[110:113]
	v_mfma_f32_16x16x32_bf16 v[106:109], v[86:89], v[182:185], v[106:109]
	v_mfma_f32_16x16x32_bf16 v[102:105], v[150:153], v[182:185], v[102:105]
	v_mfma_f32_16x16x32_bf16 v[98:101], v[158:161], v[182:185], v[98:101]
	v_mfma_f32_16x16x32_bf16 v[94:97], v[70:73], v[220:223], v[94:97]
	v_mfma_f32_16x16x32_bf16 v[90:93], v[86:89], v[220:223], v[90:93]
	v_mfma_f32_16x16x32_bf16 v[82:85], v[150:153], v[220:223], v[82:85]
	v_mfma_f32_16x16x32_bf16 v[74:77], v[158:161], v[220:223], v[74:77]
	s_barrier
	s_add_i32 s9, s9, s25
	s_mov_b32 m0, s9
	ds_read_b128 v[162:165], v236 offset:49152
	ds_read_b128 v[166:169], v236 offset:50176
	ds_read_b128 v[170:173], v236 offset:51200
	ds_read_b128 v[174:177], v236 offset:52224
	ds_read_b128 v[178:181], v236 offset:53248
	ds_read_b128 v[182:185], v236 offset:54272
	ds_read_b128 v[216:219], v236 offset:55296
	ds_read_b128 v[220:223], v236 offset:56320
	s_add_u32 s100, s46, s60
	s_addc_u32 s101, s47, s61
	global_load_lds_dwordx4 v190, s[100:101]
	s_add_i32 m0, s9, 0x2000
	s_add_u32 s10, s46, 0x20080
	s_addc_u32 s11, s47, 0
	s_add_i32 s9, s12, s25
	global_load_lds_dwordx4 v206, s[100:101]
	s_mov_b32 m0, s9
	s_nop 0
	global_load_lds_dwordx4 v190, s[10:11]
	s_add_i32 m0, s9, 0x2000
	s_nop 0
	global_load_lds_dwordx4 v206, s[10:11]
	s_mov_b32 m0, s75
	s_add_u32 s100, s94, s60
	s_addc_u32 s101, s95, s61
	global_load_lds_dwordx4 v210, s[100:101]
	s_mov_b32 m0, s0
	s_nop 0
	global_load_lds_dwordx4 v208, s[100:101]
	s_waitcnt vmcnt(8)
	s_waitcnt lgkmcnt(0)
	s_barrier
	v_mfma_f32_16x16x32_bf16 v[62:65], v[66:69], v[162:165], v[62:65]
	v_mfma_f32_16x16x32_bf16 v[58:61], v[78:81], v[162:165], v[58:61]
	v_mfma_f32_16x16x32_bf16 v[54:57], v[146:149], v[162:165], v[54:57]
	v_mfma_f32_16x16x32_bf16 v[50:53], v[154:157], v[162:165], v[50:53]
	v_mfma_f32_16x16x32_bf16 v[46:49], v[66:69], v[170:173], v[46:49]
	v_mfma_f32_16x16x32_bf16 v[42:45], v[78:81], v[170:173], v[42:45]
	v_mfma_f32_16x16x32_bf16 v[38:41], v[146:149], v[170:173], v[38:41]
	v_mfma_f32_16x16x32_bf16 v[34:37], v[154:157], v[170:173], v[34:37]
	v_mfma_f32_16x16x32_bf16 v[30:33], v[66:69], v[178:181], v[30:33]
	v_mfma_f32_16x16x32_bf16 v[26:29], v[78:81], v[178:181], v[26:29]
	v_mfma_f32_16x16x32_bf16 v[22:25], v[146:149], v[178:181], v[22:25]
	v_mfma_f32_16x16x32_bf16 v[18:21], v[154:157], v[178:181], v[18:21]
	v_mfma_f32_16x16x32_bf16 v[14:17], v[66:69], v[216:219], v[14:17]
	v_mfma_f32_16x16x32_bf16 v[10:13], v[78:81], v[216:219], v[10:13]
	v_mfma_f32_16x16x32_bf16 v[6:9], v[146:149], v[216:219], v[6:9]
	v_mfma_f32_16x16x32_bf16 v[2:5], v[154:157], v[216:219], v[2:5]
	v_mfma_f32_16x16x32_bf16 v[62:65], v[70:73], v[166:169], v[62:65]
	v_mfma_f32_16x16x32_bf16 v[58:61], v[86:89], v[166:169], v[58:61]
	v_mfma_f32_16x16x32_bf16 v[54:57], v[150:153], v[166:169], v[54:57]
	v_mfma_f32_16x16x32_bf16 v[50:53], v[158:161], v[166:169], v[50:53]
	v_mfma_f32_16x16x32_bf16 v[46:49], v[70:73], v[174:177], v[46:49]
	v_mfma_f32_16x16x32_bf16 v[42:45], v[86:89], v[174:177], v[42:45]
	v_mfma_f32_16x16x32_bf16 v[38:41], v[150:153], v[174:177], v[38:41]
	v_mfma_f32_16x16x32_bf16 v[34:37], v[158:161], v[174:177], v[34:37]
	v_mfma_f32_16x16x32_bf16 v[30:33], v[70:73], v[182:185], v[30:33]
	v_mfma_f32_16x16x32_bf16 v[26:29], v[86:89], v[182:185], v[26:29]
	v_mfma_f32_16x16x32_bf16 v[22:25], v[150:153], v[182:185], v[22:25]
	v_mfma_f32_16x16x32_bf16 v[18:21], v[158:161], v[182:185], v[18:21]
	v_mfma_f32_16x16x32_bf16 v[14:17], v[70:73], v[220:223], v[14:17]
	v_mfma_f32_16x16x32_bf16 v[10:13], v[86:89], v[220:223], v[10:13]
	v_mfma_f32_16x16x32_bf16 v[6:9], v[150:153], v[220:223], v[6:9]
	v_mfma_f32_16x16x32_bf16 v[2:5], v[158:161], v[220:223], v[2:5]
	s_barrier
	s_add_i32 s8, s8, 2
	s_add_u32 s38, s38, 0x100
	s_addc_u32 s39, s39, 0
	s_add_u32 s6, s6, 0x100
	s_addc_u32 s7, s7, 0
	s_cmp_gt_u32 s8, 29
	s_cbranch_scc0 .LBB0_927
	s_and_b64 vcc, exec, s[70:71]
	s_cbranch_vccz .LBB0_930
	s_barrier

; #define PG8_STAGE(bufoff, gbase, voff) do { _Pragma("unroll") for (int _i = 0; _i < 2; ++_i) \
;         __builtin_amdgcn_global_load_lds((const unsigned*)((const char*)(gbase) + (voff)[_i]), (PG8_LAS unsigned*)(lds + (bufoff) + ldsw + _i * 8192), 16, 0, 0); } while (0)
; #define PG8_LDA(dst, b, h) do { _Pragma("unroll") for (int m = 0; m < 4; ++m) _Pragma("unroll") for (int k = 0; k < 2; ++k) dst[m][k] = *(const PG8_LAS bf16x8*)(lds + PG8_SA(b, h) + aoff + m * 2048 + k * 1024); } while (0)
; #define PG8_LDB(dst, b, h) do { _Pragma("unroll") for (int n = 0; n < 2; ++n) _Pragma("unroll") for (int k = 0; k < 2; ++k) dst[n][k] = *(const PG8_LAS bf16x8*)(lds + PG8_SB(b, h) + boff + n * 2048 + k * 1024); } while (0)
; #define PG8_WAIT_V(n) asm volatile("s_waitcnt vmcnt(" #n ")" ::: "memory")
; #define PG8_WAIT_L(n) asm volatile("s_waitcnt lgkmcnt(" #n ")" ::: "memory")
; #define PG8_BAR __builtin_amdgcn_s_barrier()
; #define PG8_SCHED __builtin_amdgcn_sched_barrier(0)
; template <class Epi, class Sched, bool ALIGN_EPI = false, bool SP2 = false>
; __device__ __forceinline__ void gemm_phase(PG8_LAS unsigned char* lds, const Gemm g, const Sched& S, const Epi& E) {
;     ...
;         const bool has_next = S.next(ui + 1, nxt);
;         const char* nA = has_next ? (const char*)g.A + (size_t)nxt.pm * tstep : cA; const char* nB = has_next ? (const char*)g.Bt + (size_t)nxt.pn * tstep : cB;
;         for (int t = 0; t < nt; t += 2) {
;             const bool last = (t == nt - 2);
;             const char* a1 = cA + (size_t)(t + 1) * kstep;
;             const char* a2 = last ? nA : cA + (size_t)(t + 2) * kstep; const char* b2 = last ? nB : cB + (size_t)(t + 2) * kstep;
;             const char* a3 = a2 + kstep; const char* b3 = b2 + kstep;
;             if (last && has_next) S.a_ready(nxt);
;             if constexpr (SP2) {
;             PG8_LDB(B0, 0, 0); PG8_LDB(B1, 0, 1); PG8_SCHED; PG8_LDA(At, 0, 0); PG8_STAGE(PG8_SA(1, 1), a1 + hstep, voffA);
;             PG8_WAIT_V(8); PG8_WAIT_L(0); PG8_BAR; PG8_MMA(0, 0, At, B0); PG8_MMA(0, 1, At, B1); PG8_BAR; PG8_SCHED;
;             PG8_LDA(At, 0, 1); PG8_STAGE(PG8_SB(0, 0), b2, voffB); PG8_STAGE(PG8_SB(0, 1), b2 + hstepB, voffB); PG8_STAGE(PG8_SA(0, 0), a2, voffA);
;             PG8_WAIT_V(8); PG8_WAIT_L(0); PG8_BAR; PG8_MMA(1, 0, At, B0); PG8_MMA(1, 1, At, B1); PG8_BAR; PG8_SCHED;
.LBB0_1070:
	s_ashr_i32 s97, s96, 31
	s_lshl_b64 s[4:5], s[96:97], 22
	s_add_u32 s26, s0, s4
	s_addc_u32 s27, s1, s5
	s_and_b64 s[4:5], s[92:93], exec
	s_cselect_b32 s97, s27, s39
	s_cselect_b32 s4, s26, s38
	s_ashr_i32 s85, s84, 31
	s_lshl_b64 s[6:7], s[84:85], 22
	s_add_u32 s94, s56, s6
	s_addc_u32 s95, s57, s7
	s_and_b64 s[6:7], s[92:93], exec
	s_cselect_b32 s5, s95, s47
	s_cselect_b32 s6, s94, s46
	s_add_u32 s38, s38, 0x200080
	s_addc_u32 s39, s39, 0
	s_add_u32 s7, s46, 0x100
	s_addc_u32 s8, s47, 0
	s_mov_b32 s9, -2
	s_waitcnt lgkmcnt(0)
	v_add_u32_e32 v186, 0x10000, v164
	v_add_u32_e32 v187, 0x14000, v164
	v_add_u32_e32 v198, 0x18000, v164
	v_add_u32_e32 v199, 0x1c000, v164
	s_add_u32 s10, s38, 0xffe00080
	s_addc_u32 s11, s39, -1
	s_add_i32 s12, 0, 0x10000
	s_cmpk_eq_i32 s9, 0x7c
	s_cselect_b32 vcc_hi, s97, s11
	s_cselect_b32 vcc_lo, s4, s10
	s_cselect_b32 s47, s5, s8
	s_cselect_b32 s46, s6, s7
	s_add_i32 s13, 0, 0x14000
	ds_read_b128 v[130:133], v186
	ds_read_b128 v[134:137], v186 offset:1024
	ds_read_b128 v[138:141], v186 offset:2048
	ds_read_b128 v[152:155], v186 offset:3072
	ds_read_b128 v[156:159], v187
	ds_read_b128 v[160:163], v187 offset:1024
	ds_read_b128 v[168:171], v187 offset:2048
	ds_read_b128 v[172:175], v187 offset:3072
	s_add_i32 m0, s74, 0xc000
	ds_read_b128 v[176:179], v166
	ds_read_b128 v[180:183], v166 offset:1024
	ds_read_b128 v[206:209], v166 offset:2048
	ds_read_b128 v[210:213], v166 offset:3072
	ds_read_b128 v[214:217], v166 offset:4096
	ds_read_b128 v[218:221], v166 offset:5120
	ds_read_b128 v[236:239], v166 offset:6144
	ds_read_b128 v[240:243], v166 offset:7168
	global_load_lds_dwordx4 v148, s[38:39]
	s_add_i32 m0, s74, 0xe000
	s_nop 0
	global_load_lds_dwordx4 v150, s[38:39]
	s_waitcnt vmcnt(8)
	s_waitcnt lgkmcnt(0)
	s_barrier
	v_mfma_f32_16x16x32_bf16 v[126:129], v[130:133], v[176:179], 0
	v_mfma_f32_16x16x32_bf16 v[122:125], v[138:141], v[176:179], 0
	v_mfma_f32_16x16x32_bf16 v[118:121], v[156:159], v[176:179], 0
	v_mfma_f32_16x16x32_bf16 v[114:117], v[168:171], v[176:179], 0
	v_mfma_f32_16x16x32_bf16 v[110:113], v[130:133], v[206:209], 0
	v_mfma_f32_16x16x32_bf16 v[106:109], v[138:141], v[206:209], 0
	v_mfma_f32_16x16x32_bf16 v[102:105], v[156:159], v[206:209], 0
	v_mfma_f32_16x16x32_bf16 v[98:101], v[168:171], v[206:209], 0
	v_mfma_f32_16x16x32_bf16 v[94:97], v[130:133], v[214:217], 0
	v_mfma_f32_16x16x32_bf16 v[90:93], v[138:141], v[214:217], 0
	v_mfma_f32_16x16x32_bf16 v[86:89], v[156:159], v[214:217], 0
	v_mfma_f32_16x16x32_bf16 v[82:85], v[168:171], v[214:217], 0
	v_mfma_f32_16x16x32_bf16 v[78:81], v[130:133], v[236:239], 0
	v_mfma_f32_16x16x32_bf16 v[74:77], v[138:141], v[236:239], 0
	v_mfma_f32_16x16x32_bf16 v[70:73], v[156:159], v[236:239], 0
	v_mfma_f32_16x16x32_bf16 v[66:69], v[168:171], v[236:239], 0
	v_mfma_f32_16x16x32_bf16 v[126:129], v[134:137], v[180:183], v[126:129]
	v_mfma_f32_16x16x32_bf16 v[122:125], v[152:155], v[180:183], v[122:125]
	v_mfma_f32_16x16x32_bf16 v[118:121], v[160:163], v[180:183], v[118:121]
	v_mfma_f32_16x16x32_bf16 v[114:117], v[172:175], v[180:183], v[114:117]
	v_mfma_f32_16x16x32_bf16 v[110:113], v[134:137], v[210:213], v[110:113]
	v_mfma_f32_16x16x32_bf16 v[106:109], v[152:155], v[210:213], v[106:109]
	v_mfma_f32_16x16x32_bf16 v[102:105], v[160:163], v[210:213], v[102:105]
	v_mfma_f32_16x16x32_bf16 v[98:101], v[172:175], v[210:213], v[98:101]
	v_mfma_f32_16x16x32_bf16 v[94:97], v[134:137], v[218:221], v[94:97]
	v_mfma_f32_16x16x32_bf16 v[90:93], v[152:155], v[218:221], v[90:93]
	v_mfma_f32_16x16x32_bf16 v[86:89], v[160:163], v[218:221], v[86:89]
	v_mfma_f32_16x16x32_bf16 v[82:85], v[172:175], v[218:221], v[82:85]
	v_mfma_f32_16x16x32_bf16 v[78:81], v[134:137], v[240:243], v[78:81]
	v_mfma_f32_16x16x32_bf16 v[74:77], v[152:155], v[240:243], v[74:77]
	v_mfma_f32_16x16x32_bf16 v[70:73], v[160:163], v[240:243], v[70:73]
	v_mfma_f32_16x16x32_bf16 v[66:69], v[172:175], v[240:243], v[66:69]
	s_barrier
	s_add_i32 s10, s12, s67
	s_mov_b32 m0, s10
	ds_read_b128 v[176:179], v166 offset:16384
	ds_read_b128 v[180:183], v166 offset:17408
	ds_read_b128 v[206:209], v166 offset:18432
	ds_read_b128 v[210:213], v166 offset:19456
	ds_read_b128 v[214:217], v166 offset:20480
	ds_read_b128 v[218:221], v166 offset:21504
	ds_read_b128 v[236:239], v166 offset:22528
	ds_read_b128 v[240:243], v166 offset:23552
	global_load_lds_dwordx4 v146, s[46:47]
	s_add_i32 m0, s10, 0x2000
	s_add_u32 s10, s46, 0x80000
	s_addc_u32 s11, s47, 0
	s_add_i32 s12, s13, s67
	global_load_lds_dwordx4 v142, s[46:47]
	s_mov_b32 m0, s12
	s_nop 0
	global_load_lds_dwordx4 v146, s[10:11]
	s_add_i32 m0, s12, 0x2000
	s_nop 0
	global_load_lds_dwordx4 v142, s[10:11]
	s_mov_b32 m0, s74
	s_nop 0
	global_load_lds_dwordx4 v190, vcc
	s_mov_b32 m0, s75
	s_nop 0
	global_load_lds_dwordx4 v144, vcc
	s_waitcnt vmcnt(8)
	s_waitcnt lgkmcnt(0)
	s_barrier
; #define PG8_STAGE(bufoff, gbase, voff) do { _Pragma("unroll") for (int _i = 0; _i < 2; ++_i) \
;         __builtin_amdgcn_global_load_lds((const unsigned*)((const char*)(gbase) + (voff)[_i]), (PG8_LAS unsigned*)(lds + (bufoff) + ldsw + _i * 8192), 16, 0, 0); } while (0)
; #define PG8_LDA(dst, b, h) do { _Pragma("unroll") for (int m = 0; m < 4; ++m) _Pragma("unroll") for (int k = 0; k < 2; ++k) dst[m][k] = *(const PG8_LAS bf16x8*)(lds + PG8_SA(b, h) + aoff + m * 2048 + k * 1024); } while (0)
; #define PG8_LDB(dst, b, h) do { _Pragma("unroll") for (int n = 0; n < 2; ++n) _Pragma("unroll") for (int k = 0; k < 2; ++k) dst[n][k] = *(const PG8_LAS bf16x8*)(lds + PG8_SB(b, h) + boff + n * 2048 + k * 1024); } while (0)
; #define PG8_MMA(ai, bj, At, Bt) do { __builtin_amdgcn_s_setprio(1); _Pragma("unroll") for (int m = 0; m < 4; ++m) _Pragma("unroll") for (int n = 0; n < 2; ++n) _Pragma("unroll") for (int k = 0; k < 2; ++k) \
;         acc[ai][bj][m][n] = __builtin_amdgcn_mfma_f32_16x16x32_bf16(Bt[n][k], At[m][k], acc[ai][bj][m][n], 0, 0, 0); __builtin_amdgcn_s_setprio(0); } while (0)
; #define PG8_WAIT_V(n) asm volatile("s_waitcnt vmcnt(" #n ")" ::: "memory")
; #define PG8_WAIT_L(n) asm volatile("s_waitcnt lgkmcnt(" #n ")" ::: "memory")
; #define PG8_BAR __builtin_amdgcn_s_barrier()
; #define PG8_SCHED __builtin_amdgcn_sched_barrier(0)
; template <class Epi, class Sched, bool ALIGN_EPI = false, bool SP2 = false>
; __device__ __forceinline__ void gemm_phase(PG8_LAS unsigned char* lds, const Gemm g, const Sched& S, const Epi& E) {
;     ...
;             PG8_WAIT_V(8); PG8_WAIT_L(0); PG8_BAR; PG8_MMA(1, 0, At, B0); PG8_MMA(1, 1, At, B1); PG8_BAR; PG8_SCHED;
;             PG8_LDB(B0, 1, 0); PG8_LDB(B1, 1, 1); PG8_SCHED; PG8_LDA(At, 1, 0); PG8_STAGE(PG8_SA(0, 1), a2 + hstep, voffA);
;             PG8_WAIT_V(8); PG8_WAIT_L(0); PG8_BAR; PG8_MMA(0, 0, At, B0); PG8_MMA(0, 1, At, B1); PG8_BAR; PG8_SCHED;
	v_mfma_f32_16x16x32_bf16 v[62:65], v[130:133], v[176:179], 0
	v_mfma_f32_16x16x32_bf16 v[58:61], v[138:141], v[176:179], 0
	v_mfma_f32_16x16x32_bf16 v[54:57], v[156:159], v[176:179], 0
	v_mfma_f32_16x16x32_bf16 v[50:53], v[168:171], v[176:179], 0
	v_mfma_f32_16x16x32_bf16 v[46:49], v[130:133], v[206:209], 0
	v_mfma_f32_16x16x32_bf16 v[42:45], v[138:141], v[206:209], 0
	v_mfma_f32_16x16x32_bf16 v[38:41], v[156:159], v[206:209], 0
	v_mfma_f32_16x16x32_bf16 v[34:37], v[168:171], v[206:209], 0
	v_mfma_f32_16x16x32_bf16 v[30:33], v[130:133], v[214:217], 0
	v_mfma_f32_16x16x32_bf16 v[26:29], v[138:141], v[214:217], 0
	v_mfma_f32_16x16x32_bf16 v[22:25], v[156:159], v[214:217], 0
	v_mfma_f32_16x16x32_bf16 v[18:21], v[168:171], v[214:217], 0
	v_mfma_f32_16x16x32_bf16 v[14:17], v[130:133], v[236:239], 0
	v_mfma_f32_16x16x32_bf16 v[10:13], v[138:141], v[236:239], 0
	v_mfma_f32_16x16x32_bf16 v[6:9], v[156:159], v[236:239], 0
	v_mfma_f32_16x16x32_bf16 v[2:5], v[168:171], v[236:239], 0
	v_mfma_f32_16x16x32_bf16 v[62:65], v[134:137], v[180:183], v[62:65]
	v_mfma_f32_16x16x32_bf16 v[58:61], v[152:155], v[180:183], v[58:61]
	v_mfma_f32_16x16x32_bf16 v[54:57], v[160:163], v[180:183], v[54:57]
	v_mfma_f32_16x16x32_bf16 v[50:53], v[172:175], v[180:183], v[50:53]
	v_mfma_f32_16x16x32_bf16 v[46:49], v[134:137], v[210:213], v[46:49]
	v_mfma_f32_16x16x32_bf16 v[42:45], v[152:155], v[210:213], v[42:45]
	v_mfma_f32_16x16x32_bf16 v[38:41], v[160:163], v[210:213], v[38:41]
	v_mfma_f32_16x16x32_bf16 v[34:37], v[172:175], v[210:213], v[34:37]
	v_mfma_f32_16x16x32_bf16 v[30:33], v[134:137], v[218:221], v[30:33]
	v_mfma_f32_16x16x32_bf16 v[26:29], v[152:155], v[218:221], v[26:29]
	v_mfma_f32_16x16x32_bf16 v[22:25], v[160:163], v[218:221], v[22:25]
	v_mfma_f32_16x16x32_bf16 v[18:21], v[172:175], v[218:221], v[18:21]
	v_mfma_f32_16x16x32_bf16 v[14:17], v[134:137], v[240:243], v[14:17]
	v_mfma_f32_16x16x32_bf16 v[10:13], v[152:155], v[240:243], v[10:13]
	v_mfma_f32_16x16x32_bf16 v[6:9], v[160:163], v[240:243], v[6:9]
	v_mfma_f32_16x16x32_bf16 v[2:5], v[172:175], v[240:243], v[2:5]
	s_barrier
	s_add_i32 s12, 0, 0x18000
	s_add_i32 s13, 0, 0x1c000
	ds_read_b128 v[130:133], v198
	ds_read_b128 v[134:137], v198 offset:1024
	ds_read_b128 v[138:141], v198 offset:2048
	ds_read_b128 v[152:155], v198 offset:3072
	ds_read_b128 v[156:159], v199
	ds_read_b128 v[160:163], v199 offset:1024
	ds_read_b128 v[168:171], v199 offset:2048
	ds_read_b128 v[172:175], v199 offset:3072
	s_add_u32 s10, vcc_lo, 0x200000
	s_addc_u32 s11, vcc_hi, 0
	s_mov_b32 m0, s86
	ds_read_b128 v[176:179], v166 offset:32768
	ds_read_b128 v[180:183], v166 offset:33792
	ds_read_b128 v[206:209], v166 offset:34816
	ds_read_b128 v[210:213], v166 offset:35840
	ds_read_b128 v[214:217], v166 offset:36864
	ds_read_b128 v[218:221], v166 offset:37888
	ds_read_b128 v[236:239], v166 offset:38912
	ds_read_b128 v[240:243], v166 offset:39936
	global_load_lds_dwordx4 v190, s[10:11]
	s_mov_b32 m0, s87
	s_nop 0
	global_load_lds_dwordx4 v144, s[10:11]
	s_waitcnt vmcnt(8)
	s_waitcnt lgkmcnt(0)
	s_barrier
	v_mfma_f32_16x16x32_bf16 v[126:129], v[130:133], v[176:179], v[126:129]
	v_mfma_f32_16x16x32_bf16 v[122:125], v[138:141], v[176:179], v[122:125]
	v_mfma_f32_16x16x32_bf16 v[118:121], v[156:159], v[176:179], v[118:121]
	v_mfma_f32_16x16x32_bf16 v[114:117], v[168:171], v[176:179], v[114:117]
	v_mfma_f32_16x16x32_bf16 v[110:113], v[130:133], v[206:209], v[110:113]
	v_mfma_f32_16x16x32_bf16 v[106:109], v[138:141], v[206:209], v[106:109]
	v_mfma_f32_16x16x32_bf16 v[102:105], v[156:159], v[206:209], v[102:105]
	v_mfma_f32_16x16x32_bf16 v[98:101], v[168:171], v[206:209], v[98:101]
	v_mfma_f32_16x16x32_bf16 v[94:97], v[130:133], v[214:217], v[94:97]
	v_mfma_f32_16x16x32_bf16 v[90:93], v[138:141], v[214:217], v[90:93]
	v_mfma_f32_16x16x32_bf16 v[86:89], v[156:159], v[214:217], v[86:89]
	v_mfma_f32_16x16x32_bf16 v[82:85], v[168:171], v[214:217], v[82:85]
	v_mfma_f32_16x16x32_bf16 v[78:81], v[130:133], v[236:239], v[78:81]
	v_mfma_f32_16x16x32_bf16 v[74:77], v[138:141], v[236:239], v[74:77]
	v_mfma_f32_16x16x32_bf16 v[70:73], v[156:159], v[236:239], v[70:73]
	v_mfma_f32_16x16x32_bf16 v[66:69], v[168:171], v[236:239], v[66:69]
	v_mfma_f32_16x16x32_bf16 v[126:129], v[134:137], v[180:183], v[126:129]
	v_mfma_f32_16x16x32_bf16 v[122:125], v[152:155], v[180:183], v[122:125]
	v_mfma_f32_16x16x32_bf16 v[118:121], v[160:163], v[180:183], v[118:121]
	v_mfma_f32_16x16x32_bf16 v[114:117], v[172:175], v[180:183], v[114:117]
	v_mfma_f32_16x16x32_bf16 v[110:113], v[134:137], v[210:213], v[110:113]
	v_mfma_f32_16x16x32_bf16 v[106:109], v[152:155], v[210:213], v[106:109]
	v_mfma_f32_16x16x32_bf16 v[102:105], v[160:163], v[210:213], v[102:105]
	v_mfma_f32_16x16x32_bf16 v[98:101], v[172:175], v[210:213], v[98:101]
	v_mfma_f32_16x16x32_bf16 v[94:97], v[134:137], v[218:221], v[94:97]
	v_mfma_f32_16x16x32_bf16 v[90:93], v[152:155], v[218:221], v[90:93]
	v_mfma_f32_16x16x32_bf16 v[86:89], v[160:163], v[218:221], v[86:89]
	v_mfma_f32_16x16x32_bf16 v[82:85], v[172:175], v[218:221], v[82:85]
	v_mfma_f32_16x16x32_bf16 v[78:81], v[134:137], v[240:243], v[78:81]
	v_mfma_f32_16x16x32_bf16 v[74:77], v[152:155], v[240:243], v[74:77]
	v_mfma_f32_16x16x32_bf16 v[70:73], v[160:163], v[240:243], v[70:73]
	v_mfma_f32_16x16x32_bf16 v[66:69], v[172:175], v[240:243], v[66:69]
	s_barrier
; #define PG8_STAGE(bufoff, gbase, voff) do { _Pragma("unroll") for (int _i = 0; _i < 2; ++_i) \
;         __builtin_amdgcn_global_load_lds((const unsigned*)((const char*)(gbase) + (voff)[_i]), (PG8_LAS unsigned*)(lds + (bufoff) + ldsw + _i * 8192), 16, 0, 0); } while (0)
; #define PG8_LDA(dst, b, h) do { _Pragma("unroll") for (int m = 0; m < 4; ++m) _Pragma("unroll") for (int k = 0; k < 2; ++k) dst[m][k] = *(const PG8_LAS bf16x8*)(lds + PG8_SA(b, h) + aoff + m * 2048 + k * 1024); } while (0)
; #define PG8_LDB(dst, b, h) do { _Pragma("unroll") for (int n = 0; n < 2; ++n) _Pragma("unroll") for (int k = 0; k < 2; ++k) dst[n][k] = *(const PG8_LAS bf16x8*)(lds + PG8_SB(b, h) + boff + n * 2048 + k * 1024); } while (0)
; #define PG8_MMA(ai, bj, At, Bt) do { __builtin_amdgcn_s_setprio(1); _Pragma("unroll") for (int m = 0; m < 4; ++m) _Pragma("unroll") for (int n = 0; n < 2; ++n) _Pragma("unroll") for (int k = 0; k < 2; ++k) \
;         acc[ai][bj][m][n] = __builtin_amdgcn_mfma_f32_16x16x32_bf16(Bt[n][k], At[m][k], acc[ai][bj][m][n], 0, 0, 0); __builtin_amdgcn_s_setprio(0); } while (0)
; #define PG8_WAIT_V(n) asm volatile("s_waitcnt vmcnt(" #n ")" ::: "memory")
; #define PG8_BAR __builtin_amdgcn_s_barrier()
; template <class Epi, class Sched, bool ALIGN_EPI = false, bool SP2 = false>
; __device__ __forceinline__ void gemm_phase(PG8_LAS unsigned char* lds, const Gemm g, const Sched& S, const Epi& E) {
;     ...
;         for (int t = 0; t < nt; t += 2) {
;             const bool last = (t == nt - 2);
;             const char* a1 = cA + (size_t)(t + 1) * kstep;
;             const char* a2 = last ? nA : cA + (size_t)(t + 2) * kstep; const char* b2 = last ? nB : cB + (size_t)(t + 2) * kstep;
;             const char* a3 = a2 + kstep; const char* b3 = b2 + kstep;
;             if (last && has_next) S.a_ready(nxt);
;             if constexpr (SP2) {
;             PG8_LDB(B0, 0, 0); PG8_LDB(B1, 0, 1); PG8_SCHED; PG8_LDA(At, 0, 0); PG8_STAGE(PG8_SA(1, 1), a1 + hstep, voffA);
;             PG8_WAIT_V(8); PG8_WAIT_L(0); PG8_BAR; PG8_MMA(0, 0, At, B0); PG8_MMA(0, 1, At, B1); PG8_BAR; PG8_SCHED;
;     ...
;             PG8_LDA(At, 1, 1); PG8_STAGE(PG8_SB(1, 0), b3, voffB); PG8_STAGE(PG8_SB(1, 1), b3 + hstepB, voffB); PG8_STAGE(PG8_SA(1, 0), a3, voffA);
;             PG8_WAIT_V(8); PG8_WAIT_L(0); PG8_BAR; PG8_MMA(1, 0, At, B0); PG8_MMA(1, 1, At, B1); PG8_BAR; PG8_SCHED;
	s_add_i32 s10, s12, s67
	s_mov_b32 m0, s10
	ds_read_b128 v[176:179], v166 offset:49152
	ds_read_b128 v[180:183], v166 offset:50176
	ds_read_b128 v[206:209], v166 offset:51200
	ds_read_b128 v[210:213], v166 offset:52224
	ds_read_b128 v[214:217], v166 offset:53248
	ds_read_b128 v[218:221], v166 offset:54272
	ds_read_b128 v[236:239], v166 offset:55296
	ds_read_b128 v[240:243], v166 offset:56320
	s_add_u32 s100, s46, s60
	s_addc_u32 s101, s47, s61
	global_load_lds_dwordx4 v146, s[100:101]
	s_add_i32 m0, s10, 0x2000
	s_add_u32 s10, s46, 0x80080
	s_addc_u32 s11, s47, 0
	s_add_i32 s12, s13, s67
	global_load_lds_dwordx4 v142, s[100:101]
	s_mov_b32 m0, s12
	s_nop 0
	global_load_lds_dwordx4 v146, s[10:11]
	s_add_i32 m0, s12, 0x2000
	s_nop 0
	global_load_lds_dwordx4 v142, s[10:11]
	s_mov_b32 m0, s82
	s_add_u32 s100, vcc_lo, s60
	s_addc_u32 s101, vcc_hi, s61
	global_load_lds_dwordx4 v190, s[100:101]
	s_mov_b32 m0, s42
	s_nop 0
	global_load_lds_dwordx4 v144, s[100:101]
	s_waitcnt vmcnt(8)
	s_waitcnt lgkmcnt(0)
	s_barrier
	v_mfma_f32_16x16x32_bf16 v[62:65], v[130:133], v[176:179], v[62:65]
	v_mfma_f32_16x16x32_bf16 v[58:61], v[138:141], v[176:179], v[58:61]
	v_mfma_f32_16x16x32_bf16 v[54:57], v[156:159], v[176:179], v[54:57]
	v_mfma_f32_16x16x32_bf16 v[50:53], v[168:171], v[176:179], v[50:53]
	v_mfma_f32_16x16x32_bf16 v[46:49], v[130:133], v[206:209], v[46:49]
	v_mfma_f32_16x16x32_bf16 v[42:45], v[138:141], v[206:209], v[42:45]
	v_mfma_f32_16x16x32_bf16 v[38:41], v[156:159], v[206:209], v[38:41]
	v_mfma_f32_16x16x32_bf16 v[34:37], v[168:171], v[206:209], v[34:37]
	v_mfma_f32_16x16x32_bf16 v[30:33], v[130:133], v[214:217], v[30:33]
	v_mfma_f32_16x16x32_bf16 v[26:29], v[138:141], v[214:217], v[26:29]
	v_mfma_f32_16x16x32_bf16 v[22:25], v[156:159], v[214:217], v[22:25]
	v_mfma_f32_16x16x32_bf16 v[18:21], v[168:171], v[214:217], v[18:21]
	v_mfma_f32_16x16x32_bf16 v[14:17], v[130:133], v[236:239], v[14:17]
	v_mfma_f32_16x16x32_bf16 v[10:13], v[138:141], v[236:239], v[10:13]
	v_mfma_f32_16x16x32_bf16 v[6:9], v[156:159], v[236:239], v[6:9]
	v_mfma_f32_16x16x32_bf16 v[2:5], v[168:171], v[236:239], v[2:5]
	v_mfma_f32_16x16x32_bf16 v[62:65], v[134:137], v[180:183], v[62:65]
	v_mfma_f32_16x16x32_bf16 v[58:61], v[152:155], v[180:183], v[58:61]
	v_mfma_f32_16x16x32_bf16 v[54:57], v[160:163], v[180:183], v[54:57]
	v_mfma_f32_16x16x32_bf16 v[50:53], v[172:175], v[180:183], v[50:53]
	v_mfma_f32_16x16x32_bf16 v[46:49], v[134:137], v[210:213], v[46:49]
	v_mfma_f32_16x16x32_bf16 v[42:45], v[152:155], v[210:213], v[42:45]
	v_mfma_f32_16x16x32_bf16 v[38:41], v[160:163], v[210:213], v[38:41]
	v_mfma_f32_16x16x32_bf16 v[34:37], v[172:175], v[210:213], v[34:37]
	v_mfma_f32_16x16x32_bf16 v[30:33], v[134:137], v[218:221], v[30:33]
	v_mfma_f32_16x16x32_bf16 v[26:29], v[152:155], v[218:221], v[26:29]
	v_mfma_f32_16x16x32_bf16 v[22:25], v[160:163], v[218:221], v[22:25]
	v_mfma_f32_16x16x32_bf16 v[18:21], v[172:175], v[218:221], v[18:21]
	v_mfma_f32_16x16x32_bf16 v[14:17], v[134:137], v[240:243], v[14:17]
	v_mfma_f32_16x16x32_bf16 v[10:13], v[152:155], v[240:243], v[10:13]
	v_mfma_f32_16x16x32_bf16 v[6:9], v[160:163], v[240:243], v[6:9]
	v_mfma_f32_16x16x32_bf16 v[2:5], v[172:175], v[240:243], v[2:5]
	s_barrier
	s_add_i32 s9, s9, 2
	s_add_u32 s38, s38, 0x100
	s_addc_u32 s39, s39, 0
	s_add_u32 s7, s7, 0x100
	s_addc_u32 s8, s8, 0
	s_cmpk_gt_u32 s9, 0x7d
.LBB0_1071:
	s_add_u32 s10, s38, 0xffe00080
	s_addc_u32 s11, s39, -1
	s_add_i32 s12, 0, 0x10000
	s_cmpk_eq_i32 s9, 0x7c
	s_cselect_b32 vcc_hi, s97, s11
	s_cselect_b32 vcc_lo, s4, s10
	s_cselect_b32 s47, s5, s8
	s_cselect_b32 s46, s6, s7
	s_add_i32 s13, 0, 0x14000
	ds_read_b128 v[130:133], v186
	ds_read_b128 v[134:137], v186 offset:1024
	ds_read_b128 v[138:141], v186 offset:2048
	ds_read_b128 v[152:155], v186 offset:3072
	ds_read_b128 v[156:159], v187
	ds_read_b128 v[160:163], v187 offset:1024
	ds_read_b128 v[168:171], v187 offset:2048
	ds_read_b128 v[172:175], v187 offset:3072
	s_add_i32 m0, s74, 0xc000
	ds_read_b128 v[176:179], v166
	ds_read_b128 v[180:183], v166 offset:1024
	ds_read_b128 v[206:209], v166 offset:2048
	ds_read_b128 v[210:213], v166 offset:3072
	ds_read_b128 v[214:217], v166 offset:4096
	ds_read_b128 v[218:221], v166 offset:5120
	ds_read_b128 v[236:239], v166 offset:6144
	ds_read_b128 v[240:243], v166 offset:7168
	global_load_lds_dwordx4 v148, s[38:39]
	s_add_i32 m0, s74, 0xe000
	s_nop 0
	global_load_lds_dwordx4 v150, s[38:39]
	s_waitcnt vmcnt(8)
	s_waitcnt lgkmcnt(0)
	s_barrier
	v_mfma_f32_16x16x32_bf16 v[126:129], v[130:133], v[176:179], v[126:129]
	v_mfma_f32_16x16x32_bf16 v[122:125], v[138:141], v[176:179], v[122:125]
	v_mfma_f32_16x16x32_bf16 v[118:121], v[156:159], v[176:179], v[118:121]
	v_mfma_f32_16x16x32_bf16 v[114:117], v[168:171], v[176:179], v[114:117]
	v_mfma_f32_16x16x32_bf16 v[110:113], v[130:133], v[206:209], v[110:113]
	v_mfma_f32_16x16x32_bf16 v[106:109], v[138:141], v[206:209], v[106:109]
	v_mfma_f32_16x16x32_bf16 v[102:105], v[156:159], v[206:209], v[102:105]
	v_mfma_f32_16x16x32_bf16 v[98:101], v[168:171], v[206:209], v[98:101]
	v_mfma_f32_16x16x32_bf16 v[94:97], v[130:133], v[214:217], v[94:97]
	v_mfma_f32_16x16x32_bf16 v[90:93], v[138:141], v[214:217], v[90:93]
	v_mfma_f32_16x16x32_bf16 v[86:89], v[156:159], v[214:217], v[86:89]
	v_mfma_f32_16x16x32_bf16 v[82:85], v[168:171], v[214:217], v[82:85]
	v_mfma_f32_16x16x32_bf16 v[78:81], v[130:133], v[236:239], v[78:81]
	v_mfma_f32_16x16x32_bf16 v[74:77], v[138:141], v[236:239], v[74:77]
	v_mfma_f32_16x16x32_bf16 v[70:73], v[156:159], v[236:239], v[70:73]
	v_mfma_f32_16x16x32_bf16 v[66:69], v[168:171], v[236:239], v[66:69]
	v_mfma_f32_16x16x32_bf16 v[126:129], v[134:137], v[180:183], v[126:129]
	v_mfma_f32_16x16x32_bf16 v[122:125], v[152:155], v[180:183], v[122:125]
	v_mfma_f32_16x16x32_bf16 v[118:121], v[160:163], v[180:183], v[118:121]
	v_mfma_f32_16x16x32_bf16 v[114:117], v[172:175], v[180:183], v[114:117]
	v_mfma_f32_16x16x32_bf16 v[110:113], v[134:137], v[210:213], v[110:113]
	v_mfma_f32_16x16x32_bf16 v[106:109], v[152:155], v[210:213], v[106:109]
	v_mfma_f32_16x16x32_bf16 v[102:105], v[160:163], v[210:213], v[102:105]
	v_mfma_f32_16x16x32_bf16 v[98:101], v[172:175], v[210:213], v[98:101]
	v_mfma_f32_16x16x32_bf16 v[94:97], v[134:137], v[218:221], v[94:97]
	v_mfma_f32_16x16x32_bf16 v[90:93], v[152:155], v[218:221], v[90:93]
	v_mfma_f32_16x16x32_bf16 v[86:89], v[160:163], v[218:221], v[86:89]
	v_mfma_f32_16x16x32_bf16 v[82:85], v[172:175], v[218:221], v[82:85]
	v_mfma_f32_16x16x32_bf16 v[78:81], v[134:137], v[240:243], v[78:81]
	v_mfma_f32_16x16x32_bf16 v[74:77], v[152:155], v[240:243], v[74:77]
	v_mfma_f32_16x16x32_bf16 v[70:73], v[160:163], v[240:243], v[70:73]
	v_mfma_f32_16x16x32_bf16 v[66:69], v[172:175], v[240:243], v[66:69]
	s_barrier
; #define PG8_STAGE(bufoff, gbase, voff) do { _Pragma("unroll") for (int _i = 0; _i < 2; ++_i) \
;         __builtin_amdgcn_global_load_lds((const unsigned*)((const char*)(gbase) + (voff)[_i]), (PG8_LAS unsigned*)(lds + (bufoff) + ldsw + _i * 8192), 16, 0, 0); } while (0)
; #define PG8_LDA(dst, b, h) do { _Pragma("unroll") for (int m = 0; m < 4; ++m) _Pragma("unroll") for (int k = 0; k < 2; ++k) dst[m][k] = *(const PG8_LAS bf16x8*)(lds + PG8_SA(b, h) + aoff + m * 2048 + k * 1024); } while (0)
; #define PG8_LDB(dst, b, h) do { _Pragma("unroll") for (int n = 0; n < 2; ++n) _Pragma("unroll") for (int k = 0; k < 2; ++k) dst[n][k] = *(const PG8_LAS bf16x8*)(lds + PG8_SB(b, h) + boff + n * 2048 + k * 1024); } while (0)
; #define PG8_MMA(ai, bj, At, Bt) do { __builtin_amdgcn_s_setprio(1); _Pragma("unroll") for (int m = 0; m < 4; ++m) _Pragma("unroll") for (int n = 0; n < 2; ++n) _Pragma("unroll") for (int k = 0; k < 2; ++k) \
;         acc[ai][bj][m][n] = __builtin_amdgcn_mfma_f32_16x16x32_bf16(Bt[n][k], At[m][k], acc[ai][bj][m][n], 0, 0, 0); __builtin_amdgcn_s_setprio(0); } while (0)
; #define PG8_WAIT_V(n) asm volatile("s_waitcnt vmcnt(" #n ")" ::: "memory")
; #define PG8_WAIT_L(n) asm volatile("s_waitcnt lgkmcnt(" #n ")" ::: "memory")
; #define PG8_BAR __builtin_amdgcn_s_barrier()
; #define PG8_SCHED __builtin_amdgcn_sched_barrier(0)
; template <class Epi, class Sched, bool ALIGN_EPI = false, bool SP2 = false>
; __device__ __forceinline__ void gemm_phase(PG8_LAS unsigned char* lds, const Gemm g, const Sched& S, const Epi& E) {
;     ...
;             PG8_LDA(At, 0, 1); PG8_STAGE(PG8_SB(0, 0), b2, voffB); PG8_STAGE(PG8_SB(0, 1), b2 + hstepB, voffB); PG8_STAGE(PG8_SA(0, 0), a2, voffA);
;             PG8_WAIT_V(8); PG8_WAIT_L(0); PG8_BAR; PG8_MMA(1, 0, At, B0); PG8_MMA(1, 1, At, B1); PG8_BAR; PG8_SCHED;
;             PG8_LDB(B0, 1, 0); PG8_LDB(B1, 1, 1); PG8_SCHED; PG8_LDA(At, 1, 0); PG8_STAGE(PG8_SA(0, 1), a2 + hstep, voffA);
	s_add_i32 s10, s12, s67
	s_mov_b32 m0, s10
	ds_read_b128 v[176:179], v166 offset:16384
	ds_read_b128 v[180:183], v166 offset:17408
	ds_read_b128 v[206:209], v166 offset:18432
	ds_read_b128 v[210:213], v166 offset:19456
	ds_read_b128 v[214:217], v166 offset:20480
	ds_read_b128 v[218:221], v166 offset:21504
	ds_read_b128 v[236:239], v166 offset:22528
	ds_read_b128 v[240:243], v166 offset:23552
	global_load_lds_dwordx4 v146, s[46:47]
	s_add_i32 m0, s10, 0x2000
	s_add_u32 s10, s46, 0x80000
	s_addc_u32 s11, s47, 0
	s_add_i32 s12, s13, s67
	global_load_lds_dwordx4 v142, s[46:47]
	s_mov_b32 m0, s12
	s_nop 0
	global_load_lds_dwordx4 v146, s[10:11]
	s_add_i32 m0, s12, 0x2000
	s_nop 0
	global_load_lds_dwordx4 v142, s[10:11]
	s_mov_b32 m0, s74
	s_nop 0
	global_load_lds_dwordx4 v190, vcc
	s_mov_b32 m0, s75
	s_nop 0
	global_load_lds_dwordx4 v144, vcc
	s_waitcnt vmcnt(8)
	s_waitcnt lgkmcnt(0)
	s_barrier
	v_mfma_f32_16x16x32_bf16 v[62:65], v[130:133], v[176:179], v[62:65]
	v_mfma_f32_16x16x32_bf16 v[58:61], v[138:141], v[176:179], v[58:61]
	v_mfma_f32_16x16x32_bf16 v[54:57], v[156:159], v[176:179], v[54:57]
	v_mfma_f32_16x16x32_bf16 v[50:53], v[168:171], v[176:179], v[50:53]
	v_mfma_f32_16x16x32_bf16 v[46:49], v[130:133], v[206:209], v[46:49]
	v_mfma_f32_16x16x32_bf16 v[42:45], v[138:141], v[206:209], v[42:45]
	v_mfma_f32_16x16x32_bf16 v[38:41], v[156:159], v[206:209], v[38:41]
	v_mfma_f32_16x16x32_bf16 v[34:37], v[168:171], v[206:209], v[34:37]
	v_mfma_f32_16x16x32_bf16 v[30:33], v[130:133], v[214:217], v[30:33]
	v_mfma_f32_16x16x32_bf16 v[26:29], v[138:141], v[214:217], v[26:29]
	v_mfma_f32_16x16x32_bf16 v[22:25], v[156:159], v[214:217], v[22:25]
	v_mfma_f32_16x16x32_bf16 v[18:21], v[168:171], v[214:217], v[18:21]
	v_mfma_f32_16x16x32_bf16 v[14:17], v[130:133], v[236:239], v[14:17]
	v_mfma_f32_16x16x32_bf16 v[10:13], v[138:141], v[236:239], v[10:13]
	v_mfma_f32_16x16x32_bf16 v[6:9], v[156:159], v[236:239], v[6:9]
	v_mfma_f32_16x16x32_bf16 v[2:5], v[168:171], v[236:239], v[2:5]
	v_mfma_f32_16x16x32_bf16 v[62:65], v[134:137], v[180:183], v[62:65]
	v_mfma_f32_16x16x32_bf16 v[58:61], v[152:155], v[180:183], v[58:61]
	v_mfma_f32_16x16x32_bf16 v[54:57], v[160:163], v[180:183], v[54:57]
	v_mfma_f32_16x16x32_bf16 v[50:53], v[172:175], v[180:183], v[50:53]
	v_mfma_f32_16x16x32_bf16 v[46:49], v[134:137], v[210:213], v[46:49]
	v_mfma_f32_16x16x32_bf16 v[42:45], v[152:155], v[210:213], v[42:45]
	v_mfma_f32_16x16x32_bf16 v[38:41], v[160:163], v[210:213], v[38:41]
	v_mfma_f32_16x16x32_bf16 v[34:37], v[172:175], v[210:213], v[34:37]
	v_mfma_f32_16x16x32_bf16 v[30:33], v[134:137], v[218:221], v[30:33]
	v_mfma_f32_16x16x32_bf16 v[26:29], v[152:155], v[218:221], v[26:29]
	v_mfma_f32_16x16x32_bf16 v[22:25], v[160:163], v[218:221], v[22:25]
	v_mfma_f32_16x16x32_bf16 v[18:21], v[172:175], v[218:221], v[18:21]
	v_mfma_f32_16x16x32_bf16 v[14:17], v[134:137], v[240:243], v[14:17]
	v_mfma_f32_16x16x32_bf16 v[10:13], v[152:155], v[240:243], v[10:13]
	v_mfma_f32_16x16x32_bf16 v[6:9], v[160:163], v[240:243], v[6:9]
	v_mfma_f32_16x16x32_bf16 v[2:5], v[172:175], v[240:243], v[2:5]
	s_barrier
	s_add_i32 s12, 0, 0x18000
	s_add_i32 s13, 0, 0x1c000
	ds_read_b128 v[130:133], v198
	ds_read_b128 v[134:137], v198 offset:1024
	ds_read_b128 v[138:141], v198 offset:2048
	ds_read_b128 v[152:155], v198 offset:3072
	ds_read_b128 v[156:159], v199
	ds_read_b128 v[160:163], v199 offset:1024
	ds_read_b128 v[168:171], v199 offset:2048
	ds_read_b128 v[172:175], v199 offset:3072
	s_add_u32 s10, vcc_lo, 0x200000
	s_addc_u32 s11, vcc_hi, 0
	s_mov_b32 m0, s86
	ds_read_b128 v[176:179], v166 offset:32768
	ds_read_b128 v[180:183], v166 offset:33792
	ds_read_b128 v[206:209], v166 offset:34816
	ds_read_b128 v[210:213], v166 offset:35840
	ds_read_b128 v[214:217], v166 offset:36864
	ds_read_b128 v[218:221], v166 offset:37888
	ds_read_b128 v[236:239], v166 offset:38912
	ds_read_b128 v[240:243], v166 offset:39936
	global_load_lds_dwordx4 v190, s[10:11]
	s_mov_b32 m0, s87
	s_nop 0
	global_load_lds_dwordx4 v144, s[10:11]
	s_waitcnt vmcnt(8)
	s_waitcnt lgkmcnt(0)
	s_barrier
; #define PG8_STAGE(bufoff, gbase, voff) do { _Pragma("unroll") for (int _i = 0; _i < 2; ++_i) \
;         __builtin_amdgcn_global_load_lds((const unsigned*)((const char*)(gbase) + (voff)[_i]), (PG8_LAS unsigned*)(lds + (bufoff) + ldsw + _i * 8192), 16, 0, 0); } while (0)
; #define PG8_LDA(dst, b, h) do { _Pragma("unroll") for (int m = 0; m < 4; ++m) _Pragma("unroll") for (int k = 0; k < 2; ++k) dst[m][k] = *(const PG8_LAS bf16x8*)(lds + PG8_SA(b, h) + aoff + m * 2048 + k * 1024); } while (0)
; #define PG8_MMA(ai, bj, At, Bt) do { __builtin_amdgcn_s_setprio(1); _Pragma("unroll") for (int m = 0; m < 4; ++m) _Pragma("unroll") for (int n = 0; n < 2; ++n) _Pragma("unroll") for (int k = 0; k < 2; ++k) \
;         acc[ai][bj][m][n] = __builtin_amdgcn_mfma_f32_16x16x32_bf16(Bt[n][k], At[m][k], acc[ai][bj][m][n], 0, 0, 0); __builtin_amdgcn_s_setprio(0); } while (0)
; #define PG8_WAIT_V(n) asm volatile("s_waitcnt vmcnt(" #n ")" ::: "memory")
; #define PG8_WAIT_L(n) asm volatile("s_waitcnt lgkmcnt(" #n ")" ::: "memory")
; #define PG8_BAR __builtin_amdgcn_s_barrier()
; #define PG8_SCHED __builtin_amdgcn_sched_barrier(0)
; template <class Epi, class Sched, bool ALIGN_EPI = false, bool SP2 = false>
; __device__ __forceinline__ void gemm_phase(PG8_LAS unsigned char* lds, const Gemm g, const Sched& S, const Epi& E) {
;     ...
;             PG8_WAIT_V(8); PG8_WAIT_L(0); PG8_BAR; PG8_MMA(0, 0, At, B0); PG8_MMA(0, 1, At, B1); PG8_BAR; PG8_SCHED;
;             PG8_LDA(At, 1, 1); PG8_STAGE(PG8_SB(1, 0), b3, voffB); PG8_STAGE(PG8_SB(1, 1), b3 + hstepB, voffB); PG8_STAGE(PG8_SA(1, 0), a3, voffA);
;             PG8_WAIT_V(8); PG8_WAIT_L(0); PG8_BAR; PG8_MMA(1, 0, At, B0); PG8_MMA(1, 1, At, B1); PG8_BAR; PG8_SCHED;
;     ...
;         }
;         if constexpr (ALIGN_EPI) { if (wr == 0) PG8_BAR; }
	v_mfma_f32_16x16x32_bf16 v[126:129], v[130:133], v[176:179], v[126:129]
	v_mfma_f32_16x16x32_bf16 v[122:125], v[138:141], v[176:179], v[122:125]
	v_mfma_f32_16x16x32_bf16 v[118:121], v[156:159], v[176:179], v[118:121]
	v_mfma_f32_16x16x32_bf16 v[114:117], v[168:171], v[176:179], v[114:117]
	v_mfma_f32_16x16x32_bf16 v[110:113], v[130:133], v[206:209], v[110:113]
	v_mfma_f32_16x16x32_bf16 v[106:109], v[138:141], v[206:209], v[106:109]
	v_mfma_f32_16x16x32_bf16 v[102:105], v[156:159], v[206:209], v[102:105]
	v_mfma_f32_16x16x32_bf16 v[98:101], v[168:171], v[206:209], v[98:101]
	v_mfma_f32_16x16x32_bf16 v[94:97], v[130:133], v[214:217], v[94:97]
	v_mfma_f32_16x16x32_bf16 v[90:93], v[138:141], v[214:217], v[90:93]
	v_mfma_f32_16x16x32_bf16 v[86:89], v[156:159], v[214:217], v[86:89]
	v_mfma_f32_16x16x32_bf16 v[82:85], v[168:171], v[214:217], v[82:85]
	v_mfma_f32_16x16x32_bf16 v[78:81], v[130:133], v[236:239], v[78:81]
	v_mfma_f32_16x16x32_bf16 v[74:77], v[138:141], v[236:239], v[74:77]
	v_mfma_f32_16x16x32_bf16 v[70:73], v[156:159], v[236:239], v[70:73]
	v_mfma_f32_16x16x32_bf16 v[66:69], v[168:171], v[236:239], v[66:69]
	v_mfma_f32_16x16x32_bf16 v[126:129], v[134:137], v[180:183], v[126:129]
	v_mfma_f32_16x16x32_bf16 v[122:125], v[152:155], v[180:183], v[122:125]
	v_mfma_f32_16x16x32_bf16 v[118:121], v[160:163], v[180:183], v[118:121]
	v_mfma_f32_16x16x32_bf16 v[114:117], v[172:175], v[180:183], v[114:117]
	v_mfma_f32_16x16x32_bf16 v[110:113], v[134:137], v[210:213], v[110:113]
	v_mfma_f32_16x16x32_bf16 v[106:109], v[152:155], v[210:213], v[106:109]
	v_mfma_f32_16x16x32_bf16 v[102:105], v[160:163], v[210:213], v[102:105]
	v_mfma_f32_16x16x32_bf16 v[98:101], v[172:175], v[210:213], v[98:101]
	v_mfma_f32_16x16x32_bf16 v[94:97], v[134:137], v[218:221], v[94:97]
	v_mfma_f32_16x16x32_bf16 v[90:93], v[152:155], v[218:221], v[90:93]
	v_mfma_f32_16x16x32_bf16 v[86:89], v[160:163], v[218:221], v[86:89]
	v_mfma_f32_16x16x32_bf16 v[82:85], v[172:175], v[218:221], v[82:85]
	v_mfma_f32_16x16x32_bf16 v[78:81], v[134:137], v[240:243], v[78:81]
	v_mfma_f32_16x16x32_bf16 v[74:77], v[152:155], v[240:243], v[74:77]
	v_mfma_f32_16x16x32_bf16 v[70:73], v[160:163], v[240:243], v[70:73]
	v_mfma_f32_16x16x32_bf16 v[66:69], v[172:175], v[240:243], v[66:69]
	s_barrier
	s_add_i32 s10, s12, s67
	s_mov_b32 m0, s10
	ds_read_b128 v[176:179], v166 offset:49152
	ds_read_b128 v[180:183], v166 offset:50176
	ds_read_b128 v[206:209], v166 offset:51200
	ds_read_b128 v[210:213], v166 offset:52224
	ds_read_b128 v[214:217], v166 offset:53248
	ds_read_b128 v[218:221], v166 offset:54272
	ds_read_b128 v[236:239], v166 offset:55296
	ds_read_b128 v[240:243], v166 offset:56320
	s_add_u32 s100, s46, s60
	s_addc_u32 s101, s47, s61
	global_load_lds_dwordx4 v146, s[100:101]
	s_add_i32 m0, s10, 0x2000
	s_add_u32 s10, s46, 0x80080
	s_addc_u32 s11, s47, 0
	s_add_i32 s12, s13, s67
	global_load_lds_dwordx4 v142, s[100:101]
	s_mov_b32 m0, s12
	s_nop 0
	global_load_lds_dwordx4 v146, s[10:11]
	s_add_i32 m0, s12, 0x2000
	s_nop 0
	global_load_lds_dwordx4 v142, s[10:11]
	s_mov_b32 m0, s82
	s_add_u32 s100, vcc_lo, s60
	s_addc_u32 s101, vcc_hi, s61
	global_load_lds_dwordx4 v190, s[100:101]
	s_mov_b32 m0, s42
	s_nop 0
	global_load_lds_dwordx4 v144, s[100:101]
	s_waitcnt vmcnt(8)
	s_waitcnt lgkmcnt(0)
	s_barrier
	v_mfma_f32_16x16x32_bf16 v[62:65], v[130:133], v[176:179], v[62:65]
	v_mfma_f32_16x16x32_bf16 v[58:61], v[138:141], v[176:179], v[58:61]
	v_mfma_f32_16x16x32_bf16 v[54:57], v[156:159], v[176:179], v[54:57]
	v_mfma_f32_16x16x32_bf16 v[50:53], v[168:171], v[176:179], v[50:53]
	v_mfma_f32_16x16x32_bf16 v[46:49], v[130:133], v[206:209], v[46:49]
	v_mfma_f32_16x16x32_bf16 v[42:45], v[138:141], v[206:209], v[42:45]
	v_mfma_f32_16x16x32_bf16 v[38:41], v[156:159], v[206:209], v[38:41]
	v_mfma_f32_16x16x32_bf16 v[34:37], v[168:171], v[206:209], v[34:37]
	v_mfma_f32_16x16x32_bf16 v[30:33], v[130:133], v[214:217], v[30:33]
	v_mfma_f32_16x16x32_bf16 v[26:29], v[138:141], v[214:217], v[26:29]
	v_mfma_f32_16x16x32_bf16 v[22:25], v[156:159], v[214:217], v[22:25]
	v_mfma_f32_16x16x32_bf16 v[18:21], v[168:171], v[214:217], v[18:21]
	v_mfma_f32_16x16x32_bf16 v[14:17], v[130:133], v[236:239], v[14:17]
	v_mfma_f32_16x16x32_bf16 v[10:13], v[138:141], v[236:239], v[10:13]
	v_mfma_f32_16x16x32_bf16 v[6:9], v[156:159], v[236:239], v[6:9]
	v_mfma_f32_16x16x32_bf16 v[2:5], v[168:171], v[236:239], v[2:5]
	v_mfma_f32_16x16x32_bf16 v[62:65], v[134:137], v[180:183], v[62:65]
	v_mfma_f32_16x16x32_bf16 v[58:61], v[152:155], v[180:183], v[58:61]
	v_mfma_f32_16x16x32_bf16 v[54:57], v[160:163], v[180:183], v[54:57]
	v_mfma_f32_16x16x32_bf16 v[50:53], v[172:175], v[180:183], v[50:53]
	v_mfma_f32_16x16x32_bf16 v[46:49], v[134:137], v[210:213], v[46:49]
	v_mfma_f32_16x16x32_bf16 v[42:45], v[152:155], v[210:213], v[42:45]
	v_mfma_f32_16x16x32_bf16 v[38:41], v[160:163], v[210:213], v[38:41]
	v_mfma_f32_16x16x32_bf16 v[34:37], v[172:175], v[210:213], v[34:37]
	v_mfma_f32_16x16x32_bf16 v[30:33], v[134:137], v[218:221], v[30:33]
	v_mfma_f32_16x16x32_bf16 v[26:29], v[152:155], v[218:221], v[26:29]
	v_mfma_f32_16x16x32_bf16 v[22:25], v[160:163], v[218:221], v[22:25]
	v_mfma_f32_16x16x32_bf16 v[18:21], v[172:175], v[218:221], v[18:21]
	v_mfma_f32_16x16x32_bf16 v[14:17], v[134:137], v[240:243], v[14:17]
	v_mfma_f32_16x16x32_bf16 v[10:13], v[152:155], v[240:243], v[10:13]
	v_mfma_f32_16x16x32_bf16 v[6:9], v[160:163], v[240:243], v[6:9]
	v_mfma_f32_16x16x32_bf16 v[2:5], v[172:175], v[240:243], v[2:5]
	s_barrier
	s_add_i32 s9, s9, 2
	s_add_u32 s38, s38, 0x100
	s_addc_u32 s39, s39, 0
	s_add_u32 s7, s7, 0x100
	s_addc_u32 s8, s8, 0
	s_cmpk_gt_u32 s9, 0x7d
	s_cbranch_scc0 .LBB0_1071
	s_and_b64 vcc, exec, s[72:73]
	s_cbranch_vccz .LBB0_1074
	s_barrier

; #define PG8_STAGE(bufoff, gbase, voff) do { _Pragma("unroll") for (int _i = 0; _i < 2; ++_i) \
;         __builtin_amdgcn_global_load_lds((const unsigned*)((const char*)(gbase) + (voff)[_i]), (PG8_LAS unsigned*)(lds + (bufoff) + ldsw + _i * 8192), 16, 0, 0); } while (0)
; #define PG8_LDA(dst, b, h) do { _Pragma("unroll") for (int m = 0; m < 4; ++m) _Pragma("unroll") for (int k = 0; k < 2; ++k) dst[m][k] = *(const PG8_LAS bf16x8*)(lds + PG8_SA(b, h) + aoff + m * 2048 + k * 1024); } while (0)
; #define PG8_LDB(dst, b, h) do { _Pragma("unroll") for (int n = 0; n < 2; ++n) _Pragma("unroll") for (int k = 0; k < 2; ++k) dst[n][k] = *(const PG8_LAS bf16x8*)(lds + PG8_SB(b, h) + boff + n * 2048 + k * 1024); } while (0)
; #define PG8_WAIT_V(n) asm volatile("s_waitcnt vmcnt(" #n ")" ::: "memory")
; #define PG8_WAIT_L(n) asm volatile("s_waitcnt lgkmcnt(" #n ")" ::: "memory")
; #define PG8_BAR __builtin_amdgcn_s_barrier()
; #define PG8_SCHED __builtin_amdgcn_sched_barrier(0)
; template <class Epi, class Sched, bool ALIGN_EPI = false, bool SP2 = false>
; __device__ __forceinline__ void gemm_phase(PG8_LAS unsigned char* lds, const Gemm g, const Sched& S, const Epi& E) {
;     ...
;         const bool has_next = S.next(ui + 1, nxt);
;         const char* nA = has_next ? (const char*)g.A + (size_t)nxt.pm * tstep : cA; const char* nB = has_next ? (const char*)g.Bt + (size_t)nxt.pn * tstep : cB;
;         for (int t = 0; t < nt; t += 2) {
;             const bool last = (t == nt - 2);
;             const char* a1 = cA + (size_t)(t + 1) * kstep;
;             const char* a2 = last ? nA : cA + (size_t)(t + 2) * kstep; const char* b2 = last ? nB : cB + (size_t)(t + 2) * kstep;
;             const char* a3 = a2 + kstep; const char* b3 = b2 + kstep;
;             if (last && has_next) S.a_ready(nxt);
;             if constexpr (SP2) {
;             PG8_LDB(B0, 0, 0); PG8_LDB(B1, 0, 1); PG8_SCHED; PG8_LDA(At, 0, 0); PG8_STAGE(PG8_SA(1, 1), a1 + hstep, voffA);
;             PG8_WAIT_V(8); PG8_WAIT_L(0); PG8_BAR; PG8_MMA(0, 0, At, B0); PG8_MMA(0, 1, At, B1); PG8_BAR; PG8_SCHED;
;             PG8_LDA(At, 0, 1); PG8_STAGE(PG8_SB(0, 0), b2, voffB); PG8_STAGE(PG8_SB(0, 1), b2 + hstepB, voffB); PG8_STAGE(PG8_SA(0, 0), a2, voffA);
;             PG8_WAIT_V(8); PG8_WAIT_L(0); PG8_BAR; PG8_MMA(1, 0, At, B0); PG8_MMA(1, 1, At, B1); PG8_BAR; PG8_SCHED;
.LBB0_1232:
	s_add_u32 s36, s80, 0x100
	s_addc_u32 s37, s81, 0
	s_ashr_i32 s73, s72, 31
	s_lshl_b64 s[4:5], s[72:73], 20
	s_add_u32 s78, s0, s4
	s_addc_u32 s79, s1, s5
	s_and_b64 s[4:5], s[46:47], exec
	s_cselect_b32 s4, s79, s69
	s_cselect_b32 s5, s78, s68
	s_ashr_i32 s71, s70, 31
	s_lshl_b64 s[6:7], s[70:71], 20
	s_add_u32 s76, s34, s6
	s_addc_u32 s77, s35, s7
	s_and_b64 s[6:7], s[46:47], exec
	s_cselect_b32 s6, s77, s81
	s_cselect_b32 s7, s76, s80
	s_add_u32 s8, s68, 0x80080
	s_addc_u32 s9, s69, 0
	v_lshl_add_u64 v[140:141], s[8:9], 0, v[136:137]
	v_lshl_add_u64 v[142:143], s[8:9], 0, v[138:139]
	s_mov_b32 s8, -2
	s_mov_b64 s[80:81], 0
	v_add_u32_e32 v186, 0x10000, v145
	v_add_u32_e32 v187, 0x14000, v145
	v_add_u32_e32 v198, 0x18000, v145
	v_add_u32_e32 v199, 0x1c000, v145
	s_add_u32 s9, s68, s80
	s_addc_u32 s10, s69, s81
	s_add_u32 s9, s9, 0x100
	s_addc_u32 s10, s10, 0
	s_add_u32 s100, s9, 0x7ff80
	s_addc_u32 s101, s10, 0
	s_add_u32 s11, s36, s80
	s_addc_u32 s12, s37, s81
	s_add_i32 s13, 0, 0x10000
	s_cmpk_eq_i32 s80, 0xf00
	s_cselect_b32 s93, s4, s10
	s_cselect_b32 s92, s5, s9
	s_cselect_b32 s85, s6, s12
	s_cselect_b32 s84, s7, s11
	s_add_i32 s9, 0, 0x14000
	ds_read_b128 v[152:155], v186
	ds_read_b128 v[156:159], v186 offset:1024
	ds_read_b128 v[160:163], v186 offset:2048
	ds_read_b128 v[164:167], v186 offset:3072
	ds_read_b128 v[168:171], v187
	ds_read_b128 v[172:175], v187 offset:1024
	ds_read_b128 v[176:179], v187 offset:2048
	ds_read_b128 v[180:183], v187 offset:3072
	s_add_i32 m0, s51, 0xc000
	ds_read_b128 v[206:209], v151
	ds_read_b128 v[210:213], v151 offset:1024
	ds_read_b128 v[214:217], v151 offset:2048
	ds_read_b128 v[218:221], v151 offset:3072
	ds_read_b128 v[236:239], v151 offset:4096
	ds_read_b128 v[240:243], v151 offset:5120
	ds_read_b128 v[244:247], v151 offset:6144
	ds_read_b128 v[194:197], v151 offset:7168
	global_load_lds_dwordx4 v136, s[100:101]
	s_add_i32 m0, s51, 0xe000
	s_nop 0
	global_load_lds_dwordx4 v138, s[100:101]
	s_waitcnt vmcnt(8)
	s_waitcnt lgkmcnt(0)
	s_barrier
	v_mfma_f32_16x16x32_bf16 v[126:129], v[152:155], v[206:209], 0
	v_mfma_f32_16x16x32_bf16 v[122:125], v[160:163], v[206:209], 0
	v_mfma_f32_16x16x32_bf16 v[94:97], v[168:171], v[206:209], 0
	v_mfma_f32_16x16x32_bf16 v[90:93], v[176:179], v[206:209], 0
	v_mfma_f32_16x16x32_bf16 v[118:121], v[152:155], v[214:217], 0
	v_mfma_f32_16x16x32_bf16 v[114:117], v[160:163], v[214:217], 0
	v_mfma_f32_16x16x32_bf16 v[86:89], v[168:171], v[214:217], 0
	v_mfma_f32_16x16x32_bf16 v[82:85], v[176:179], v[214:217], 0
	v_mfma_f32_16x16x32_bf16 v[110:113], v[152:155], v[236:239], 0
	v_mfma_f32_16x16x32_bf16 v[106:109], v[160:163], v[236:239], 0
	v_mfma_f32_16x16x32_bf16 v[78:81], v[168:171], v[236:239], 0
	v_mfma_f32_16x16x32_bf16 v[74:77], v[176:179], v[236:239], 0
	v_mfma_f32_16x16x32_bf16 v[102:105], v[152:155], v[244:247], 0
	v_mfma_f32_16x16x32_bf16 v[98:101], v[160:163], v[244:247], 0
	v_mfma_f32_16x16x32_bf16 v[70:73], v[168:171], v[244:247], 0
	v_mfma_f32_16x16x32_bf16 v[66:69], v[176:179], v[244:247], 0
	v_mfma_f32_16x16x32_bf16 v[126:129], v[156:159], v[210:213], v[126:129]
	v_mfma_f32_16x16x32_bf16 v[122:125], v[164:167], v[210:213], v[122:125]
	v_mfma_f32_16x16x32_bf16 v[94:97], v[172:175], v[210:213], v[94:97]
	v_mfma_f32_16x16x32_bf16 v[90:93], v[180:183], v[210:213], v[90:93]
	v_mfma_f32_16x16x32_bf16 v[118:121], v[156:159], v[218:221], v[118:121]
	v_mfma_f32_16x16x32_bf16 v[114:117], v[164:167], v[218:221], v[114:117]
	v_mfma_f32_16x16x32_bf16 v[86:89], v[172:175], v[218:221], v[86:89]
	v_mfma_f32_16x16x32_bf16 v[82:85], v[180:183], v[218:221], v[82:85]
	v_mfma_f32_16x16x32_bf16 v[110:113], v[156:159], v[240:243], v[110:113]
	v_mfma_f32_16x16x32_bf16 v[106:109], v[164:167], v[240:243], v[106:109]
	v_mfma_f32_16x16x32_bf16 v[78:81], v[172:175], v[240:243], v[78:81]
	v_mfma_f32_16x16x32_bf16 v[74:77], v[180:183], v[240:243], v[74:77]
	v_mfma_f32_16x16x32_bf16 v[102:105], v[156:159], v[194:197], v[102:105]
	v_mfma_f32_16x16x32_bf16 v[98:101], v[164:167], v[194:197], v[98:101]
	v_mfma_f32_16x16x32_bf16 v[70:73], v[172:175], v[194:197], v[70:73]
	v_mfma_f32_16x16x32_bf16 v[66:69], v[180:183], v[194:197], v[66:69]
	s_barrier
	s_add_i32 s10, s13, s42
	s_mov_b32 m0, s10
	ds_read_b128 v[194:197], v151 offset:16384
	ds_read_b128 v[206:209], v151 offset:17408
	ds_read_b128 v[210:213], v151 offset:18432
	ds_read_b128 v[214:217], v151 offset:19456
	ds_read_b128 v[218:221], v151 offset:20480
	ds_read_b128 v[236:239], v151 offset:21504
	ds_read_b128 v[240:243], v151 offset:22528
	ds_read_b128 v[244:247], v151 offset:23552
	global_load_lds_dwordx4 v130, s[84:85]
	s_add_i32 m0, s10, 0x2000
	s_add_u32 s10, s84, 0x20000
	s_addc_u32 s11, s85, 0
	s_add_i32 s9, s9, s42
	global_load_lds_dwordx4 v134, s[84:85]
	s_mov_b32 m0, s9
	s_nop 0
	global_load_lds_dwordx4 v130, s[10:11]
	s_add_i32 m0, s9, 0x2000
	s_nop 0
	global_load_lds_dwordx4 v134, s[10:11]
	s_mov_b32 m0, s51
	s_nop 0
	global_load_lds_dwordx4 v190, s[92:93]
	s_mov_b32 m0, s67
	s_nop 0
	global_load_lds_dwordx4 v132, s[92:93]
	s_waitcnt vmcnt(8)
	s_waitcnt lgkmcnt(0)
	s_barrier
; #define PG8_STAGE(bufoff, gbase, voff) do { _Pragma("unroll") for (int _i = 0; _i < 2; ++_i) \
;         __builtin_amdgcn_global_load_lds((const unsigned*)((const char*)(gbase) + (voff)[_i]), (PG8_LAS unsigned*)(lds + (bufoff) + ldsw + _i * 8192), 16, 0, 0); } while (0)
; #define PG8_LDA(dst, b, h) do { _Pragma("unroll") for (int m = 0; m < 4; ++m) _Pragma("unroll") for (int k = 0; k < 2; ++k) dst[m][k] = *(const PG8_LAS bf16x8*)(lds + PG8_SA(b, h) + aoff + m * 2048 + k * 1024); } while (0)
; #define PG8_LDB(dst, b, h) do { _Pragma("unroll") for (int n = 0; n < 2; ++n) _Pragma("unroll") for (int k = 0; k < 2; ++k) dst[n][k] = *(const PG8_LAS bf16x8*)(lds + PG8_SB(b, h) + boff + n * 2048 + k * 1024); } while (0)
; #define PG8_MMA(ai, bj, At, Bt) do { __builtin_amdgcn_s_setprio(1); _Pragma("unroll") for (int m = 0; m < 4; ++m) _Pragma("unroll") for (int n = 0; n < 2; ++n) _Pragma("unroll") for (int k = 0; k < 2; ++k) \
;         acc[ai][bj][m][n] = __builtin_amdgcn_mfma_f32_16x16x32_bf16(Bt[n][k], At[m][k], acc[ai][bj][m][n], 0, 0, 0); __builtin_amdgcn_s_setprio(0); } while (0)
; #define PG8_WAIT_V(n) asm volatile("s_waitcnt vmcnt(" #n ")" ::: "memory")
; #define PG8_WAIT_L(n) asm volatile("s_waitcnt lgkmcnt(" #n ")" ::: "memory")
; #define PG8_BAR __builtin_amdgcn_s_barrier()
; #define PG8_SCHED __builtin_amdgcn_sched_barrier(0)
; template <class Epi, class Sched, bool ALIGN_EPI = false, bool SP2 = false>
; __device__ __forceinline__ void gemm_phase(PG8_LAS unsigned char* lds, const Gemm g, const Sched& S, const Epi& E) {
;     ...
;             PG8_WAIT_V(8); PG8_WAIT_L(0); PG8_BAR; PG8_MMA(1, 0, At, B0); PG8_MMA(1, 1, At, B1); PG8_BAR; PG8_SCHED;
;             PG8_LDB(B0, 1, 0); PG8_LDB(B1, 1, 1); PG8_SCHED; PG8_LDA(At, 1, 0); PG8_STAGE(PG8_SA(0, 1), a2 + hstep, voffA);
;             PG8_WAIT_V(8); PG8_WAIT_L(0); PG8_BAR; PG8_MMA(0, 0, At, B0); PG8_MMA(0, 1, At, B1); PG8_BAR; PG8_SCHED;
	v_mfma_f32_16x16x32_bf16 v[62:65], v[152:155], v[194:197], 0
	v_mfma_f32_16x16x32_bf16 v[58:61], v[160:163], v[194:197], 0
	v_mfma_f32_16x16x32_bf16 v[30:33], v[168:171], v[194:197], 0
	v_mfma_f32_16x16x32_bf16 v[26:29], v[176:179], v[194:197], 0
	v_mfma_f32_16x16x32_bf16 v[54:57], v[152:155], v[210:213], 0
	v_mfma_f32_16x16x32_bf16 v[50:53], v[160:163], v[210:213], 0
	v_mfma_f32_16x16x32_bf16 v[22:25], v[168:171], v[210:213], 0
	v_mfma_f32_16x16x32_bf16 v[18:21], v[176:179], v[210:213], 0
	v_mfma_f32_16x16x32_bf16 v[46:49], v[152:155], v[218:221], 0
	v_mfma_f32_16x16x32_bf16 v[42:45], v[160:163], v[218:221], 0
	v_mfma_f32_16x16x32_bf16 v[14:17], v[168:171], v[218:221], 0
	v_mfma_f32_16x16x32_bf16 v[10:13], v[176:179], v[218:221], 0
	v_mfma_f32_16x16x32_bf16 v[38:41], v[152:155], v[240:243], 0
	v_mfma_f32_16x16x32_bf16 v[34:37], v[160:163], v[240:243], 0
	v_mfma_f32_16x16x32_bf16 v[6:9], v[168:171], v[240:243], 0
	v_mfma_f32_16x16x32_bf16 v[2:5], v[176:179], v[240:243], 0
	v_mfma_f32_16x16x32_bf16 v[62:65], v[156:159], v[206:209], v[62:65]
	v_mfma_f32_16x16x32_bf16 v[58:61], v[164:167], v[206:209], v[58:61]
	v_mfma_f32_16x16x32_bf16 v[30:33], v[172:175], v[206:209], v[30:33]
	v_mfma_f32_16x16x32_bf16 v[26:29], v[180:183], v[206:209], v[26:29]
	v_mfma_f32_16x16x32_bf16 v[54:57], v[156:159], v[214:217], v[54:57]
	v_mfma_f32_16x16x32_bf16 v[50:53], v[164:167], v[214:217], v[50:53]
	v_mfma_f32_16x16x32_bf16 v[22:25], v[172:175], v[214:217], v[22:25]
	v_mfma_f32_16x16x32_bf16 v[18:21], v[180:183], v[214:217], v[18:21]
	v_mfma_f32_16x16x32_bf16 v[46:49], v[156:159], v[236:239], v[46:49]
	v_mfma_f32_16x16x32_bf16 v[42:45], v[164:167], v[236:239], v[42:45]
	v_mfma_f32_16x16x32_bf16 v[14:17], v[172:175], v[236:239], v[14:17]
	v_mfma_f32_16x16x32_bf16 v[10:13], v[180:183], v[236:239], v[10:13]
	v_mfma_f32_16x16x32_bf16 v[38:41], v[156:159], v[244:247], v[38:41]
	v_mfma_f32_16x16x32_bf16 v[34:37], v[164:167], v[244:247], v[34:37]
	v_mfma_f32_16x16x32_bf16 v[6:9], v[172:175], v[244:247], v[6:9]
	v_mfma_f32_16x16x32_bf16 v[2:5], v[180:183], v[244:247], v[2:5]
	s_barrier
	s_add_i32 s9, 0, 0x18000
	s_add_i32 s12, 0, 0x1c000
	ds_read_b128 v[152:155], v198
	ds_read_b128 v[156:159], v198 offset:1024
	ds_read_b128 v[160:163], v198 offset:2048
	ds_read_b128 v[164:167], v198 offset:3072
	ds_read_b128 v[168:171], v199
	ds_read_b128 v[172:175], v199 offset:1024
	ds_read_b128 v[176:179], v199 offset:2048
	ds_read_b128 v[180:183], v199 offset:3072
	s_add_u32 s10, s92, 0x80000
	s_addc_u32 s11, s93, 0
	s_mov_b32 m0, s74
	ds_read_b128 v[194:197], v151 offset:32768
	ds_read_b128 v[206:209], v151 offset:33792
	ds_read_b128 v[210:213], v151 offset:34816
	ds_read_b128 v[214:217], v151 offset:35840
	ds_read_b128 v[218:221], v151 offset:36864
	ds_read_b128 v[236:239], v151 offset:37888
	ds_read_b128 v[240:243], v151 offset:38912
	ds_read_b128 v[244:247], v151 offset:39936
	global_load_lds_dwordx4 v190, s[10:11]
	s_mov_b32 m0, s75
	s_nop 0
	global_load_lds_dwordx4 v132, s[10:11]
	s_waitcnt vmcnt(8)
	s_waitcnt lgkmcnt(0)
	s_barrier
	v_mfma_f32_16x16x32_bf16 v[126:129], v[152:155], v[194:197], v[126:129]
	v_mfma_f32_16x16x32_bf16 v[122:125], v[160:163], v[194:197], v[122:125]
	v_mfma_f32_16x16x32_bf16 v[94:97], v[168:171], v[194:197], v[94:97]
	v_mfma_f32_16x16x32_bf16 v[90:93], v[176:179], v[194:197], v[90:93]
	v_mfma_f32_16x16x32_bf16 v[118:121], v[152:155], v[210:213], v[118:121]
	v_mfma_f32_16x16x32_bf16 v[114:117], v[160:163], v[210:213], v[114:117]
	v_mfma_f32_16x16x32_bf16 v[86:89], v[168:171], v[210:213], v[86:89]
	v_mfma_f32_16x16x32_bf16 v[82:85], v[176:179], v[210:213], v[82:85]
	v_mfma_f32_16x16x32_bf16 v[110:113], v[152:155], v[218:221], v[110:113]
	v_mfma_f32_16x16x32_bf16 v[106:109], v[160:163], v[218:221], v[106:109]
	v_mfma_f32_16x16x32_bf16 v[78:81], v[168:171], v[218:221], v[78:81]
	v_mfma_f32_16x16x32_bf16 v[74:77], v[176:179], v[218:221], v[74:77]
	v_mfma_f32_16x16x32_bf16 v[102:105], v[152:155], v[240:243], v[102:105]
	v_mfma_f32_16x16x32_bf16 v[98:101], v[160:163], v[240:243], v[98:101]
	v_mfma_f32_16x16x32_bf16 v[70:73], v[168:171], v[240:243], v[70:73]
	v_mfma_f32_16x16x32_bf16 v[66:69], v[176:179], v[240:243], v[66:69]
	v_mfma_f32_16x16x32_bf16 v[126:129], v[156:159], v[206:209], v[126:129]
	v_mfma_f32_16x16x32_bf16 v[122:125], v[164:167], v[206:209], v[122:125]
	v_mfma_f32_16x16x32_bf16 v[94:97], v[172:175], v[206:209], v[94:97]
	v_mfma_f32_16x16x32_bf16 v[90:93], v[180:183], v[206:209], v[90:93]
	v_mfma_f32_16x16x32_bf16 v[118:121], v[156:159], v[214:217], v[118:121]
	v_mfma_f32_16x16x32_bf16 v[114:117], v[164:167], v[214:217], v[114:117]
	v_mfma_f32_16x16x32_bf16 v[86:89], v[172:175], v[214:217], v[86:89]
	v_mfma_f32_16x16x32_bf16 v[82:85], v[180:183], v[214:217], v[82:85]
	v_mfma_f32_16x16x32_bf16 v[110:113], v[156:159], v[236:239], v[110:113]
	v_mfma_f32_16x16x32_bf16 v[106:109], v[164:167], v[236:239], v[106:109]
	v_mfma_f32_16x16x32_bf16 v[78:81], v[172:175], v[236:239], v[78:81]
	v_mfma_f32_16x16x32_bf16 v[74:77], v[180:183], v[236:239], v[74:77]
	v_mfma_f32_16x16x32_bf16 v[102:105], v[156:159], v[244:247], v[102:105]
	v_mfma_f32_16x16x32_bf16 v[98:101], v[164:167], v[244:247], v[98:101]
	v_mfma_f32_16x16x32_bf16 v[70:73], v[172:175], v[244:247], v[70:73]
	v_mfma_f32_16x16x32_bf16 v[66:69], v[180:183], v[244:247], v[66:69]
	s_barrier
; #define PG8_STAGE(bufoff, gbase, voff) do { _Pragma("unroll") for (int _i = 0; _i < 2; ++_i) \
;         __builtin_amdgcn_global_load_lds((const unsigned*)((const char*)(gbase) + (voff)[_i]), (PG8_LAS unsigned*)(lds + (bufoff) + ldsw + _i * 8192), 16, 0, 0); } while (0)
; #define PG8_LDA(dst, b, h) do { _Pragma("unroll") for (int m = 0; m < 4; ++m) _Pragma("unroll") for (int k = 0; k < 2; ++k) dst[m][k] = *(const PG8_LAS bf16x8*)(lds + PG8_SA(b, h) + aoff + m * 2048 + k * 1024); } while (0)
; #define PG8_LDB(dst, b, h) do { _Pragma("unroll") for (int n = 0; n < 2; ++n) _Pragma("unroll") for (int k = 0; k < 2; ++k) dst[n][k] = *(const PG8_LAS bf16x8*)(lds + PG8_SB(b, h) + boff + n * 2048 + k * 1024); } while (0)
; #define PG8_MMA(ai, bj, At, Bt) do { __builtin_amdgcn_s_setprio(1); _Pragma("unroll") for (int m = 0; m < 4; ++m) _Pragma("unroll") for (int n = 0; n < 2; ++n) _Pragma("unroll") for (int k = 0; k < 2; ++k) \
;         acc[ai][bj][m][n] = __builtin_amdgcn_mfma_f32_16x16x32_bf16(Bt[n][k], At[m][k], acc[ai][bj][m][n], 0, 0, 0); __builtin_amdgcn_s_setprio(0); } while (0)
; #define PG8_WAIT_V(n) asm volatile("s_waitcnt vmcnt(" #n ")" ::: "memory")
; #define PG8_WAIT_L(n) asm volatile("s_waitcnt lgkmcnt(" #n ")" ::: "memory")
; #define PG8_BAR __builtin_amdgcn_s_barrier()
; #define PG8_SCHED __builtin_amdgcn_sched_barrier(0)
; template <class Epi, class Sched, bool ALIGN_EPI = false, bool SP2 = false>
; __device__ __forceinline__ void gemm_phase(PG8_LAS unsigned char* lds, const Gemm g, const Sched& S, const Epi& E) {
;     ...
;         for (int t = 0; t < nt; t += 2) {
;             const bool last = (t == nt - 2);
;             const char* a1 = cA + (size_t)(t + 1) * kstep;
;             const char* a2 = last ? nA : cA + (size_t)(t + 2) * kstep; const char* b2 = last ? nB : cB + (size_t)(t + 2) * kstep;
;             const char* a3 = a2 + kstep; const char* b3 = b2 + kstep;
;             if (last && has_next) S.a_ready(nxt);
;             if constexpr (SP2) {
;             PG8_LDB(B0, 0, 0); PG8_LDB(B1, 0, 1); PG8_SCHED; PG8_LDA(At, 0, 0); PG8_STAGE(PG8_SA(1, 1), a1 + hstep, voffA);
;     ...
;             PG8_LDA(At, 1, 1); PG8_STAGE(PG8_SB(1, 0), b3, voffB); PG8_STAGE(PG8_SB(1, 1), b3 + hstepB, voffB); PG8_STAGE(PG8_SA(1, 0), a3, voffA);
;             PG8_WAIT_V(8); PG8_WAIT_L(0); PG8_BAR; PG8_MMA(1, 0, At, B0); PG8_MMA(1, 1, At, B1); PG8_BAR; PG8_SCHED;
	s_add_i32 s9, s9, s42
	s_mov_b32 m0, s9
	ds_read_b128 v[194:197], v151 offset:49152
	ds_read_b128 v[206:209], v151 offset:50176
	ds_read_b128 v[210:213], v151 offset:51200
	ds_read_b128 v[214:217], v151 offset:52224
	ds_read_b128 v[218:221], v151 offset:53248
	ds_read_b128 v[236:239], v151 offset:54272
	ds_read_b128 v[240:243], v151 offset:55296
	ds_read_b128 v[244:247], v151 offset:56320
	s_add_u32 s100, s84, s60
	s_addc_u32 s101, s85, s61
	global_load_lds_dwordx4 v130, s[100:101]
	s_add_i32 m0, s9, 0x2000
	s_add_u32 s10, s84, 0x20080
	s_addc_u32 s11, s85, 0
	s_add_i32 s9, s12, s42
	global_load_lds_dwordx4 v134, s[100:101]
	s_mov_b32 m0, s9
	s_nop 0
	global_load_lds_dwordx4 v130, s[10:11]
	s_add_i32 m0, s9, 0x2000
	s_nop 0
	global_load_lds_dwordx4 v134, s[10:11]
	s_mov_b32 m0, s82
	s_add_u32 s100, s92, s60
	s_addc_u32 s101, s93, s61
	global_load_lds_dwordx4 v190, s[100:101]
	s_mov_b32 m0, s86
	s_nop 0
	global_load_lds_dwordx4 v132, s[100:101]
	s_waitcnt vmcnt(8)
	s_waitcnt lgkmcnt(0)
	s_barrier
	v_mfma_f32_16x16x32_bf16 v[62:65], v[152:155], v[194:197], v[62:65]
	v_mfma_f32_16x16x32_bf16 v[58:61], v[160:163], v[194:197], v[58:61]
	v_mfma_f32_16x16x32_bf16 v[30:33], v[168:171], v[194:197], v[30:33]
	v_mfma_f32_16x16x32_bf16 v[26:29], v[176:179], v[194:197], v[26:29]
	v_mfma_f32_16x16x32_bf16 v[54:57], v[152:155], v[210:213], v[54:57]
	v_mfma_f32_16x16x32_bf16 v[50:53], v[160:163], v[210:213], v[50:53]
	v_mfma_f32_16x16x32_bf16 v[22:25], v[168:171], v[210:213], v[22:25]
	v_mfma_f32_16x16x32_bf16 v[18:21], v[176:179], v[210:213], v[18:21]
	v_mfma_f32_16x16x32_bf16 v[46:49], v[152:155], v[218:221], v[46:49]
	v_mfma_f32_16x16x32_bf16 v[42:45], v[160:163], v[218:221], v[42:45]
	v_mfma_f32_16x16x32_bf16 v[14:17], v[168:171], v[218:221], v[14:17]
	v_mfma_f32_16x16x32_bf16 v[10:13], v[176:179], v[218:221], v[10:13]
	v_mfma_f32_16x16x32_bf16 v[38:41], v[152:155], v[240:243], v[38:41]
	v_mfma_f32_16x16x32_bf16 v[34:37], v[160:163], v[240:243], v[34:37]
	v_mfma_f32_16x16x32_bf16 v[6:9], v[168:171], v[240:243], v[6:9]
	v_mfma_f32_16x16x32_bf16 v[2:5], v[176:179], v[240:243], v[2:5]
	v_mfma_f32_16x16x32_bf16 v[62:65], v[156:159], v[206:209], v[62:65]
	v_mfma_f32_16x16x32_bf16 v[58:61], v[164:167], v[206:209], v[58:61]
	v_mfma_f32_16x16x32_bf16 v[30:33], v[172:175], v[206:209], v[30:33]
	v_mfma_f32_16x16x32_bf16 v[26:29], v[180:183], v[206:209], v[26:29]
	v_mfma_f32_16x16x32_bf16 v[54:57], v[156:159], v[214:217], v[54:57]
	v_mfma_f32_16x16x32_bf16 v[50:53], v[164:167], v[214:217], v[50:53]
	v_mfma_f32_16x16x32_bf16 v[22:25], v[172:175], v[214:217], v[22:25]
	v_mfma_f32_16x16x32_bf16 v[18:21], v[180:183], v[214:217], v[18:21]
	v_mfma_f32_16x16x32_bf16 v[46:49], v[156:159], v[236:239], v[46:49]
	v_mfma_f32_16x16x32_bf16 v[42:45], v[164:167], v[236:239], v[42:45]
	v_mfma_f32_16x16x32_bf16 v[14:17], v[172:175], v[236:239], v[14:17]
	v_mfma_f32_16x16x32_bf16 v[10:13], v[180:183], v[236:239], v[10:13]
	v_mfma_f32_16x16x32_bf16 v[38:41], v[156:159], v[244:247], v[38:41]
	v_mfma_f32_16x16x32_bf16 v[34:37], v[164:167], v[244:247], v[34:37]
	v_mfma_f32_16x16x32_bf16 v[6:9], v[172:175], v[244:247], v[6:9]
	v_mfma_f32_16x16x32_bf16 v[2:5], v[180:183], v[244:247], v[2:5]
	s_barrier
	s_add_i32 s8, s8, 2
	s_add_u32 s80, s80, 0x100
	s_addc_u32 s81, s81, 0
	s_cmp_gt_u32 s8, 29
.LBB0_1233:
	s_add_u32 s9, s68, s80
	s_addc_u32 s10, s69, s81
	s_add_u32 s9, s9, 0x100
	s_addc_u32 s10, s10, 0
	s_add_u32 s100, s9, 0x7ff80
	s_addc_u32 s101, s10, 0
	s_add_u32 s11, s36, s80
	s_addc_u32 s12, s37, s81
	s_add_i32 s13, 0, 0x10000
	s_cmpk_eq_i32 s80, 0xf00
	s_cselect_b32 s93, s4, s10
	s_cselect_b32 s92, s5, s9
	s_cselect_b32 s85, s6, s12
	s_cselect_b32 s84, s7, s11
	s_add_i32 s9, 0, 0x14000
	ds_read_b128 v[152:155], v186
	ds_read_b128 v[156:159], v186 offset:1024
	ds_read_b128 v[160:163], v186 offset:2048
	ds_read_b128 v[164:167], v186 offset:3072
	ds_read_b128 v[168:171], v187
	ds_read_b128 v[172:175], v187 offset:1024
	ds_read_b128 v[176:179], v187 offset:2048
	ds_read_b128 v[180:183], v187 offset:3072
	s_add_i32 m0, s51, 0xc000
	ds_read_b128 v[206:209], v151
	ds_read_b128 v[210:213], v151 offset:1024
	ds_read_b128 v[214:217], v151 offset:2048
	ds_read_b128 v[218:221], v151 offset:3072
	ds_read_b128 v[236:239], v151 offset:4096
	ds_read_b128 v[240:243], v151 offset:5120
	ds_read_b128 v[244:247], v151 offset:6144
	ds_read_b128 v[194:197], v151 offset:7168
	global_load_lds_dwordx4 v136, s[100:101]
	s_add_i32 m0, s51, 0xe000
	s_nop 0
	global_load_lds_dwordx4 v138, s[100:101]
	s_waitcnt vmcnt(8)
	s_waitcnt lgkmcnt(0)
	s_barrier
; #define PG8_STAGE(bufoff, gbase, voff) do { _Pragma("unroll") for (int _i = 0; _i < 2; ++_i) \
;         __builtin_amdgcn_global_load_lds((const unsigned*)((const char*)(gbase) + (voff)[_i]), (PG8_LAS unsigned*)(lds + (bufoff) + ldsw + _i * 8192), 16, 0, 0); } while (0)
; #define PG8_LDA(dst, b, h) do { _Pragma("unroll") for (int m = 0; m < 4; ++m) _Pragma("unroll") for (int k = 0; k < 2; ++k) dst[m][k] = *(const PG8_LAS bf16x8*)(lds + PG8_SA(b, h) + aoff + m * 2048 + k * 1024); } while (0)
; #define PG8_LDB(dst, b, h) do { _Pragma("unroll") for (int n = 0; n < 2; ++n) _Pragma("unroll") for (int k = 0; k < 2; ++k) dst[n][k] = *(const PG8_LAS bf16x8*)(lds + PG8_SB(b, h) + boff + n * 2048 + k * 1024); } while (0)
; #define PG8_MMA(ai, bj, At, Bt) do { __builtin_amdgcn_s_setprio(1); _Pragma("unroll") for (int m = 0; m < 4; ++m) _Pragma("unroll") for (int n = 0; n < 2; ++n) _Pragma("unroll") for (int k = 0; k < 2; ++k) \
;         acc[ai][bj][m][n] = __builtin_amdgcn_mfma_f32_16x16x32_bf16(Bt[n][k], At[m][k], acc[ai][bj][m][n], 0, 0, 0); __builtin_amdgcn_s_setprio(0); } while (0)
; #define PG8_WAIT_V(n) asm volatile("s_waitcnt vmcnt(" #n ")" ::: "memory")
; #define PG8_WAIT_L(n) asm volatile("s_waitcnt lgkmcnt(" #n ")" ::: "memory")
; #define PG8_BAR __builtin_amdgcn_s_barrier()
; #define PG8_SCHED __builtin_amdgcn_sched_barrier(0)
; template <class Epi, class Sched, bool ALIGN_EPI = false, bool SP2 = false>
; __device__ __forceinline__ void gemm_phase(PG8_LAS unsigned char* lds, const Gemm g, const Sched& S, const Epi& E) {
;     ...
;             PG8_LDB(B0, 0, 0); PG8_LDB(B1, 0, 1); PG8_SCHED; PG8_LDA(At, 0, 0); PG8_STAGE(PG8_SA(1, 1), a1 + hstep, voffA);
;             PG8_WAIT_V(8); PG8_WAIT_L(0); PG8_BAR; PG8_MMA(0, 0, At, B0); PG8_MMA(0, 1, At, B1); PG8_BAR; PG8_SCHED;
;             PG8_LDA(At, 0, 1); PG8_STAGE(PG8_SB(0, 0), b2, voffB); PG8_STAGE(PG8_SB(0, 1), b2 + hstepB, voffB); PG8_STAGE(PG8_SA(0, 0), a2, voffA);
;             PG8_WAIT_V(8); PG8_WAIT_L(0); PG8_BAR; PG8_MMA(1, 0, At, B0); PG8_MMA(1, 1, At, B1); PG8_BAR; PG8_SCHED;
	v_mfma_f32_16x16x32_bf16 v[126:129], v[152:155], v[206:209], v[126:129]
	v_mfma_f32_16x16x32_bf16 v[122:125], v[160:163], v[206:209], v[122:125]
	v_mfma_f32_16x16x32_bf16 v[94:97], v[168:171], v[206:209], v[94:97]
	v_mfma_f32_16x16x32_bf16 v[90:93], v[176:179], v[206:209], v[90:93]
	v_mfma_f32_16x16x32_bf16 v[118:121], v[152:155], v[214:217], v[118:121]
	v_mfma_f32_16x16x32_bf16 v[114:117], v[160:163], v[214:217], v[114:117]
	v_mfma_f32_16x16x32_bf16 v[86:89], v[168:171], v[214:217], v[86:89]
	v_mfma_f32_16x16x32_bf16 v[82:85], v[176:179], v[214:217], v[82:85]
	v_mfma_f32_16x16x32_bf16 v[110:113], v[152:155], v[236:239], v[110:113]
	v_mfma_f32_16x16x32_bf16 v[106:109], v[160:163], v[236:239], v[106:109]
	v_mfma_f32_16x16x32_bf16 v[78:81], v[168:171], v[236:239], v[78:81]
	v_mfma_f32_16x16x32_bf16 v[74:77], v[176:179], v[236:239], v[74:77]
	v_mfma_f32_16x16x32_bf16 v[102:105], v[152:155], v[244:247], v[102:105]
	v_mfma_f32_16x16x32_bf16 v[98:101], v[160:163], v[244:247], v[98:101]
	v_mfma_f32_16x16x32_bf16 v[70:73], v[168:171], v[244:247], v[70:73]
	v_mfma_f32_16x16x32_bf16 v[66:69], v[176:179], v[244:247], v[66:69]
	v_mfma_f32_16x16x32_bf16 v[126:129], v[156:159], v[210:213], v[126:129]
	v_mfma_f32_16x16x32_bf16 v[122:125], v[164:167], v[210:213], v[122:125]
	v_mfma_f32_16x16x32_bf16 v[94:97], v[172:175], v[210:213], v[94:97]
	v_mfma_f32_16x16x32_bf16 v[90:93], v[180:183], v[210:213], v[90:93]
	v_mfma_f32_16x16x32_bf16 v[118:121], v[156:159], v[218:221], v[118:121]
	v_mfma_f32_16x16x32_bf16 v[114:117], v[164:167], v[218:221], v[114:117]
	v_mfma_f32_16x16x32_bf16 v[86:89], v[172:175], v[218:221], v[86:89]
	v_mfma_f32_16x16x32_bf16 v[82:85], v[180:183], v[218:221], v[82:85]
	v_mfma_f32_16x16x32_bf16 v[110:113], v[156:159], v[240:243], v[110:113]
	v_mfma_f32_16x16x32_bf16 v[106:109], v[164:167], v[240:243], v[106:109]
	v_mfma_f32_16x16x32_bf16 v[78:81], v[172:175], v[240:243], v[78:81]
	v_mfma_f32_16x16x32_bf16 v[74:77], v[180:183], v[240:243], v[74:77]
	v_mfma_f32_16x16x32_bf16 v[102:105], v[156:159], v[194:197], v[102:105]
	v_mfma_f32_16x16x32_bf16 v[98:101], v[164:167], v[194:197], v[98:101]
	v_mfma_f32_16x16x32_bf16 v[70:73], v[172:175], v[194:197], v[70:73]
	v_mfma_f32_16x16x32_bf16 v[66:69], v[180:183], v[194:197], v[66:69]
	s_barrier
	s_add_i32 s10, s13, s42
	s_mov_b32 m0, s10
	ds_read_b128 v[194:197], v151 offset:16384
	ds_read_b128 v[206:209], v151 offset:17408
	ds_read_b128 v[210:213], v151 offset:18432
	ds_read_b128 v[214:217], v151 offset:19456
	ds_read_b128 v[218:221], v151 offset:20480
	ds_read_b128 v[236:239], v151 offset:21504
	ds_read_b128 v[240:243], v151 offset:22528
	ds_read_b128 v[244:247], v151 offset:23552
	global_load_lds_dwordx4 v130, s[84:85]
	s_add_i32 m0, s10, 0x2000
	s_add_u32 s10, s84, 0x20000
	s_addc_u32 s11, s85, 0
	s_add_i32 s9, s9, s42
	global_load_lds_dwordx4 v134, s[84:85]
	s_mov_b32 m0, s9
	s_nop 0
	global_load_lds_dwordx4 v130, s[10:11]
	s_add_i32 m0, s9, 0x2000
	s_nop 0
	global_load_lds_dwordx4 v134, s[10:11]
	s_mov_b32 m0, s51
	s_nop 0
	global_load_lds_dwordx4 v190, s[92:93]
	s_mov_b32 m0, s67
	s_nop 0
	global_load_lds_dwordx4 v132, s[92:93]
	s_waitcnt vmcnt(8)
	s_waitcnt lgkmcnt(0)
	s_barrier
	v_mfma_f32_16x16x32_bf16 v[62:65], v[152:155], v[194:197], v[62:65]
	v_mfma_f32_16x16x32_bf16 v[58:61], v[160:163], v[194:197], v[58:61]
	v_mfma_f32_16x16x32_bf16 v[30:33], v[168:171], v[194:197], v[30:33]
	v_mfma_f32_16x16x32_bf16 v[26:29], v[176:179], v[194:197], v[26:29]
	v_mfma_f32_16x16x32_bf16 v[54:57], v[152:155], v[210:213], v[54:57]
	v_mfma_f32_16x16x32_bf16 v[50:53], v[160:163], v[210:213], v[50:53]
	v_mfma_f32_16x16x32_bf16 v[22:25], v[168:171], v[210:213], v[22:25]
	v_mfma_f32_16x16x32_bf16 v[18:21], v[176:179], v[210:213], v[18:21]
	v_mfma_f32_16x16x32_bf16 v[46:49], v[152:155], v[218:221], v[46:49]
	v_mfma_f32_16x16x32_bf16 v[42:45], v[160:163], v[218:221], v[42:45]
	v_mfma_f32_16x16x32_bf16 v[14:17], v[168:171], v[218:221], v[14:17]
	v_mfma_f32_16x16x32_bf16 v[10:13], v[176:179], v[218:221], v[10:13]
	v_mfma_f32_16x16x32_bf16 v[38:41], v[152:155], v[240:243], v[38:41]
	v_mfma_f32_16x16x32_bf16 v[34:37], v[160:163], v[240:243], v[34:37]
	v_mfma_f32_16x16x32_bf16 v[6:9], v[168:171], v[240:243], v[6:9]
	v_mfma_f32_16x16x32_bf16 v[2:5], v[176:179], v[240:243], v[2:5]
	v_mfma_f32_16x16x32_bf16 v[62:65], v[156:159], v[206:209], v[62:65]
	v_mfma_f32_16x16x32_bf16 v[58:61], v[164:167], v[206:209], v[58:61]
	v_mfma_f32_16x16x32_bf16 v[30:33], v[172:175], v[206:209], v[30:33]
	v_mfma_f32_16x16x32_bf16 v[26:29], v[180:183], v[206:209], v[26:29]
	v_mfma_f32_16x16x32_bf16 v[54:57], v[156:159], v[214:217], v[54:57]
	v_mfma_f32_16x16x32_bf16 v[50:53], v[164:167], v[214:217], v[50:53]
	v_mfma_f32_16x16x32_bf16 v[22:25], v[172:175], v[214:217], v[22:25]
	v_mfma_f32_16x16x32_bf16 v[18:21], v[180:183], v[214:217], v[18:21]
	v_mfma_f32_16x16x32_bf16 v[46:49], v[156:159], v[236:239], v[46:49]
	v_mfma_f32_16x16x32_bf16 v[42:45], v[164:167], v[236:239], v[42:45]
	v_mfma_f32_16x16x32_bf16 v[14:17], v[172:175], v[236:239], v[14:17]
	v_mfma_f32_16x16x32_bf16 v[10:13], v[180:183], v[236:239], v[10:13]
	v_mfma_f32_16x16x32_bf16 v[38:41], v[156:159], v[244:247], v[38:41]
	v_mfma_f32_16x16x32_bf16 v[34:37], v[164:167], v[244:247], v[34:37]
	v_mfma_f32_16x16x32_bf16 v[6:9], v[172:175], v[244:247], v[6:9]
	v_mfma_f32_16x16x32_bf16 v[2:5], v[180:183], v[244:247], v[2:5]
	s_barrier
; #define PG8_STAGE(bufoff, gbase, voff) do { _Pragma("unroll") for (int _i = 0; _i < 2; ++_i) \
;         __builtin_amdgcn_global_load_lds((const unsigned*)((const char*)(gbase) + (voff)[_i]), (PG8_LAS unsigned*)(lds + (bufoff) + ldsw + _i * 8192), 16, 0, 0); } while (0)
; #define PG8_LDA(dst, b, h) do { _Pragma("unroll") for (int m = 0; m < 4; ++m) _Pragma("unroll") for (int k = 0; k < 2; ++k) dst[m][k] = *(const PG8_LAS bf16x8*)(lds + PG8_SA(b, h) + aoff + m * 2048 + k * 1024); } while (0)
; #define PG8_LDB(dst, b, h) do { _Pragma("unroll") for (int n = 0; n < 2; ++n) _Pragma("unroll") for (int k = 0; k < 2; ++k) dst[n][k] = *(const PG8_LAS bf16x8*)(lds + PG8_SB(b, h) + boff + n * 2048 + k * 1024); } while (0)
; #define PG8_MMA(ai, bj, At, Bt) do { __builtin_amdgcn_s_setprio(1); _Pragma("unroll") for (int m = 0; m < 4; ++m) _Pragma("unroll") for (int n = 0; n < 2; ++n) _Pragma("unroll") for (int k = 0; k < 2; ++k) \
;         acc[ai][bj][m][n] = __builtin_amdgcn_mfma_f32_16x16x32_bf16(Bt[n][k], At[m][k], acc[ai][bj][m][n], 0, 0, 0); __builtin_amdgcn_s_setprio(0); } while (0)
; #define PG8_WAIT_V(n) asm volatile("s_waitcnt vmcnt(" #n ")" ::: "memory")
; #define PG8_WAIT_L(n) asm volatile("s_waitcnt lgkmcnt(" #n ")" ::: "memory")
; #define PG8_BAR __builtin_amdgcn_s_barrier()
; #define PG8_SCHED __builtin_amdgcn_sched_barrier(0)
; template <class Epi, class Sched, bool ALIGN_EPI = false, bool SP2 = false>
; __device__ __forceinline__ void gemm_phase(PG8_LAS unsigned char* lds, const Gemm g, const Sched& S, const Epi& E) {
;     ...
;             PG8_LDB(B0, 1, 0); PG8_LDB(B1, 1, 1); PG8_SCHED; PG8_LDA(At, 1, 0); PG8_STAGE(PG8_SA(0, 1), a2 + hstep, voffA);
;             PG8_WAIT_V(8); PG8_WAIT_L(0); PG8_BAR; PG8_MMA(0, 0, At, B0); PG8_MMA(0, 1, At, B1); PG8_BAR; PG8_SCHED;
;             PG8_LDA(At, 1, 1); PG8_STAGE(PG8_SB(1, 0), b3, voffB); PG8_STAGE(PG8_SB(1, 1), b3 + hstepB, voffB); PG8_STAGE(PG8_SA(1, 0), a3, voffA);
;             PG8_WAIT_V(8); PG8_WAIT_L(0); PG8_BAR; PG8_MMA(1, 0, At, B0); PG8_MMA(1, 1, At, B1); PG8_BAR; PG8_SCHED;
	s_add_i32 s9, 0, 0x18000
	s_add_i32 s12, 0, 0x1c000
	ds_read_b128 v[152:155], v198
	ds_read_b128 v[156:159], v198 offset:1024
	ds_read_b128 v[160:163], v198 offset:2048
	ds_read_b128 v[164:167], v198 offset:3072
	ds_read_b128 v[168:171], v199
	ds_read_b128 v[172:175], v199 offset:1024
	ds_read_b128 v[176:179], v199 offset:2048
	ds_read_b128 v[180:183], v199 offset:3072
	s_add_u32 s10, s92, 0x80000
	s_addc_u32 s11, s93, 0
	s_mov_b32 m0, s74
	ds_read_b128 v[194:197], v151 offset:32768
	ds_read_b128 v[206:209], v151 offset:33792
	ds_read_b128 v[210:213], v151 offset:34816
	ds_read_b128 v[214:217], v151 offset:35840
	ds_read_b128 v[218:221], v151 offset:36864
	ds_read_b128 v[236:239], v151 offset:37888
	ds_read_b128 v[240:243], v151 offset:38912
	ds_read_b128 v[244:247], v151 offset:39936
	global_load_lds_dwordx4 v190, s[10:11]
	s_mov_b32 m0, s75
	s_nop 0
	global_load_lds_dwordx4 v132, s[10:11]
	s_waitcnt vmcnt(8)
	s_waitcnt lgkmcnt(0)
	s_barrier
	v_mfma_f32_16x16x32_bf16 v[126:129], v[152:155], v[194:197], v[126:129]
	v_mfma_f32_16x16x32_bf16 v[122:125], v[160:163], v[194:197], v[122:125]
	v_mfma_f32_16x16x32_bf16 v[94:97], v[168:171], v[194:197], v[94:97]
	v_mfma_f32_16x16x32_bf16 v[90:93], v[176:179], v[194:197], v[90:93]
	v_mfma_f32_16x16x32_bf16 v[118:121], v[152:155], v[210:213], v[118:121]
	v_mfma_f32_16x16x32_bf16 v[114:117], v[160:163], v[210:213], v[114:117]
	v_mfma_f32_16x16x32_bf16 v[86:89], v[168:171], v[210:213], v[86:89]
	v_mfma_f32_16x16x32_bf16 v[82:85], v[176:179], v[210:213], v[82:85]
	v_mfma_f32_16x16x32_bf16 v[110:113], v[152:155], v[218:221], v[110:113]
	v_mfma_f32_16x16x32_bf16 v[106:109], v[160:163], v[218:221], v[106:109]
	v_mfma_f32_16x16x32_bf16 v[78:81], v[168:171], v[218:221], v[78:81]
	v_mfma_f32_16x16x32_bf16 v[74:77], v[176:179], v[218:221], v[74:77]
	v_mfma_f32_16x16x32_bf16 v[102:105], v[152:155], v[240:243], v[102:105]
	v_mfma_f32_16x16x32_bf16 v[98:101], v[160:163], v[240:243], v[98:101]
	v_mfma_f32_16x16x32_bf16 v[70:73], v[168:171], v[240:243], v[70:73]
	v_mfma_f32_16x16x32_bf16 v[66:69], v[176:179], v[240:243], v[66:69]
	v_mfma_f32_16x16x32_bf16 v[126:129], v[156:159], v[206:209], v[126:129]
	v_mfma_f32_16x16x32_bf16 v[122:125], v[164:167], v[206:209], v[122:125]
	v_mfma_f32_16x16x32_bf16 v[94:97], v[172:175], v[206:209], v[94:97]
	v_mfma_f32_16x16x32_bf16 v[90:93], v[180:183], v[206:209], v[90:93]
	v_mfma_f32_16x16x32_bf16 v[118:121], v[156:159], v[214:217], v[118:121]
	v_mfma_f32_16x16x32_bf16 v[114:117], v[164:167], v[214:217], v[114:117]
	v_mfma_f32_16x16x32_bf16 v[86:89], v[172:175], v[214:217], v[86:89]
	v_mfma_f32_16x16x32_bf16 v[82:85], v[180:183], v[214:217], v[82:85]
	v_mfma_f32_16x16x32_bf16 v[110:113], v[156:159], v[236:239], v[110:113]
	v_mfma_f32_16x16x32_bf16 v[106:109], v[164:167], v[236:239], v[106:109]
	v_mfma_f32_16x16x32_bf16 v[78:81], v[172:175], v[236:239], v[78:81]
	v_mfma_f32_16x16x32_bf16 v[74:77], v[180:183], v[236:239], v[74:77]
	v_mfma_f32_16x16x32_bf16 v[102:105], v[156:159], v[244:247], v[102:105]
	v_mfma_f32_16x16x32_bf16 v[98:101], v[164:167], v[244:247], v[98:101]
	v_mfma_f32_16x16x32_bf16 v[70:73], v[172:175], v[244:247], v[70:73]
	v_mfma_f32_16x16x32_bf16 v[66:69], v[180:183], v[244:247], v[66:69]
	s_barrier
	s_add_i32 s9, s9, s42
	s_mov_b32 m0, s9
	ds_read_b128 v[194:197], v151 offset:49152
	ds_read_b128 v[206:209], v151 offset:50176
	ds_read_b128 v[210:213], v151 offset:51200
	ds_read_b128 v[214:217], v151 offset:52224
	ds_read_b128 v[218:221], v151 offset:53248
	ds_read_b128 v[236:239], v151 offset:54272
	ds_read_b128 v[240:243], v151 offset:55296
	ds_read_b128 v[244:247], v151 offset:56320
	s_add_u32 s100, s84, s60
	s_addc_u32 s101, s85, s61
	global_load_lds_dwordx4 v130, s[100:101]
	s_add_i32 m0, s9, 0x2000
	s_add_u32 s10, s84, 0x20080
	s_addc_u32 s11, s85, 0
	s_add_i32 s9, s12, s42
	global_load_lds_dwordx4 v134, s[100:101]
	s_mov_b32 m0, s9
	s_nop 0
	global_load_lds_dwordx4 v130, s[10:11]
	s_add_i32 m0, s9, 0x2000
	s_nop 0
	global_load_lds_dwordx4 v134, s[10:11]
	s_mov_b32 m0, s82
	s_add_u32 s100, s92, s60
	s_addc_u32 s101, s93, s61
	global_load_lds_dwordx4 v190, s[100:101]
	s_mov_b32 m0, s86
	s_nop 0
	global_load_lds_dwordx4 v132, s[100:101]
	s_waitcnt vmcnt(8)
	s_waitcnt lgkmcnt(0)
	s_barrier
	v_mfma_f32_16x16x32_bf16 v[62:65], v[152:155], v[194:197], v[62:65]
	v_mfma_f32_16x16x32_bf16 v[58:61], v[160:163], v[194:197], v[58:61]
	v_mfma_f32_16x16x32_bf16 v[30:33], v[168:171], v[194:197], v[30:33]
	v_mfma_f32_16x16x32_bf16 v[26:29], v[176:179], v[194:197], v[26:29]
	v_mfma_f32_16x16x32_bf16 v[54:57], v[152:155], v[210:213], v[54:57]
	v_mfma_f32_16x16x32_bf16 v[50:53], v[160:163], v[210:213], v[50:53]
	v_mfma_f32_16x16x32_bf16 v[22:25], v[168:171], v[210:213], v[22:25]
	v_mfma_f32_16x16x32_bf16 v[18:21], v[176:179], v[210:213], v[18:21]
	v_mfma_f32_16x16x32_bf16 v[46:49], v[152:155], v[218:221], v[46:49]
	v_mfma_f32_16x16x32_bf16 v[42:45], v[160:163], v[218:221], v[42:45]
	v_mfma_f32_16x16x32_bf16 v[14:17], v[168:171], v[218:221], v[14:17]
	v_mfma_f32_16x16x32_bf16 v[10:13], v[176:179], v[218:221], v[10:13]
	v_mfma_f32_16x16x32_bf16 v[38:41], v[152:155], v[240:243], v[38:41]
	v_mfma_f32_16x16x32_bf16 v[34:37], v[160:163], v[240:243], v[34:37]
	v_mfma_f32_16x16x32_bf16 v[6:9], v[168:171], v[240:243], v[6:9]
	v_mfma_f32_16x16x32_bf16 v[2:5], v[176:179], v[240:243], v[2:5]
	v_mfma_f32_16x16x32_bf16 v[62:65], v[156:159], v[206:209], v[62:65]
	v_mfma_f32_16x16x32_bf16 v[58:61], v[164:167], v[206:209], v[58:61]
	v_mfma_f32_16x16x32_bf16 v[30:33], v[172:175], v[206:209], v[30:33]
	v_mfma_f32_16x16x32_bf16 v[26:29], v[180:183], v[206:209], v[26:29]
	v_mfma_f32_16x16x32_bf16 v[54:57], v[156:159], v[214:217], v[54:57]
	v_mfma_f32_16x16x32_bf16 v[50:53], v[164:167], v[214:217], v[50:53]
	v_mfma_f32_16x16x32_bf16 v[22:25], v[172:175], v[214:217], v[22:25]
	v_mfma_f32_16x16x32_bf16 v[18:21], v[180:183], v[214:217], v[18:21]
	v_mfma_f32_16x16x32_bf16 v[46:49], v[156:159], v[236:239], v[46:49]
	v_mfma_f32_16x16x32_bf16 v[42:45], v[164:167], v[236:239], v[42:45]
	v_mfma_f32_16x16x32_bf16 v[14:17], v[172:175], v[236:239], v[14:17]
	v_mfma_f32_16x16x32_bf16 v[10:13], v[180:183], v[236:239], v[10:13]
	v_mfma_f32_16x16x32_bf16 v[38:41], v[156:159], v[244:247], v[38:41]
	v_mfma_f32_16x16x32_bf16 v[34:37], v[164:167], v[244:247], v[34:37]
	v_mfma_f32_16x16x32_bf16 v[6:9], v[172:175], v[244:247], v[6:9]
	v_mfma_f32_16x16x32_bf16 v[2:5], v[180:183], v[244:247], v[2:5]
	s_barrier
	s_add_i32 s8, s8, 2
	s_add_u32 s80, s80, 0x100
	s_addc_u32 s81, s81, 0
	s_cmp_gt_u32 s8, 29
	s_cbranch_scc0 .LBB0_1233
	s_and_b64 vcc, exec, s[62:63]
	s_cbranch_vccz .LBB0_1236
	s_barrier
